# prompt attention: separate unmasked fast path for key tiles fully below the diagonal (skips causal-mask VALU); sample-attention key-norm section hand-scheduled; waves 4-7 staggered; 1/x via v_rcp_f32
# speedup vs baseline: 1.0199x; 1.0082x over previous
; DI unsigned pk2(float lo, float hi) { f32x2 v = {lo, hi}; bf16x2_t b = __builtin_convertvector(v, bf16x2_t); return __builtin_bit_cast(unsigned, b); }
; DI void attn_prompt_unit(const Args& a, LAS unsigned char* lds, int b, int h, int qb, float cB, int tid, int lane, int wave) {
;     ...
;     lsum += __shfl_xor(lsum, 32);
;     const float inv = 1.f / lsum;
;     bf16* op = MIX + qrow * DM + h * 64;
; #pragma unroll
;     for (int q = 0; q < 4; ++q) { const int dv = 8 * q + 4 * h2;
;         u32x2 w0, w1; w0.x = pk2(o0[4 * q] * inv, o0[4 * q + 1] * inv); w0.y = pk2(o0[4 * q + 2] * inv, o0[4 * q + 3] * inv);
;         w1.x = pk2(o1[4 * q] * inv, o1[4 * q + 1] * inv); w1.y = pk2(o1[4 * q + 2] * inv, o1[4 * q + 3] * inv);
;         *(u32x2*)(op + dv) = w0; *(u32x2*)(op + 32 + dv) = w1; }
.LBB0_832:
	ds_bpermute_b32 v50, v143, v1
	s_lshl_b32 s6, s6, 1
	v_mov_b32_e32 v161, v127
	s_waitcnt lgkmcnt(0)
	s_barrier
	v_add_f32_e32 v1, v1, v50
	v_div_scale_f32 v50, s[4:5], v1, v1, 1.0
	v_rcp_f32_e32 v51, v50
	s_nop 0
	v_fma_f32 v53, -v50, v51, 1.0
	v_fmac_f32_e32 v51, v53, v51
	v_rcp_f32_e32 v50, v1
	v_lshlrev_b64 v[52:53], 11, v[176:177]
	v_lshl_add_u64 v[52:53], s[10:11], 0, v[52:53]
	v_pk_mul_f32 v[18:19], v[18:19], v[50:51] op_sel_hi:[1,0]
	v_pk_mul_f32 v[20:21], v[20:21], v[50:51] op_sel_hi:[1,0]
	v_lshl_add_u64 v[52:53], v[52:53], 0, s[6:7]
	v_cvt_pk_bf16_f32 v18, v18, v19
	v_cvt_pk_bf16_f32 v19, v20, v21
	v_pk_mul_f32 v[20:21], v[34:35], v[50:51] op_sel_hi:[1,0]
	v_pk_mul_f32 v[34:35], v[36:37], v[50:51] op_sel_hi:[1,0]
	v_cvt_pk_bf16_f32 v20, v20, v21
	v_cvt_pk_bf16_f32 v21, v34, v35
	v_lshl_add_u64 v[34:35], v[52:53], 0, v[160:161]
	global_store_dwordx2 v[34:35], v[18:19], off
	global_store_dwordx2 v[34:35], v[20:21], off offset:64
	v_pk_mul_f32 v[18:19], v[22:23], v[50:51] op_sel_hi:[1,0]
	v_pk_mul_f32 v[20:21], v[24:25], v[50:51] op_sel_hi:[1,0]
	v_cvt_pk_bf16_f32 v18, v18, v19
	v_cvt_pk_bf16_f32 v19, v20, v21
	v_pk_mul_f32 v[20:21], v[38:39], v[50:51] op_sel_hi:[1,0]
	v_pk_mul_f32 v[22:23], v[40:41], v[50:51] op_sel_hi:[1,0]
	v_cvt_pk_bf16_f32 v20, v20, v21
	v_cvt_pk_bf16_f32 v21, v22, v23
	global_store_dwordx2 v[34:35], v[18:19], off offset:16
	global_store_dwordx2 v[34:35], v[20:21], off offset:80
	v_pk_mul_f32 v[18:19], v[26:27], v[50:51] op_sel_hi:[1,0]
	v_pk_mul_f32 v[20:21], v[28:29], v[50:51] op_sel_hi:[1,0]
	v_cvt_pk_bf16_f32 v18, v18, v19
	v_cvt_pk_bf16_f32 v19, v20, v21
	v_pk_mul_f32 v[20:21], v[42:43], v[50:51] op_sel_hi:[1,0]
	v_pk_mul_f32 v[22:23], v[44:45], v[50:51] op_sel_hi:[1,0]
	v_cvt_pk_bf16_f32 v20, v20, v21
	v_cvt_pk_bf16_f32 v21, v22, v23
	global_store_dwordx2 v[34:35], v[18:19], off offset:32
	global_store_dwordx2 v[34:35], v[20:21], off offset:96
	v_pk_mul_f32 v[18:19], v[30:31], v[50:51] op_sel_hi:[1,0]
	v_pk_mul_f32 v[20:21], v[32:33], v[50:51] op_sel_hi:[1,0]
	v_cvt_pk_bf16_f32 v18, v18, v19
	v_cvt_pk_bf16_f32 v19, v20, v21
	v_pk_mul_f32 v[20:21], v[46:47], v[50:51] op_sel_hi:[1,0]
	v_pk_mul_f32 v[22:23], v[48:49], v[50:51] op_sel_hi:[1,0]
	s_add_i32 s26, s26, s91
	s_add_i32 s25, s25, s91
	v_cvt_pk_bf16_f32 v20, v20, v21
	v_cvt_pk_bf16_f32 v21, v22, v23
	s_cmpk_lt_i32 s26, 0x100
	global_store_dwordx2 v[34:35], v[18:19], off offset:48
	global_store_dwordx2 v[34:35], v[20:21], off offset:112
	s_cbranch_scc0 .LBB0_861

; #define LAS __attribute__((address_space(3)))
; #define MFMA32(a, b, c) __builtin_amdgcn_mfma_f32_32x32x16_bf16((a), (b), (c), 0, 0, 0)
; DI int crow(int r, int hi) { return (r & 3) + 8 * (r >> 2) + 4 * hi; }
; DI void attn_prompt_unit(const Args& a, LAS unsigned char* lds, int b, int h, int qb, float cB, int tid, int lane, int wave) {
;     ...
;         if (t + 1 < NT) { const size_t kv1 = (size_t)(t + 1) * 64;
;             kst0 = *(const u32x4*)(kbase + (kv1 + kr0) * 768 + kp0 * 8); if (k1) kst1 = *(const u32x4*)(kbase + (kv1 + kr1) * 768 + kp1 * 8); vst = *(const u32x4*)(vbase + kv1 * 1024); }
;         if (t * 64 <= qmax_w) {
;             const LAS bf16* Kb = Ks + buf * 6656; const LAS bf16* Vb = Vs + buf * 6144;
;             f32x16 p0, p1;
; #pragma unroll
;             for (int r = 0; r < 16; ++r) { p0[r] = -cB; p1[r] = -cB; }
; #pragma unroll
;             for (int s = 0; s < 6; ++s) { const bf16x8 k0 = *(const LAS bf16x8*)(Kb + r32 * 104 + 16 * s + 8 * h2), k1f = *(const LAS bf16x8*)(Kb + (32 + r32) * 104 + 16 * s + 8 * h2);
;                 p0 = MFMA32(k0, qf[s], p0); p1 = MFMA32(k1f, qf[s], p1); }
;             const bool diag = (t * 64 + 63 > qb * 256 + wave * 32);
; #pragma unroll
;             for (int r = 0; r < 16; ++r) { const int kv = t * 64 + crow(r, h2);
;                 float e0 = __builtin_amdgcn_exp2f(p0[r]), e1 = __builtin_amdgcn_exp2f(p1[r]);
;                 if (diag) { if (kv > qloc) e0 = 0.f; if (kv + 32 > qloc) e1 = 0.f; }
;                 p0[r] = e0; p1[r] = e1; lsum += e0 + e1; }
; #pragma unroll
.LBB0_841:
	s_or_b64 exec, exec, s[4:5]
	global_load_dwordx4 v[114:117], v[184:185], off
	s_and_b32 s36, s35, 1
	s_cmp_gt_i32 s34, s31
	s_cbranch_scc1 .LBB0_843
	s_mul_i32 s4, s36, 0x3400
	s_add_i32 s4, s4, 0
	v_add3_u32 v119, s4, v227, v126
	ds_read_b128 v[50:53], v119
	ds_read_b128 v[186:189], v119 offset:32
	v_add3_u32 v121, s4, v228, v126
	ds_read_b128 v[190:193], v121
	ds_read_b128 v[194:197], v121 offset:32
	s_add_i32 s4, s34, 63
	s_cmp_gt_i32 s4, s29
	s_cselect_b64 s[20:21], -1, 0
	s_mul_i32 s37, s36, 0x3000
	s_waitcnt lgkmcnt(3)
	v_mfma_f32_32x32x16_bf16 v[66:81], v[50:53], v[86:89], v[2:17]
	s_waitcnt lgkmcnt(1)
	v_mfma_f32_32x32x16_bf16 v[50:65], v[190:193], v[86:89], v[2:17]
	v_mfma_f32_32x32x16_bf16 v[66:81], v[186:189], v[90:93], v[66:81]
	ds_read_b128 v[186:189], v119 offset:64
	ds_read_b128 v[190:193], v119 offset:96
	s_waitcnt lgkmcnt(2)
	v_mfma_f32_32x32x16_bf16 v[50:65], v[194:197], v[90:93], v[50:65]
	s_waitcnt lgkmcnt(1)
	v_mfma_f32_32x32x16_bf16 v[66:81], v[186:189], v[94:97], v[66:81]
	ds_read_b128 v[186:189], v121 offset:64
	ds_read_b128 v[194:197], v121 offset:96
	s_waitcnt lgkmcnt(1)
	v_mfma_f32_32x32x16_bf16 v[50:65], v[186:189], v[94:97], v[50:65]
	v_mfma_f32_32x32x16_bf16 v[66:81], v[190:193], v[98:101], v[66:81]
	ds_read_b128 v[186:189], v119 offset:128
	ds_read_b128 v[190:193], v119 offset:160
	v_add_u32_e32 v119, s34, v118
	v_cmp_gt_i32_e32 vcc, v119, v178
	s_and_b64 s[38:39], s[20:21], vcc
	v_cmp_ge_i32_e32 vcc, v119, v178
	s_waitcnt lgkmcnt(2)
	v_mfma_f32_32x32x16_bf16 v[50:65], v[194:197], v[98:101], v[50:65]
	s_waitcnt lgkmcnt(1)
	v_mfma_f32_32x32x16_bf16 v[66:81], v[186:189], v[106:109], v[66:81]
	ds_read_b128 v[186:189], v121 offset:128
	ds_read_b128 v[194:197], v121 offset:160
	v_add_u32_e32 v121, 32, v119
	v_cmp_gt_i32_e64 s[4:5], v121, v178
	s_and_b64 s[4:5], s[20:21], s[4:5]
	s_waitcnt lgkmcnt(1)
	v_mfma_f32_32x32x16_bf16 v[50:65], v[186:189], v[106:109], v[50:65]
	s_waitcnt lgkmcnt(0)
	v_mfma_f32_32x32x16_bf16 v[50:65], v[194:197], v[102:105], v[50:65]
	v_mfma_f32_32x32x16_bf16 v[66:81], v[190:193], v[102:105], v[66:81]
	s_cmp_lg_u64 s[20:21], 0
	s_cbranch_scc0 .Lpa_fast_0
	s_nop 10
	v_exp_f32_e32 v50, v50
	v_exp_f32_e32 v51, v51
	v_exp_f32_e32 v52, v52
	v_exp_f32_e32 v64, v64
	v_cndmask_b32_e64 v121, v50, 0, s[4:5]
	v_exp_f32_e32 v65, v65
	v_exp_f32_e32 v66, v66
	v_exp_f32_e32 v50, v67
	v_add_u32_e32 v67, 33, v119
	v_cmp_gt_i32_e64 s[4:5], v67, v178
	v_cndmask_b32_e64 v66, v66, 0, s[38:39]
	s_and_b64 s[38:39], s[20:21], vcc
	s_and_b64 s[4:5], s[20:21], s[4:5]
	v_cndmask_b32_e64 v67, v50, 0, s[38:39]
	v_cndmask_b32_e64 v133, v51, 0, s[4:5]
	v_add_u32_e32 v50, 2, v119
	v_exp_f32_e32 v51, v68
	v_cmp_gt_i32_e32 vcc, v50, v178
	v_add_u32_e32 v50, 34, v119
	v_cmp_gt_i32_e64 s[4:5], v50, v178
	s_and_b64 s[38:39], s[20:21], vcc
	s_and_b64 s[4:5], s[20:21], s[4:5]
	v_cndmask_b32_e64 v68, v51, 0, s[38:39]
	v_cndmask_b32_e64 v137, v52, 0, s[4:5]
	v_add_u32_e32 v50, 3, v119
	v_exp_f32_e32 v51, v69
	v_exp_f32_e32 v52, v53
	v_cmp_gt_i32_e32 vcc, v50, v178
	v_add_u32_e32 v50, 35, v119
	v_cmp_gt_i32_e64 s[4:5], v50, v178
	s_and_b64 s[38:39], s[20:21], vcc
	s_and_b64 s[4:5], s[20:21], s[4:5]
	v_cndmask_b32_e64 v69, v51, 0, s[38:39]
	v_cndmask_b32_e64 v157, v52, 0, s[4:5]
	v_add_u32_e32 v50, 8, v119
	v_exp_f32_e32 v51, v70
	v_exp_f32_e32 v52, v54
	v_cmp_gt_i32_e32 vcc, v50, v178
	v_add_u32_e32 v50, 40, v119
	v_cmp_gt_i32_e64 s[4:5], v50, v178
	s_and_b64 s[38:39], s[20:21], vcc
	s_and_b64 s[4:5], s[20:21], s[4:5]
	v_cndmask_b32_e64 v70, v51, 0, s[38:39]
	v_cndmask_b32_e64 v161, v52, 0, s[4:5]
	v_add_u32_e32 v50, 9, v119
	v_exp_f32_e32 v51, v71
	v_exp_f32_e32 v52, v55
	v_cmp_gt_i32_e32 vcc, v50, v178
	v_add_u32_e32 v50, 41, v119
	v_cmp_gt_i32_e64 s[4:5], v50, v178
	s_and_b64 s[38:39], s[20:21], vcc
	s_and_b64 s[4:5], s[20:21], s[4:5]
	v_cndmask_b32_e64 v71, v51, 0, s[38:39]
	v_cndmask_b32_e64 v171, v52, 0, s[4:5]
	v_add_u32_e32 v50, 10, v119
	v_exp_f32_e32 v51, v72
	v_exp_f32_e32 v52, v56
	v_cmp_gt_i32_e32 vcc, v50, v178
	v_add_u32_e32 v50, 42, v119
	v_cmp_gt_i32_e64 s[4:5], v50, v178
	s_and_b64 s[38:39], s[20:21], vcc
	s_and_b64 s[4:5], s[20:21], s[4:5]
	v_cndmask_b32_e64 v72, v51, 0, s[38:39]
	v_cndmask_b32_e64 v186, v52, 0, s[4:5]
	v_add_u32_e32 v50, 11, v119
	v_exp_f32_e32 v51, v73
	v_exp_f32_e32 v52, v57
	v_cmp_gt_i32_e32 vcc, v50, v178
	v_add_u32_e32 v50, 43, v119
	v_cmp_gt_i32_e64 s[4:5], v50, v178
	s_and_b64 s[38:39], s[20:21], vcc
	s_and_b64 s[4:5], s[20:21], s[4:5]
	v_cndmask_b32_e64 v57, v51, 0, s[38:39]
	v_cndmask_b32_e64 v73, v52, 0, s[4:5]
	v_add_u32_e32 v50, 16, v119
	v_exp_f32_e32 v51, v74
	v_exp_f32_e32 v52, v58
	v_cmp_gt_i32_e32 vcc, v50, v178
	v_add_u32_e32 v50, 48, v119
	v_cmp_gt_i32_e64 s[4:5], v50, v178
	s_and_b64 s[38:39], s[20:21], vcc
	s_and_b64 s[4:5], s[20:21], s[4:5]
	v_cndmask_b32_e64 v74, v51, 0, s[38:39]
	v_cndmask_b32_e64 v189, v52, 0, s[4:5]
	v_add_u32_e32 v50, 17, v119
	v_exp_f32_e32 v51, v75
	v_exp_f32_e32 v52, v59
	v_cmp_gt_i32_e32 vcc, v50, v178
	v_add_u32_e32 v50, 49, v119
	v_cmp_gt_i32_e64 s[4:5], v50, v178
	s_and_b64 s[38:39], s[20:21], vcc
	s_and_b64 s[4:5], s[20:21], s[4:5]
	v_cndmask_b32_e64 v75, v51, 0, s[38:39]
	v_cndmask_b32_e64 v191, v52, 0, s[4:5]
	v_add_u32_e32 v50, 18, v119
	v_exp_f32_e32 v51, v76
	v_exp_f32_e32 v52, v60
	v_cmp_gt_i32_e32 vcc, v50, v178
	v_add_u32_e32 v50, 50, v119
	v_cmp_gt_i32_e64 s[4:5], v50, v178
	s_and_b64 s[38:39], s[20:21], vcc
	s_and_b64 s[4:5], s[20:21], s[4:5]
	v_cndmask_b32_e64 v76, v51, 0, s[38:39]
	v_cndmask_b32_e64 v192, v52, 0, s[4:5]
	v_add_u32_e32 v50, 19, v119
	v_exp_f32_e32 v51, v77
	v_exp_f32_e32 v52, v61
	v_cmp_gt_i32_e32 vcc, v50, v178
	v_add_u32_e32 v50, 51, v119
	v_cmp_gt_i32_e64 s[4:5], v50, v178
	s_and_b64 s[38:39], s[20:21], vcc
	s_and_b64 s[4:5], s[20:21], s[4:5]
	v_cndmask_b32_e64 v77, v51, 0, s[38:39]
	v_cndmask_b32_e64 v193, v52, 0, s[4:5]
	v_add_u32_e32 v50, 24, v119
	v_exp_f32_e32 v51, v78
	v_exp_f32_e32 v52, v62
	v_cmp_gt_i32_e32 vcc, v50, v178
	v_add_u32_e32 v50, 56, v119
	v_cmp_gt_i32_e64 s[4:5], v50, v178
	s_and_b64 s[38:39], s[20:21], vcc
	s_and_b64 s[4:5], s[20:21], s[4:5]
	v_add_u32_e32 v50, 25, v119
	v_exp_f32_e32 v54, v79
	v_add_u32_e32 v79, s37, v229
	v_cndmask_b32_e64 v62, v51, 0, s[38:39]
	v_cndmask_b32_e64 v78, v52, 0, s[4:5]
	v_cmp_gt_i32_e32 vcc, v50, v178
	ds_read_b64_tr_b16 v[50:51], v79 offset:26624
	ds_read_b64_tr_b16 v[52:53], v79 offset:28160
	ds_read_b64_tr_b16 v[60:61], v79 offset:28224
	ds_read_b64_tr_b16 v[58:59], v79 offset:26688
	s_and_b64 s[4:5], s[20:21], vcc
	v_add_f32_e32 v188, v57, v73
	v_cndmask_b32_e64 v194, v54, 0, s[4:5]
	v_cvt_pk_bf16_f32 v54, v66, v67
	v_cvt_pk_bf16_f32 v55, v68, v69
	v_cvt_pk_bf16_f32 v56, v70, v71
	v_cvt_pk_bf16_f32 v57, v72, v57
	v_exp_f32_e32 v80, v80
	v_add_f32_e32 v135, v67, v133
	s_waitcnt lgkmcnt(2)
; #define MFMA32(a, b, c) __builtin_amdgcn_mfma_f32_32x32x16_bf16((a), (b), (c), 0, 0, 0)
; DI int crow(int r, int hi) { return (r & 3) + 8 * (r >> 2) + 4 * hi; }
; DI void attn_prompt_unit(const Args& a, LAS unsigned char* lds, int b, int h, int qb, float cB, int tid, int lane, int wave) {
;     ...
;             for (int r = 0; r < 16; ++r) { const int kv = t * 64 + crow(r, h2);
;                 float e0 = __builtin_amdgcn_exp2f(p0[r]), e1 = __builtin_amdgcn_exp2f(p1[r]);
;                 if (diag) { if (kv > qloc) e0 = 0.f; if (kv + 32 > qloc) e1 = 0.f; }
;                 p0[r] = e0; p1[r] = e1; lsum += e0 + e1; }
; #pragma unroll
;             for (int s4 = 0; s4 < 4; ++s4) { const bf16x8 pf = (s4 < 2) ? pack8(p0, s4 & 1) : pack8(p1, s4 & 1);
;                 o0 = MFMA32(tr_frag(Vb, 96, 16 * s4 + 4 * h2, 16 * s4 + 8 + 4 * h2, 0, lane), pf, o0); o1 = MFMA32(tr_frag(Vb, 96, 16 * s4 + 4 * h2, 16 * s4 + 8 + 4 * h2, 32, lane), pf, o1); }
	v_mfma_f32_32x32x16_bf16 v[18:33], v[50:53], v[54:57], v[18:33]
	v_add_u32_e32 v50, 26, v119
	v_cmp_gt_i32_e32 vcc, v50, v178
	v_add_u32_e32 v50, 27, v119
	v_exp_f32_e32 v67, v81
	s_and_b64 s[4:5], s[20:21], vcc
	v_cmp_gt_i32_e32 vcc, v50, v178
	ds_read_b64_tr_b16 v[50:51], v79 offset:29696
	ds_read_b64_tr_b16 v[52:53], v79 offset:31232
	s_waitcnt lgkmcnt(2)
	v_mfma_f32_32x32x16_bf16 v[34:49], v[58:61], v[54:57], v[34:49]
	ds_read_b64_tr_b16 v[60:61], v79 offset:31296
	ds_read_b64_tr_b16 v[58:59], v79 offset:29760
	v_add_f32_e32 v129, v66, v121
	v_cndmask_b32_e64 v66, v80, 0, s[4:5]
	s_and_b64 s[4:5], s[20:21], vcc
	v_cndmask_b32_e64 v67, v67, 0, s[4:5]
	v_cvt_pk_bf16_f32 v54, v74, v75
	v_cvt_pk_bf16_f32 v55, v76, v77
	v_cvt_pk_bf16_f32 v56, v62, v194
	v_cvt_pk_bf16_f32 v57, v66, v67
	v_add_f32_e32 v1, v1, v129
	v_add_f32_e32 v139, v68, v137
	s_waitcnt lgkmcnt(2)
	v_mfma_f32_32x32x16_bf16 v[18:33], v[50:53], v[54:57], v[18:33]
	v_exp_f32_e32 v50, v63
	v_add_u32_e32 v51, 57, v119
	v_cmp_gt_i32_e32 vcc, v51, v178
	s_and_b64 s[4:5], s[20:21], vcc
	v_cndmask_b32_e64 v63, v50, 0, s[4:5]
	ds_read_b64_tr_b16 v[50:51], v79 offset:32768
	ds_read_b64_tr_b16 v[52:53], v79 offset:34304
	v_add_f32_e32 v1, v135, v1
	s_waitcnt lgkmcnt(2)
	v_mfma_f32_32x32x16_bf16 v[34:49], v[58:61], v[54:57], v[34:49]
	ds_read_b64_tr_b16 v[60:61], v79 offset:34368
	ds_read_b64_tr_b16 v[58:59], v79 offset:32832
	v_cvt_pk_bf16_f32 v54, v121, v133
	v_cvt_pk_bf16_f32 v55, v137, v157
	v_cvt_pk_bf16_f32 v56, v161, v171
	v_cvt_pk_bf16_f32 v57, v186, v73
	v_add_f32_e32 v159, v69, v157
	v_add_f32_e32 v1, v139, v1
	s_waitcnt lgkmcnt(2)
	v_mfma_f32_32x32x16_bf16 v[18:33], v[50:53], v[54:57], v[18:33]
	v_add_u32_e32 v50, 58, v119
	v_cmp_gt_i32_e32 vcc, v50, v178
	v_add_u32_e32 v50, 59, v119
	v_add_f32_e32 v169, v70, v161
	s_and_b64 s[4:5], s[20:21], vcc
	v_cmp_gt_i32_e32 vcc, v50, v178
	ds_read_b64_tr_b16 v[50:51], v79 offset:35840
	ds_read_b64_tr_b16 v[52:53], v79 offset:37376
	s_waitcnt lgkmcnt(2)
	v_mfma_f32_32x32x16_bf16 v[34:49], v[58:61], v[54:57], v[34:49]
	ds_read_b64_tr_b16 v[60:61], v79 offset:37440
	ds_read_b64_tr_b16 v[58:59], v79 offset:35904
	v_add_f32_e32 v1, v159, v1
	v_add_f32_e32 v179, v71, v171
	v_add_f32_e32 v1, v169, v1
	v_add_f32_e32 v187, v72, v186
	v_cndmask_b32_e64 v64, v64, 0, s[4:5]
	s_and_b64 s[4:5], s[20:21], vcc
	v_add_f32_e32 v1, v179, v1
	v_cndmask_b32_e64 v65, v65, 0, s[4:5]
	v_add_f32_e32 v1, v187, v1
	v_add_f32_e32 v190, v74, v189
	v_cvt_pk_bf16_f32 v54, v189, v191
	v_cvt_pk_bf16_f32 v55, v192, v193
	v_cvt_pk_bf16_f32 v56, v78, v63
	v_cvt_pk_bf16_f32 v57, v64, v65
	v_add_f32_e32 v1, v188, v1
	v_add_f32_e32 v1, v190, v1
	s_waitcnt lgkmcnt(2)
	v_mfma_f32_32x32x16_bf16 v[18:33], v[50:53], v[54:57], v[18:33]
	v_add_f32_e32 v50, v75, v191
	v_add_f32_e32 v51, v76, v192
	v_add_f32_e32 v1, v50, v1
	v_add_f32_e32 v52, v77, v193
	v_add_f32_e32 v1, v51, v1
	v_add_f32_e32 v53, v62, v78
	v_add_f32_e32 v1, v52, v1
	s_waitcnt lgkmcnt(0)
	v_mfma_f32_32x32x16_bf16 v[34:49], v[58:61], v[54:57], v[34:49]
	v_add_f32_e32 v62, v194, v63
	v_add_f32_e32 v1, v53, v1
	v_add_f32_e32 v63, v66, v64
	v_add_f32_e32 v1, v62, v1
	v_add_f32_e32 v64, v67, v65
	v_add_f32_e32 v1, v63, v1
	v_add_f32_e32 v1, v64, v1
	s_branch .LBB0_843
; #define MFMA32(a, b, c) __builtin_amdgcn_mfma_f32_32x32x16_bf16((a), (b), (c), 0, 0, 0)
; DI int crow(int r, int hi) { return (r & 3) + 8 * (r >> 2) + 4 * hi; }
; DI void attn_prompt_unit(const Args& a, LAS unsigned char* lds, int b, int h, int qb, float cB, int tid, int lane, int wave) {
;     ...
;             for (int r = 0; r < 16; ++r) { const int kv = t * 64 + crow(r, h2);
;                 float e0 = __builtin_amdgcn_exp2f(p0[r]), e1 = __builtin_amdgcn_exp2f(p1[r]);
;                 if (diag) { if (kv > qloc) e0 = 0.f; if (kv + 32 > qloc) e1 = 0.f; }
;                 p0[r] = e0; p1[r] = e1; lsum += e0 + e1; }
; #pragma unroll
;             for (int s4 = 0; s4 < 4; ++s4) { const bf16x8 pf = (s4 < 2) ? pack8(p0, s4 & 1) : pack8(p1, s4 & 1);
;                 o0 = MFMA32(tr_frag(Vb, 96, 16 * s4 + 4 * h2, 16 * s4 + 8 + 4 * h2, 0, lane), pf, o0); o1 = MFMA32(tr_frag(Vb, 96, 16 * s4 + 4 * h2, 16 * s4 + 8 + 4 * h2, 32, lane), pf, o1); }
.Lpa_fast_0:
	s_nop 10
	v_exp_f32_e32 v121, v50
	v_exp_f32_e32 v133, v51
	v_exp_f32_e32 v137, v52
	v_exp_f32_e32 v64, v64
	v_exp_f32_e32 v65, v65
	v_exp_f32_e32 v66, v66
	v_exp_f32_e32 v67, v67
	v_exp_f32_e32 v68, v68
	v_exp_f32_e32 v69, v69
	v_exp_f32_e32 v157, v53
	v_exp_f32_e32 v70, v70
	v_exp_f32_e32 v161, v54
	v_exp_f32_e32 v71, v71
	v_exp_f32_e32 v171, v55
	v_exp_f32_e32 v72, v72
	v_exp_f32_e32 v186, v56
	v_exp_f32_e32 v51, v73
	v_exp_f32_e32 v73, v57
	v_mov_b32_e32 v57, v51
	v_exp_f32_e32 v74, v74
	v_exp_f32_e32 v189, v58
	v_exp_f32_e32 v75, v75
	v_exp_f32_e32 v191, v59
	v_exp_f32_e32 v76, v76
	v_exp_f32_e32 v192, v60
	v_exp_f32_e32 v77, v77
	v_exp_f32_e32 v193, v61
	v_exp_f32_e32 v51, v78
	v_exp_f32_e32 v78, v62
	v_exp_f32_e32 v194, v79
	v_add_u32_e32 v79, s37, v229
	v_mov_b32_e32 v62, v51
	ds_read_b64_tr_b16 v[50:51], v79 offset:26624
	ds_read_b64_tr_b16 v[52:53], v79 offset:28160
	ds_read_b64_tr_b16 v[60:61], v79 offset:28224
	ds_read_b64_tr_b16 v[58:59], v79 offset:26688
	v_add_f32_e32 v188, v57, v73
	v_cvt_pk_bf16_f32 v54, v66, v67
	v_cvt_pk_bf16_f32 v55, v68, v69
	v_cvt_pk_bf16_f32 v56, v70, v71
	v_cvt_pk_bf16_f32 v57, v72, v57
	v_exp_f32_e32 v80, v80
	v_add_f32_e32 v135, v67, v133
	s_waitcnt lgkmcnt(2)
	v_mfma_f32_32x32x16_bf16 v[18:33], v[50:53], v[54:57], v[18:33]
	v_exp_f32_e32 v67, v81
	ds_read_b64_tr_b16 v[50:51], v79 offset:29696
	ds_read_b64_tr_b16 v[52:53], v79 offset:31232
	s_waitcnt lgkmcnt(2)
	v_mfma_f32_32x32x16_bf16 v[34:49], v[58:61], v[54:57], v[34:49]
	ds_read_b64_tr_b16 v[60:61], v79 offset:31296
	ds_read_b64_tr_b16 v[58:59], v79 offset:29760
	v_add_f32_e32 v129, v66, v121
	v_mov_b32_e32 v66, v80
	v_cvt_pk_bf16_f32 v54, v74, v75
	v_cvt_pk_bf16_f32 v55, v76, v77
	v_cvt_pk_bf16_f32 v56, v62, v194
	v_cvt_pk_bf16_f32 v57, v66, v67
	v_add_f32_e32 v1, v1, v129
	v_add_f32_e32 v139, v68, v137
	s_waitcnt lgkmcnt(2)
	v_mfma_f32_32x32x16_bf16 v[18:33], v[50:53], v[54:57], v[18:33]
	v_exp_f32_e32 v63, v63
	ds_read_b64_tr_b16 v[50:51], v79 offset:32768
	ds_read_b64_tr_b16 v[52:53], v79 offset:34304
	v_add_f32_e32 v1, v135, v1
	s_waitcnt lgkmcnt(2)
	v_mfma_f32_32x32x16_bf16 v[34:49], v[58:61], v[54:57], v[34:49]
	ds_read_b64_tr_b16 v[60:61], v79 offset:34368
	ds_read_b64_tr_b16 v[58:59], v79 offset:32832
	v_cvt_pk_bf16_f32 v54, v121, v133
	v_cvt_pk_bf16_f32 v55, v137, v157
	v_cvt_pk_bf16_f32 v56, v161, v171
	v_cvt_pk_bf16_f32 v57, v186, v73
	v_add_f32_e32 v159, v69, v157
	v_add_f32_e32 v1, v139, v1
	s_waitcnt lgkmcnt(2)
	v_mfma_f32_32x32x16_bf16 v[18:33], v[50:53], v[54:57], v[18:33]
	v_add_f32_e32 v169, v70, v161
	ds_read_b64_tr_b16 v[50:51], v79 offset:35840
	ds_read_b64_tr_b16 v[52:53], v79 offset:37376
	s_waitcnt lgkmcnt(2)
	v_mfma_f32_32x32x16_bf16 v[34:49], v[58:61], v[54:57], v[34:49]
	ds_read_b64_tr_b16 v[60:61], v79 offset:37440
	ds_read_b64_tr_b16 v[58:59], v79 offset:35904
	v_add_f32_e32 v1, v159, v1
	v_add_f32_e32 v179, v71, v171
	v_add_f32_e32 v1, v169, v1
	v_add_f32_e32 v187, v72, v186
	v_add_f32_e32 v1, v179, v1
	v_add_f32_e32 v1, v187, v1
	v_add_f32_e32 v190, v74, v189
	v_cvt_pk_bf16_f32 v54, v189, v191
	v_cvt_pk_bf16_f32 v55, v192, v193
	v_cvt_pk_bf16_f32 v56, v78, v63
	v_cvt_pk_bf16_f32 v57, v64, v65
	v_add_f32_e32 v1, v188, v1
	v_add_f32_e32 v1, v190, v1
	s_waitcnt lgkmcnt(2)
	v_mfma_f32_32x32x16_bf16 v[18:33], v[50:53], v[54:57], v[18:33]
	v_add_f32_e32 v50, v75, v191
	v_add_f32_e32 v51, v76, v192
	v_add_f32_e32 v1, v50, v1
	v_add_f32_e32 v52, v77, v193
	v_add_f32_e32 v1, v51, v1
	v_add_f32_e32 v53, v62, v78
	v_add_f32_e32 v1, v52, v1
	s_waitcnt lgkmcnt(0)
	v_mfma_f32_32x32x16_bf16 v[34:49], v[58:61], v[54:57], v[34:49]
	v_add_f32_e32 v62, v194, v63
	v_add_f32_e32 v1, v53, v1
	v_add_f32_e32 v63, v66, v64
	v_add_f32_e32 v1, v62, v1
	v_add_f32_e32 v64, v67, v65
	v_add_f32_e32 v1, v63, v1
	v_add_f32_e32 v1, v64, v1

; DI void attn_prompt_unit(const Args& a, LAS unsigned char* lds, int b, int h, int qb, float cB, int tid, int lane, int wave) {
;     ...
;     { const bf16* QR = (const bf16*)(a.ws + WS_QRAW); const float* gq = (const float*)a.in[I_GQH]; const float* rc = (const float*)(a.ws + WS_ROPE); const float* rs = rc + 8200 * 16;
;         u32x4 wq[6]; float ss = 0.f;
; #pragma unroll
;         for (int s = 0; s < 6; ++s) { wq[s] = *(const u32x4*)(QR + qrow * 768 + h * 96 + 16 * s + 8 * h2);
;             const float e0 = bflo(wq[s].x), e1 = bfhi(wq[s].x), e2 = bflo(wq[s].y), e3 = bfhi(wq[s].y), e4 = bflo(wq[s].z), e5 = bfhi(wq[s].z), e6 = bflo(wq[s].w), e7 = bfhi(wq[s].w);
;             ss += ((e0 * e0 + e1 * e1) + (e2 * e2 + e3 * e3)) + ((e4 * e4 + e5 * e5) + (e6 * e6 + e7 * e7)); }
;         ss += __shfl_xor(ss, 32);
;         const float r = __builtin_amdgcn_rsqf(ss * (1.f / 96.f) + EPS) * QSCALE;
; #pragma unroll
;         for (int s = 0; s < 4; ++s) { const f32x4 g0 = *(const f32x4*)(gq + 16 * s + 8 * h2) * r, g1 = *(const f32x4*)(gq + 16 * s + 8 * h2 + 4) * r;
;             u32x4 o; o.x = pk2(bflo(wq[s].x) * g0.x, bfhi(wq[s].x) * g0.y); o.y = pk2(bflo(wq[s].y) * g0.z, bfhi(wq[s].y) * g0.w); o.z = pk2(bflo(wq[s].z) * g1.x, bfhi(wq[s].z) * g1.y); o.w = pk2(bflo(wq[s].w) * g1.z, bfhi(wq[s].w) * g1.w);
;             qf[s] = __builtin_bit_cast(bf16x8, o); }
;         { const f32x4 ga0 = *(const f32x4*)(gq + 64 + 8 * h2) * r, ga1 = *(const f32x4*)(gq + 64 + 8 * h2 + 4) * r, gb0 = *(const f32x4*)(gq + 80 + 8 * h2) * r, gb1 = *(const f32x4*)(gq + 80 + 8 * h2 + 4) * r;
;             const f32x4 c0 = *(const f32x4*)(rc + qloc * 16 + 8 * h2), c1 = *(const f32x4*)(rc + qloc * 16 + 8 * h2 + 4), s0 = *(const f32x4*)(rs + qloc * 16 + 8 * h2), s1 = *(const f32x4*)(rs + qloc * 16 + 8 * h2 + 4);
;     ...
;     lsum += __shfl_xor(lsum, 32);
;     const float inv = 1.f / lsum;
;     bf16* op = MIX + qrow * DM + h * 64;
; #pragma unroll
;     for (int q = 0; q < 4; ++q) { const int dv = 8 * q + 4 * h2;
;         u32x2 w0, w1; w0.x = pk2(o0[4 * q] * inv, o0[4 * q + 1] * inv); w0.y = pk2(o0[4 * q + 2] * inv, o0[4 * q + 3] * inv);
;         w1.x = pk2(o1[4 * q] * inv, o1[4 * q + 1] * inv); w1.y = pk2(o1[4 * q + 2] * inv, o1[4 * q + 3] * inv);
;         *(u32x2*)(op + dv) = w0; *(u32x2*)(op + 32 + dv) = w1; }
.LBB0_847:
	ds_bpermute_b32 v50, v143, v1
	v_mov_b32_e32 v161, v127
	s_waitcnt lgkmcnt(0)
	s_barrier
	v_add_f32_e32 v1, v1, v50
	v_div_scale_f32 v50, s[4:5], v1, v1, 1.0
	v_rcp_f32_e32 v51, v50
	s_lshl_b32 s4, s27, 7
	v_fma_f32 v53, -v50, v51, 1.0
	v_fmac_f32_e32 v51, v53, v51
	v_rcp_f32_e32 v50, v1
	v_lshlrev_b64 v[52:53], 11, v[176:177]
	v_lshl_add_u64 v[52:53], s[10:11], 0, v[52:53]
	s_mov_b32 s5, s7
	v_pk_mul_f32 v[18:19], v[18:19], v[50:51] op_sel_hi:[1,0]
	v_pk_mul_f32 v[20:21], v[20:21], v[50:51] op_sel_hi:[1,0]
	v_lshl_add_u64 v[52:53], v[52:53], 0, s[4:5]
	v_cvt_pk_bf16_f32 v18, v18, v19
	v_cvt_pk_bf16_f32 v19, v20, v21
	v_pk_mul_f32 v[20:21], v[34:35], v[50:51] op_sel_hi:[1,0]
	v_pk_mul_f32 v[34:35], v[36:37], v[50:51] op_sel_hi:[1,0]
	v_cvt_pk_bf16_f32 v20, v20, v21
	v_cvt_pk_bf16_f32 v21, v34, v35
	v_lshl_add_u64 v[34:35], v[52:53], 0, v[160:161]
	global_store_dwordx2 v[34:35], v[18:19], off
	global_store_dwordx2 v[34:35], v[20:21], off offset:64
	v_pk_mul_f32 v[18:19], v[22:23], v[50:51] op_sel_hi:[1,0]
	v_pk_mul_f32 v[20:21], v[24:25], v[50:51] op_sel_hi:[1,0]
	v_cvt_pk_bf16_f32 v18, v18, v19
	v_cvt_pk_bf16_f32 v19, v20, v21
	v_pk_mul_f32 v[20:21], v[38:39], v[50:51] op_sel_hi:[1,0]
	v_pk_mul_f32 v[22:23], v[40:41], v[50:51] op_sel_hi:[1,0]
	v_cvt_pk_bf16_f32 v20, v20, v21
	v_cvt_pk_bf16_f32 v21, v22, v23
	global_store_dwordx2 v[34:35], v[18:19], off offset:16
	global_store_dwordx2 v[34:35], v[20:21], off offset:80
	v_pk_mul_f32 v[18:19], v[26:27], v[50:51] op_sel_hi:[1,0]
	v_pk_mul_f32 v[20:21], v[28:29], v[50:51] op_sel_hi:[1,0]
	v_cvt_pk_bf16_f32 v18, v18, v19
	v_cvt_pk_bf16_f32 v19, v20, v21
	v_pk_mul_f32 v[20:21], v[42:43], v[50:51] op_sel_hi:[1,0]
	v_pk_mul_f32 v[22:23], v[44:45], v[50:51] op_sel_hi:[1,0]
	s_lshl_b32 s20, s28, 8
	v_cvt_pk_bf16_f32 v20, v20, v21
	v_cvt_pk_bf16_f32 v21, v22, v23
	s_add_i32 s20, s20, s46
	global_store_dwordx2 v[34:35], v[18:19], off offset:32
	global_store_dwordx2 v[34:35], v[20:21], off offset:96
	v_pk_mul_f32 v[18:19], v[30:31], v[50:51] op_sel_hi:[1,0]
	v_pk_mul_f32 v[20:21], v[32:33], v[50:51] op_sel_hi:[1,0]
	v_or_b32_e32 v178, s20, v210
	v_cvt_pk_bf16_f32 v18, v18, v19
	v_cvt_pk_bf16_f32 v19, v20, v21
	v_pk_mul_f32 v[20:21], v[46:47], v[50:51] op_sel_hi:[1,0]
	v_pk_mul_f32 v[22:23], v[48:49], v[50:51] op_sel_hi:[1,0]
	v_ashrrev_i32_e32 v179, 31, v178
	v_cvt_pk_bf16_f32 v20, v20, v21
	v_cvt_pk_bf16_f32 v21, v22, v23
	global_store_dwordx2 v[34:35], v[18:19], off offset:48
	global_store_dwordx2 v[34:35], v[20:21], off offset:112
	v_lshl_add_u64 v[176:177], s[18:19], 0, v[178:179]
	v_mov_b64_e32 v[18:19], s[8:9]
	v_mad_u64_u32 v[18:19], s[4:5], v176, s22, v[18:19]
	v_mad_i32_i24 v19, v177, s22, v19
	v_lshl_add_u64 v[18:19], v[18:19], 0, s[6:7]
	v_lshl_add_u64 v[18:19], v[18:19], 0, v[126:127]
	global_load_dwordx4 v[22:25], v[18:19], off offset:128
	global_load_dwordx4 v[26:29], v[18:19], off offset:160
	global_load_dwordx4 v[30:33], v[18:19], off offset:96
	global_load_dwordx4 v[58:61], v[18:19], off offset:64
	v_lshlrev_b32_e32 v20, 4, v178
	v_ashrrev_i32_e32 v21, 31, v20
	v_lshlrev_b64 v[90:91], 2, v[20:21]
	global_load_dwordx4 v[82:85], v[18:19], off offset:32
	v_lshl_add_u64 v[92:93], v[146:147], 0, v[90:91]
	global_load_dwordx4 v[232:235], v[18:19], off
	s_nop 0
	global_load_dwordx4 v[18:21], v[92:93], off
	global_load_dwordx4 v[78:81], v[144:145], off offset:16
	global_load_dwordx4 v[86:89], v[144:145], off
	global_load_dwordx4 v[70:73], v[144:145], off offset:80
	global_load_dwordx4 v[74:77], v[144:145], off offset:64
	global_load_dwordx4 v[62:65], v[144:145], off offset:144
	global_load_dwordx4 v[66:69], v[144:145], off offset:128
	global_load_dwordx4 v[38:41], v[144:145], off offset:208
	global_load_dwordx4 v[50:53], v[144:145], off offset:192
	global_load_dwordx4 v[46:49], v[144:145], off offset:272
	global_load_dwordx4 v[54:57], v[144:145], off offset:256
	global_load_dwordx4 v[34:37], v[144:145], off offset:336
	global_load_dwordx4 v[42:45], v[144:145], off offset:320
	s_waitcnt vmcnt(18)
	v_lshlrev_b32_e32 v106, 16, v22
	v_and_b32_e32 v107, 0xffff0000, v22
	s_waitcnt vmcnt(16)
; DI void attn_prompt_unit(const Args& a, LAS unsigned char* lds, int b, int h, int qb, float cB, int tid, int lane, int wave) {
;     ...
;         u32x4 wq[6]; float ss = 0.f;
; #pragma unroll
;         for (int s = 0; s < 6; ++s) { wq[s] = *(const u32x4*)(QR + qrow * 768 + h * 96 + 16 * s + 8 * h2);
;             const float e0 = bflo(wq[s].x), e1 = bfhi(wq[s].x), e2 = bflo(wq[s].y), e3 = bfhi(wq[s].y), e4 = bflo(wq[s].z), e5 = bfhi(wq[s].z), e6 = bflo(wq[s].w), e7 = bfhi(wq[s].w);
;             ss += ((e0 * e0 + e1 * e1) + (e2 * e2 + e3 * e3)) + ((e4 * e4 + e5 * e5) + (e6 * e6 + e7 * e7)); }
;         ss += __shfl_xor(ss, 32);
;         const float r = __builtin_amdgcn_rsqf(ss * (1.f / 96.f) + EPS) * QSCALE;
; #pragma unroll
;         for (int s = 0; s < 4; ++s) { const f32x4 g0 = *(const f32x4*)(gq + 16 * s + 8 * h2) * r, g1 = *(const f32x4*)(gq + 16 * s + 8 * h2 + 4) * r;
;             u32x4 o; o.x = pk2(bflo(wq[s].x) * g0.x, bfhi(wq[s].x) * g0.y); o.y = pk2(bflo(wq[s].y) * g0.z, bfhi(wq[s].y) * g0.w); o.z = pk2(bflo(wq[s].z) * g1.x, bfhi(wq[s].z) * g1.y); o.w = pk2(bflo(wq[s].w) * g1.z, bfhi(wq[s].w) * g1.w);
;             qf[s] = __builtin_bit_cast(bf16x8, o); }
;         { const f32x4 ga0 = *(const f32x4*)(gq + 64 + 8 * h2) * r, ga1 = *(const f32x4*)(gq + 64 + 8 * h2 + 4) * r, gb0 = *(const f32x4*)(gq + 80 + 8 * h2) * r, gb1 = *(const f32x4*)(gq + 80 + 8 * h2 + 4) * r;
;             const f32x4 c0 = *(const f32x4*)(rc + qloc * 16 + 8 * h2), c1 = *(const f32x4*)(rc + qloc * 16 + 8 * h2 + 4), s0 = *(const f32x4*)(rs + qloc * 16 + 8 * h2), s1 = *(const f32x4*)(rs + qloc * 16 + 8 * h2 + 4);
;             const f32x4 xa0 = (f32x4){bflo(wq[4].x), bfhi(wq[4].x), bflo(wq[4].y), bfhi(wq[4].y)} * ga0, xa1 = (f32x4){bflo(wq[4].z), bfhi(wq[4].z), bflo(wq[4].w), bfhi(wq[4].w)} * ga1;
;             const f32x4 xb0 = (f32x4){bflo(wq[5].x), bfhi(wq[5].x), bflo(wq[5].y), bfhi(wq[5].y)} * gb0, xb1 = (f32x4){bflo(wq[5].z), bfhi(wq[5].z), bflo(wq[5].w), bfhi(wq[5].w)} * gb1;
;             const f32x4 ra0 = xa0 * c0 - xb0 * s0, ra1 = xa1 * c1 - xb1 * s1, rb0 = xb0 * c0 + xa0 * s0, rb1 = xb1 * c1 + xa1 * s1;
;             u32x4 o4, o5; o4.x = pk2(ra0.x, ra0.y); o4.y = pk2(ra0.z, ra0.w); o4.z = pk2(ra1.x, ra1.y); o4.w = pk2(ra1.z, ra1.w); o5.x = pk2(rb0.x, rb0.y); o5.y = pk2(rb0.z, rb0.w); o5.z = pk2(rb1.x, rb1.y); o5.w = pk2(rb1.z, rb1.w);
	v_and_b32_e32 v1, 0xffff0000, v32
	v_lshlrev_b32_e32 v180, 16, v33
	v_and_b32_e32 v97, 0xffff0000, v33
	v_mov_b32_e32 v96, v1
	v_and_b32_e32 v119, 0xffff0000, v30
	v_lshlrev_b32_e32 v112, 16, v23
	v_and_b32_e32 v113, 0xffff0000, v23
	v_lshlrev_b32_e32 v100, 16, v32
	v_mov_b32_e32 v101, v180
	v_pk_mul_f32 v[22:23], v[96:97], v[96:97]
	v_lshlrev_b32_e32 v182, 16, v31
	v_and_b32_e32 v185, 0xffff0000, v31
	v_mov_b32_e32 v184, v119
	v_pk_fma_f32 v[236:237], v[100:101], v[100:101], v[22:23]
	v_lshlrev_b32_e32 v98, 16, v30
	v_mov_b32_e32 v99, v182
	v_pk_mul_f32 v[22:23], v[184:185], v[184:185]
	v_lshl_add_u64 v[30:31], v[148:149], 0, v[90:91]
	v_lshlrev_b32_e32 v110, 16, v24
	v_and_b32_e32 v111, 0xffff0000, v24
	v_lshlrev_b32_e32 v114, 16, v25
	v_and_b32_e32 v115, 0xffff0000, v25
	v_lshlrev_b32_e32 v104, 16, v26
	v_and_b32_e32 v105, 0xffff0000, v26
	v_lshlrev_b32_e32 v116, 16, v27
	v_and_b32_e32 v117, 0xffff0000, v27
	v_lshlrev_b32_e32 v102, 16, v28
	v_and_b32_e32 v103, 0xffff0000, v28
	v_lshlrev_b32_e32 v108, 16, v29
	v_and_b32_e32 v109, 0xffff0000, v29
	v_pk_fma_f32 v[238:239], v[98:99], v[98:99], v[22:23]
	global_load_dwordx4 v[22:25], v[30:31], off offset:16
	global_load_dwordx4 v[26:29], v[92:93], off offset:16
	s_nop 0
	global_load_dwordx4 v[30:33], v[30:31], off
	s_nop 0
	global_load_dwordx4 v[90:93], v[172:173], off
	s_waitcnt vmcnt(19)
	v_and_b32_e32 v121, 0xffff0000, v59
	v_and_b32_e32 v129, 0xffff0000, v58
	v_lshlrev_b32_e32 v184, 16, v61
	v_and_b32_e32 v191, 0xffff0000, v61
	v_lshlrev_b32_e32 v96, 16, v60
	v_and_b32_e32 v189, 0xffff0000, v60
	v_mov_b32_e32 v190, v121
	v_mov_b32_e32 v188, v129
	v_lshlrev_b32_e32 v186, 16, v59
	v_lshlrev_b32_e32 v94, 16, v58
	v_mov_b32_e32 v187, v184
	v_pk_mul_f32 v[58:59], v[190:191], v[190:191]
	v_mov_b32_e32 v95, v96
	v_pk_mul_f32 v[60:61], v[188:189], v[188:189]
	s_waitcnt vmcnt(17)
	v_and_b32_e32 v139, 0xffff0000, v235
	v_and_b32_e32 v133, 0xffff0000, v234
	v_pk_fma_f32 v[58:59], v[186:187], v[186:187], v[58:59]
	v_pk_fma_f32 v[60:61], v[94:95], v[94:95], v[60:61]
	v_lshlrev_b32_e32 v172, 16, v85
	v_and_b32_e32 v209, 0xffff0000, v85
	v_lshlrev_b32_e32 v188, 16, v84
	v_and_b32_e32 v207, 0xffff0000, v84
	v_mov_b32_e32 v208, v139
	v_mov_b32_e32 v206, v133
	v_pk_add_f32 v[58:59], v[60:61], v[58:59]
	v_lshlrev_b32_e32 v190, 16, v83
	v_and_b32_e32 v205, 0xffff0000, v83
	v_lshlrev_b32_e32 v192, 16, v82
	v_and_b32_e32 v203, 0xffff0000, v82
	v_lshlrev_b32_e32 v194, 16, v235
	v_lshlrev_b32_e32 v196, 16, v234
	v_and_b32_e32 v135, 0xffff0000, v233
	v_and_b32_e32 v137, 0xffff0000, v232
	v_mov_b32_e32 v195, v172
	v_pk_mul_f32 v[60:61], v[208:209], v[208:209]
	v_mov_b32_e32 v197, v188
	v_pk_mul_f32 v[82:83], v[206:207], v[206:207]
	v_pk_fma_f32 v[60:61], v[194:195], v[194:195], v[60:61]
	v_pk_fma_f32 v[82:83], v[196:197], v[196:197], v[82:83]
	v_mov_b32_e32 v204, v135
	v_mov_b32_e32 v202, v137
	v_lshlrev_b32_e32 v198, 16, v233
	v_lshlrev_b32_e32 v200, 16, v232
	v_pk_add_f32 v[60:61], v[82:83], v[60:61]
	v_mov_b32_e32 v199, v190
	v_pk_mul_f32 v[82:83], v[204:205], v[204:205]
	v_mov_b32_e32 v201, v192
	v_pk_mul_f32 v[84:85], v[202:203], v[202:203]
	v_pk_fma_f32 v[82:83], v[198:199], v[198:199], v[82:83]
	v_pk_fma_f32 v[84:85], v[200:201], v[200:201], v[84:85]
	v_mul_f32_e32 v171, v102, v102
	v_pk_add_f32 v[82:83], v[84:85], v[82:83]
	v_mul_f32_e32 v84, v113, v113
	v_pk_add_f32 v[60:61], v[82:83], v[60:61]
	v_mul_f32_e32 v82, v107, v107
	v_mul_f32_e32 v179, v103, v103
	v_pk_fma_f32 v[82:83], v[106:107], v[106:107], v[82:83] op_sel_hi:[1,1,0]
	v_pk_fma_f32 v[84:85], v[112:113], v[112:113], v[84:85] op_sel_hi:[1,1,0]
	v_mov_b32_e32 v83, v171
	v_mov_b32_e32 v85, v179
	v_pk_add_f32 v[82:83], v[82:83], v[84:85]
	v_mul_f32_e32 v84, v111, v111
	v_mul_f32_e32 v202, v115, v115
	v_mul_f32_e32 v181, v108, v108
	v_mul_f32_e32 v183, v109, v109
	v_pk_fma_f32 v[84:85], v[110:111], v[110:111], v[84:85] op_sel_hi:[1,1,0]
	v_pk_fma_f32 v[232:233], v[114:115], v[114:115], v[202:203] op_sel_hi:[1,1,0]
	v_mov_b32_e32 v85, v181
	v_mov_b32_e32 v233, v183
	v_pk_add_f32 v[84:85], v[84:85], v[232:233]
	v_mul_f32_e32 v157, v104, v104
	v_mul_f32_e32 v159, v105, v105
	v_mul_f32_e32 v161, v116, v116
	v_mul_f32_e32 v169, v117, v117
	v_pk_add_f32 v[82:83], v[82:83], v[84:85]
	v_pk_add_f32 v[84:85], v[238:239], v[238:239] op_sel:[0,1] op_sel_hi:[1,0]
	v_pk_add_f32 v[232:233], v[236:237], v[236:237] op_sel:[0,1] op_sel_hi:[1,0]
	v_pk_add_f32 v[60:61], v[60:61], v[60:61] op_sel:[0,1] op_sel_hi:[1,0]
	v_pk_add_f32 v[58:59], v[58:59], v[58:59] op_sel:[0,1] op_sel_hi:[1,0]
	v_mov_b32_e32 v85, v161
	v_mov_b32_e32 v233, v169
	v_mov_b32_e32 v61, v157
	v_mov_b32_e32 v59, v159
	v_pk_add_f32 v[84:85], v[84:85], v[232:233]
	v_pk_add_f32 v[58:59], v[60:61], v[58:59]
	s_nop 0
	v_pk_add_f32 v[58:59], v[58:59], v[84:85]
	v_mov_b32_e32 v84, v127
	v_pk_add_f32 v[58:59], v[58:59], v[82:83]
	v_mov_b32_e32 v82, v127
	v_add_f32_e32 v157, v58, v59
	ds_bpermute_b32 v159, v143, v157
	v_mov_b32_e32 v83, v127
	v_mov_b32_e32 v85, v127
	s_and_saveexec_b64 s[4:5], s[2:3]
	s_cbranch_execz .LBB0_849
	v_mov_b32_e32 v171, v127
	v_lshl_add_u64 v[58:59], s[16:17], 0, v[170:171]
	v_mov_b32_e32 v169, v127
	v_lshl_add_u64 v[58:59], v[58:59], 0, v[168:169]
	global_load_dwordx4 v[82:85], v[58:59], off

; #define LAS __attribute__((address_space(3)))
; #define MFMA32(a, b, c) __builtin_amdgcn_mfma_f32_32x32x16_bf16((a), (b), (c), 0, 0, 0)
; DI int crow(int r, int hi) { return (r & 3) + 8 * (r >> 2) + 4 * hi; }
; DI void attn_prompt_unit(const Args& a, LAS unsigned char* lds, int b, int h, int qb, float cB, int tid, int lane, int wave) {
;     ...
;         if (t + 1 < NT) { const size_t kv1 = (size_t)(t + 1) * 64;
;             kst0 = *(const u32x4*)(kbase + (kv1 + kr0) * 768 + kp0 * 8); if (k1) kst1 = *(const u32x4*)(kbase + (kv1 + kr1) * 768 + kp1 * 8); vst = *(const u32x4*)(vbase + kv1 * 1024); }
;         if (t * 64 <= qmax_w) {
;             const LAS bf16* Kb = Ks + buf * 6656; const LAS bf16* Vb = Vs + buf * 6144;
;             f32x16 p0, p1;
; #pragma unroll
;             for (int r = 0; r < 16; ++r) { p0[r] = -cB; p1[r] = -cB; }
; #pragma unroll
;             for (int s = 0; s < 6; ++s) { const bf16x8 k0 = *(const LAS bf16x8*)(Kb + r32 * 104 + 16 * s + 8 * h2), k1f = *(const LAS bf16x8*)(Kb + (32 + r32) * 104 + 16 * s + 8 * h2);
;                 p0 = MFMA32(k0, qf[s], p0); p1 = MFMA32(k1f, qf[s], p1); }
;             const bool diag = (t * 64 + 63 > qb * 256 + wave * 32);
; #pragma unroll
;             for (int r = 0; r < 16; ++r) { const int kv = t * 64 + crow(r, h2);
;                 float e0 = __builtin_amdgcn_exp2f(p0[r]), e1 = __builtin_amdgcn_exp2f(p1[r]);
;                 if (diag) { if (kv > qloc) e0 = 0.f; if (kv + 32 > qloc) e1 = 0.f; }
;                 p0[r] = e0; p1[r] = e1; lsum += e0 + e1; }
; #pragma unroll
.LBB0_855:
	s_or_b64 exec, exec, s[4:5]
	global_load_dwordx4 v[114:117], v[162:163], off
	s_and_b32 s28, s27, 1
	s_cmp_gt_i32 s21, s19
	s_cbranch_scc1 .LBB0_857
	s_mul_i32 s4, s28, 0x3400
	s_add_i32 s4, s4, 0
	v_add3_u32 v119, s4, v227, v126
	ds_read_b128 v[50:53], v119
	ds_read_b128 v[168:171], v119 offset:32
	v_add3_u32 v121, s4, v228, v126
	ds_read_b128 v[172:175], v121
	ds_read_b128 v[180:183], v121 offset:32
	s_add_i32 s4, s21, 63
	s_cmp_gt_i32 s4, s20
	s_cselect_b64 s[16:17], -1, 0
	s_mul_i32 s29, s28, 0x3000
	s_waitcnt lgkmcnt(3)
	v_mfma_f32_32x32x16_bf16 v[66:81], v[50:53], v[86:89], v[2:17]
	s_waitcnt lgkmcnt(1)
	v_mfma_f32_32x32x16_bf16 v[50:65], v[172:175], v[86:89], v[2:17]
	v_mfma_f32_32x32x16_bf16 v[66:81], v[168:171], v[90:93], v[66:81]
	ds_read_b128 v[168:171], v119 offset:64
	ds_read_b128 v[172:175], v119 offset:96
	s_waitcnt lgkmcnt(2)
	v_mfma_f32_32x32x16_bf16 v[50:65], v[180:183], v[90:93], v[50:65]
	s_waitcnt lgkmcnt(1)
	v_mfma_f32_32x32x16_bf16 v[66:81], v[168:171], v[94:97], v[66:81]
	ds_read_b128 v[168:171], v121 offset:64
	ds_read_b128 v[180:183], v121 offset:96
	s_waitcnt lgkmcnt(1)
	v_mfma_f32_32x32x16_bf16 v[50:65], v[168:171], v[94:97], v[50:65]
	v_mfma_f32_32x32x16_bf16 v[66:81], v[172:175], v[98:101], v[66:81]
	ds_read_b128 v[168:171], v119 offset:128
	ds_read_b128 v[172:175], v119 offset:160
	v_add_u32_e32 v119, s21, v118
	v_cmp_gt_i32_e32 vcc, v119, v178
	s_and_b64 s[30:31], s[16:17], vcc
	v_cmp_ge_i32_e32 vcc, v119, v178
	s_waitcnt lgkmcnt(2)
	v_mfma_f32_32x32x16_bf16 v[50:65], v[180:183], v[98:101], v[50:65]
	s_waitcnt lgkmcnt(1)
	v_mfma_f32_32x32x16_bf16 v[66:81], v[168:171], v[106:109], v[66:81]
	ds_read_b128 v[168:171], v121 offset:128
	ds_read_b128 v[180:183], v121 offset:160
	v_add_u32_e32 v121, 32, v119
	v_cmp_gt_i32_e64 s[4:5], v121, v178
	s_and_b64 s[4:5], s[16:17], s[4:5]
	s_waitcnt lgkmcnt(1)
	v_mfma_f32_32x32x16_bf16 v[50:65], v[168:171], v[106:109], v[50:65]
	s_waitcnt lgkmcnt(0)
	v_mfma_f32_32x32x16_bf16 v[50:65], v[180:183], v[102:105], v[50:65]
	v_mfma_f32_32x32x16_bf16 v[66:81], v[172:175], v[102:105], v[66:81]
	s_cmp_lg_u64 s[16:17], 0
	s_cbranch_scc0 .Lpa_fast_1
	s_nop 10
	v_exp_f32_e32 v50, v50
	v_exp_f32_e32 v51, v51
	v_exp_f32_e32 v52, v52
	v_exp_f32_e32 v64, v64
	v_cndmask_b32_e64 v121, v50, 0, s[4:5]
	v_exp_f32_e32 v65, v65
	v_exp_f32_e32 v66, v66
	v_exp_f32_e32 v50, v67
	v_add_u32_e32 v67, 33, v119
	v_cmp_gt_i32_e64 s[4:5], v67, v178
	v_cndmask_b32_e64 v66, v66, 0, s[30:31]
	s_and_b64 s[30:31], s[16:17], vcc
	s_and_b64 s[4:5], s[16:17], s[4:5]
	v_cndmask_b32_e64 v67, v50, 0, s[30:31]
	v_cndmask_b32_e64 v133, v51, 0, s[4:5]
	v_add_u32_e32 v50, 2, v119
	v_exp_f32_e32 v51, v68
	v_cmp_gt_i32_e32 vcc, v50, v178
	v_add_u32_e32 v50, 34, v119
	v_cmp_gt_i32_e64 s[4:5], v50, v178
	s_and_b64 s[30:31], s[16:17], vcc
	s_and_b64 s[4:5], s[16:17], s[4:5]
	v_cndmask_b32_e64 v68, v51, 0, s[30:31]
	v_cndmask_b32_e64 v137, v52, 0, s[4:5]
	v_add_u32_e32 v50, 3, v119
	v_exp_f32_e32 v51, v69
	v_exp_f32_e32 v52, v53
	v_cmp_gt_i32_e32 vcc, v50, v178
	v_add_u32_e32 v50, 35, v119
	v_cmp_gt_i32_e64 s[4:5], v50, v178
	s_and_b64 s[30:31], s[16:17], vcc
	s_and_b64 s[4:5], s[16:17], s[4:5]
	v_cndmask_b32_e64 v69, v51, 0, s[30:31]
	v_cndmask_b32_e64 v157, v52, 0, s[4:5]
	v_add_u32_e32 v50, 8, v119
	v_exp_f32_e32 v51, v70
	v_exp_f32_e32 v52, v54
	v_cmp_gt_i32_e32 vcc, v50, v178
	v_add_u32_e32 v50, 40, v119
	v_cmp_gt_i32_e64 s[4:5], v50, v178
	s_and_b64 s[30:31], s[16:17], vcc
	s_and_b64 s[4:5], s[16:17], s[4:5]
	v_cndmask_b32_e64 v70, v51, 0, s[30:31]
	v_cndmask_b32_e64 v161, v52, 0, s[4:5]
	v_add_u32_e32 v50, 9, v119
	v_exp_f32_e32 v51, v71
	v_exp_f32_e32 v52, v55
	v_cmp_gt_i32_e32 vcc, v50, v178
	v_add_u32_e32 v50, 41, v119
	v_cmp_gt_i32_e64 s[4:5], v50, v178
	s_and_b64 s[30:31], s[16:17], vcc
	s_and_b64 s[4:5], s[16:17], s[4:5]
	v_cndmask_b32_e64 v71, v51, 0, s[30:31]
	v_cndmask_b32_e64 v169, v52, 0, s[4:5]
	v_add_u32_e32 v50, 10, v119
	v_exp_f32_e32 v51, v72
	v_exp_f32_e32 v52, v56
	v_cmp_gt_i32_e32 vcc, v50, v178
	v_add_u32_e32 v50, 42, v119
	v_cmp_gt_i32_e64 s[4:5], v50, v178
	s_and_b64 s[30:31], s[16:17], vcc
	s_and_b64 s[4:5], s[16:17], s[4:5]
	v_cndmask_b32_e64 v72, v51, 0, s[30:31]
	v_cndmask_b32_e64 v171, v52, 0, s[4:5]
	v_add_u32_e32 v50, 11, v119
	v_exp_f32_e32 v51, v73
	v_exp_f32_e32 v52, v57
	v_cmp_gt_i32_e32 vcc, v50, v178
	v_add_u32_e32 v50, 43, v119
	v_cmp_gt_i32_e64 s[4:5], v50, v178
	s_and_b64 s[30:31], s[16:17], vcc
	s_and_b64 s[4:5], s[16:17], s[4:5]
	v_cndmask_b32_e64 v57, v51, 0, s[30:31]
	v_cndmask_b32_e64 v73, v52, 0, s[4:5]
	v_add_u32_e32 v50, 16, v119
	v_exp_f32_e32 v51, v74
	v_exp_f32_e32 v52, v58
	v_cmp_gt_i32_e32 vcc, v50, v178
	v_add_u32_e32 v50, 48, v119
	v_cmp_gt_i32_e64 s[4:5], v50, v178
	s_and_b64 s[30:31], s[16:17], vcc
	s_and_b64 s[4:5], s[16:17], s[4:5]
	v_cndmask_b32_e64 v74, v51, 0, s[30:31]
	v_cndmask_b32_e64 v174, v52, 0, s[4:5]
	v_add_u32_e32 v50, 17, v119
	v_exp_f32_e32 v51, v75
	v_exp_f32_e32 v52, v59
	v_cmp_gt_i32_e32 vcc, v50, v178
	v_add_u32_e32 v50, 49, v119
	v_cmp_gt_i32_e64 s[4:5], v50, v178
	s_and_b64 s[30:31], s[16:17], vcc
	s_and_b64 s[4:5], s[16:17], s[4:5]
	v_cndmask_b32_e64 v75, v51, 0, s[30:31]
	v_cndmask_b32_e64 v179, v52, 0, s[4:5]
	v_add_u32_e32 v50, 18, v119
	v_exp_f32_e32 v51, v76
	v_exp_f32_e32 v52, v60
	v_cmp_gt_i32_e32 vcc, v50, v178
	v_add_u32_e32 v50, 50, v119
	v_cmp_gt_i32_e64 s[4:5], v50, v178
	s_and_b64 s[30:31], s[16:17], vcc
	s_and_b64 s[4:5], s[16:17], s[4:5]
	v_cndmask_b32_e64 v76, v51, 0, s[30:31]
	v_cndmask_b32_e64 v180, v52, 0, s[4:5]
	v_add_u32_e32 v50, 19, v119
	v_exp_f32_e32 v51, v77
	v_exp_f32_e32 v52, v61
	v_cmp_gt_i32_e32 vcc, v50, v178
	v_add_u32_e32 v50, 51, v119
	v_cmp_gt_i32_e64 s[4:5], v50, v178
	s_and_b64 s[30:31], s[16:17], vcc
	s_and_b64 s[4:5], s[16:17], s[4:5]
	v_cndmask_b32_e64 v77, v51, 0, s[30:31]
	v_cndmask_b32_e64 v181, v52, 0, s[4:5]
	v_add_u32_e32 v50, 24, v119
	v_exp_f32_e32 v51, v78
	v_exp_f32_e32 v52, v62
	v_cmp_gt_i32_e32 vcc, v50, v178
	v_add_u32_e32 v50, 56, v119
	v_cmp_gt_i32_e64 s[4:5], v50, v178
	s_and_b64 s[30:31], s[16:17], vcc
	s_and_b64 s[4:5], s[16:17], s[4:5]
	v_add_u32_e32 v50, 25, v119
	v_exp_f32_e32 v54, v79
	v_add_u32_e32 v79, s29, v229
	v_cndmask_b32_e64 v62, v51, 0, s[30:31]
	v_cndmask_b32_e64 v78, v52, 0, s[4:5]
	v_cmp_gt_i32_e32 vcc, v50, v178
	ds_read_b64_tr_b16 v[50:51], v79 offset:26624
	ds_read_b64_tr_b16 v[52:53], v79 offset:28160
	ds_read_b64_tr_b16 v[60:61], v79 offset:28224
	ds_read_b64_tr_b16 v[58:59], v79 offset:26688
	s_and_b64 s[4:5], s[16:17], vcc
	v_add_f32_e32 v173, v57, v73
	v_cndmask_b32_e64 v182, v54, 0, s[4:5]
	v_cvt_pk_bf16_f32 v54, v66, v67
	v_cvt_pk_bf16_f32 v55, v68, v69
	v_cvt_pk_bf16_f32 v56, v70, v71
	v_cvt_pk_bf16_f32 v57, v72, v57
	v_exp_f32_e32 v80, v80
	v_add_f32_e32 v135, v67, v133
	s_waitcnt lgkmcnt(2)
; #define MFMA32(a, b, c) __builtin_amdgcn_mfma_f32_32x32x16_bf16((a), (b), (c), 0, 0, 0)
; DI int crow(int r, int hi) { return (r & 3) + 8 * (r >> 2) + 4 * hi; }
; DI void attn_prompt_unit(const Args& a, LAS unsigned char* lds, int b, int h, int qb, float cB, int tid, int lane, int wave) {
;     ...
;             for (int r = 0; r < 16; ++r) { const int kv = t * 64 + crow(r, h2);
;                 float e0 = __builtin_amdgcn_exp2f(p0[r]), e1 = __builtin_amdgcn_exp2f(p1[r]);
;                 if (diag) { if (kv > qloc) e0 = 0.f; if (kv + 32 > qloc) e1 = 0.f; }
;                 p0[r] = e0; p1[r] = e1; lsum += e0 + e1; }
; #pragma unroll
;             for (int s4 = 0; s4 < 4; ++s4) { const bf16x8 pf = (s4 < 2) ? pack8(p0, s4 & 1) : pack8(p1, s4 & 1);
;                 o0 = MFMA32(tr_frag(Vb, 96, 16 * s4 + 4 * h2, 16 * s4 + 8 + 4 * h2, 0, lane), pf, o0); o1 = MFMA32(tr_frag(Vb, 96, 16 * s4 + 4 * h2, 16 * s4 + 8 + 4 * h2, 32, lane), pf, o1); }
	v_mfma_f32_32x32x16_bf16 v[18:33], v[50:53], v[54:57], v[18:33]
	v_add_u32_e32 v50, 26, v119
	v_cmp_gt_i32_e32 vcc, v50, v178
	v_add_u32_e32 v50, 27, v119
	v_exp_f32_e32 v67, v81
	s_and_b64 s[4:5], s[16:17], vcc
	v_cmp_gt_i32_e32 vcc, v50, v178
	ds_read_b64_tr_b16 v[50:51], v79 offset:29696
	ds_read_b64_tr_b16 v[52:53], v79 offset:31232
	s_waitcnt lgkmcnt(2)
	v_mfma_f32_32x32x16_bf16 v[34:49], v[58:61], v[54:57], v[34:49]
	ds_read_b64_tr_b16 v[60:61], v79 offset:31296
	ds_read_b64_tr_b16 v[58:59], v79 offset:29760
	v_add_f32_e32 v129, v66, v121
	v_cndmask_b32_e64 v66, v80, 0, s[4:5]
	s_and_b64 s[4:5], s[16:17], vcc
	v_cndmask_b32_e64 v67, v67, 0, s[4:5]
	v_cvt_pk_bf16_f32 v54, v74, v75
	v_cvt_pk_bf16_f32 v55, v76, v77
	v_cvt_pk_bf16_f32 v56, v62, v182
	v_cvt_pk_bf16_f32 v57, v66, v67
	v_add_f32_e32 v1, v1, v129
	v_add_f32_e32 v139, v68, v137
	s_waitcnt lgkmcnt(2)
	v_mfma_f32_32x32x16_bf16 v[18:33], v[50:53], v[54:57], v[18:33]
	v_exp_f32_e32 v50, v63
	v_add_u32_e32 v51, 57, v119
	v_cmp_gt_i32_e32 vcc, v51, v178
	s_and_b64 s[4:5], s[16:17], vcc
	v_cndmask_b32_e64 v63, v50, 0, s[4:5]
	ds_read_b64_tr_b16 v[50:51], v79 offset:32768
	ds_read_b64_tr_b16 v[52:53], v79 offset:34304
	v_add_f32_e32 v1, v135, v1
	s_waitcnt lgkmcnt(2)
	v_mfma_f32_32x32x16_bf16 v[34:49], v[58:61], v[54:57], v[34:49]
	ds_read_b64_tr_b16 v[60:61], v79 offset:34368
	ds_read_b64_tr_b16 v[58:59], v79 offset:32832
	v_cvt_pk_bf16_f32 v54, v121, v133
	v_cvt_pk_bf16_f32 v55, v137, v157
	v_cvt_pk_bf16_f32 v56, v161, v169
	v_cvt_pk_bf16_f32 v57, v171, v73
	v_add_f32_e32 v159, v69, v157
	v_add_f32_e32 v1, v139, v1
	s_waitcnt lgkmcnt(2)
	v_mfma_f32_32x32x16_bf16 v[18:33], v[50:53], v[54:57], v[18:33]
	v_add_u32_e32 v50, 58, v119
	v_cmp_gt_i32_e32 vcc, v50, v178
	v_add_u32_e32 v50, 59, v119
	v_add_f32_e32 v168, v70, v161
	s_and_b64 s[4:5], s[16:17], vcc
	v_cmp_gt_i32_e32 vcc, v50, v178
	ds_read_b64_tr_b16 v[50:51], v79 offset:35840
	ds_read_b64_tr_b16 v[52:53], v79 offset:37376
	s_waitcnt lgkmcnt(2)
	v_mfma_f32_32x32x16_bf16 v[34:49], v[58:61], v[54:57], v[34:49]
	ds_read_b64_tr_b16 v[60:61], v79 offset:37440
	ds_read_b64_tr_b16 v[58:59], v79 offset:35904
	v_add_f32_e32 v1, v159, v1
	v_add_f32_e32 v170, v71, v169
	v_add_f32_e32 v1, v168, v1
	v_add_f32_e32 v172, v72, v171
	v_cndmask_b32_e64 v64, v64, 0, s[4:5]
	s_and_b64 s[4:5], s[16:17], vcc
	v_add_f32_e32 v1, v170, v1
	v_cndmask_b32_e64 v65, v65, 0, s[4:5]
	v_add_f32_e32 v1, v172, v1
	v_add_f32_e32 v175, v74, v174
	v_cvt_pk_bf16_f32 v54, v174, v179
	v_cvt_pk_bf16_f32 v55, v180, v181
	v_cvt_pk_bf16_f32 v56, v78, v63
	v_cvt_pk_bf16_f32 v57, v64, v65
	v_add_f32_e32 v1, v173, v1
	v_add_f32_e32 v1, v175, v1
	s_waitcnt lgkmcnt(2)
	v_mfma_f32_32x32x16_bf16 v[18:33], v[50:53], v[54:57], v[18:33]
	v_add_f32_e32 v50, v75, v179
	v_add_f32_e32 v51, v76, v180
	v_add_f32_e32 v1, v50, v1
	v_add_f32_e32 v52, v77, v181
	v_add_f32_e32 v1, v51, v1
	v_add_f32_e32 v53, v62, v78
	v_add_f32_e32 v1, v52, v1
	s_waitcnt lgkmcnt(0)
	v_mfma_f32_32x32x16_bf16 v[34:49], v[58:61], v[54:57], v[34:49]
	v_add_f32_e32 v62, v182, v63
	v_add_f32_e32 v1, v53, v1
	v_add_f32_e32 v63, v66, v64
	v_add_f32_e32 v1, v62, v1
	v_add_f32_e32 v64, v67, v65
	v_add_f32_e32 v1, v63, v1
	v_add_f32_e32 v1, v64, v1
	s_branch .LBB0_857
; #define MFMA32(a, b, c) __builtin_amdgcn_mfma_f32_32x32x16_bf16((a), (b), (c), 0, 0, 0)
; DI int crow(int r, int hi) { return (r & 3) + 8 * (r >> 2) + 4 * hi; }
; DI void attn_prompt_unit(const Args& a, LAS unsigned char* lds, int b, int h, int qb, float cB, int tid, int lane, int wave) {
;     ...
;             for (int r = 0; r < 16; ++r) { const int kv = t * 64 + crow(r, h2);
;                 float e0 = __builtin_amdgcn_exp2f(p0[r]), e1 = __builtin_amdgcn_exp2f(p1[r]);
;                 if (diag) { if (kv > qloc) e0 = 0.f; if (kv + 32 > qloc) e1 = 0.f; }
;                 p0[r] = e0; p1[r] = e1; lsum += e0 + e1; }
; #pragma unroll
;             for (int s4 = 0; s4 < 4; ++s4) { const bf16x8 pf = (s4 < 2) ? pack8(p0, s4 & 1) : pack8(p1, s4 & 1);
;                 o0 = MFMA32(tr_frag(Vb, 96, 16 * s4 + 4 * h2, 16 * s4 + 8 + 4 * h2, 0, lane), pf, o0); o1 = MFMA32(tr_frag(Vb, 96, 16 * s4 + 4 * h2, 16 * s4 + 8 + 4 * h2, 32, lane), pf, o1); }
.Lpa_fast_1:
	s_nop 10
	v_exp_f32_e32 v121, v50
	v_exp_f32_e32 v133, v51
	v_exp_f32_e32 v137, v52
	v_exp_f32_e32 v64, v64
	v_exp_f32_e32 v65, v65
	v_exp_f32_e32 v66, v66
	v_exp_f32_e32 v67, v67
	v_exp_f32_e32 v68, v68
	v_exp_f32_e32 v69, v69
	v_exp_f32_e32 v157, v53
	v_exp_f32_e32 v70, v70
	v_exp_f32_e32 v161, v54
	v_exp_f32_e32 v71, v71
	v_exp_f32_e32 v169, v55
	v_exp_f32_e32 v72, v72
	v_exp_f32_e32 v171, v56
	v_exp_f32_e32 v51, v73
	v_exp_f32_e32 v73, v57
	v_mov_b32_e32 v57, v51
	v_exp_f32_e32 v74, v74
	v_exp_f32_e32 v174, v58
	v_exp_f32_e32 v75, v75
	v_exp_f32_e32 v179, v59
	v_exp_f32_e32 v76, v76
	v_exp_f32_e32 v180, v60
	v_exp_f32_e32 v77, v77
	v_exp_f32_e32 v181, v61
	v_add_u32_e32 v50, 24, v119
	v_exp_f32_e32 v51, v78
	v_exp_f32_e32 v78, v62
	v_cmp_gt_i32_e32 vcc, v50, v178
	s_and_b64 s[30:31], s[16:17], vcc
	v_exp_f32_e32 v182, v79
	v_add_u32_e32 v79, s29, v229
	v_mov_b32_e32 v62, v51
	ds_read_b64_tr_b16 v[50:51], v79 offset:26624
	ds_read_b64_tr_b16 v[52:53], v79 offset:28160
	ds_read_b64_tr_b16 v[60:61], v79 offset:28224
	ds_read_b64_tr_b16 v[58:59], v79 offset:26688
	v_add_f32_e32 v173, v57, v73
	v_cvt_pk_bf16_f32 v54, v66, v67
	v_cvt_pk_bf16_f32 v55, v68, v69
	v_cvt_pk_bf16_f32 v56, v70, v71
	v_cvt_pk_bf16_f32 v57, v72, v57
	v_exp_f32_e32 v80, v80
	v_add_f32_e32 v135, v67, v133
	s_waitcnt lgkmcnt(2)
	v_mfma_f32_32x32x16_bf16 v[18:33], v[50:53], v[54:57], v[18:33]
	v_exp_f32_e32 v67, v81
	ds_read_b64_tr_b16 v[50:51], v79 offset:29696
	ds_read_b64_tr_b16 v[52:53], v79 offset:31232
	s_waitcnt lgkmcnt(2)
	v_mfma_f32_32x32x16_bf16 v[34:49], v[58:61], v[54:57], v[34:49]
	ds_read_b64_tr_b16 v[60:61], v79 offset:31296
	ds_read_b64_tr_b16 v[58:59], v79 offset:29760
	v_add_f32_e32 v129, v66, v121
	v_mov_b32_e32 v66, v80
	v_cvt_pk_bf16_f32 v54, v74, v75
	v_cvt_pk_bf16_f32 v55, v76, v77
	v_cvt_pk_bf16_f32 v56, v62, v182
	v_cvt_pk_bf16_f32 v57, v66, v67
	v_add_f32_e32 v1, v1, v129
	v_add_f32_e32 v139, v68, v137
	s_waitcnt lgkmcnt(2)
	v_mfma_f32_32x32x16_bf16 v[18:33], v[50:53], v[54:57], v[18:33]
	v_exp_f32_e32 v63, v63
	ds_read_b64_tr_b16 v[50:51], v79 offset:32768
	ds_read_b64_tr_b16 v[52:53], v79 offset:34304
	v_add_f32_e32 v1, v135, v1
	s_waitcnt lgkmcnt(2)
	v_mfma_f32_32x32x16_bf16 v[34:49], v[58:61], v[54:57], v[34:49]
	ds_read_b64_tr_b16 v[60:61], v79 offset:34368
	ds_read_b64_tr_b16 v[58:59], v79 offset:32832
	v_cvt_pk_bf16_f32 v54, v121, v133
	v_cvt_pk_bf16_f32 v55, v137, v157
	v_cvt_pk_bf16_f32 v56, v161, v169
	v_cvt_pk_bf16_f32 v57, v171, v73
	v_add_f32_e32 v159, v69, v157
	v_add_f32_e32 v1, v139, v1
	s_waitcnt lgkmcnt(2)
	v_mfma_f32_32x32x16_bf16 v[18:33], v[50:53], v[54:57], v[18:33]
	v_add_f32_e32 v168, v70, v161
	ds_read_b64_tr_b16 v[50:51], v79 offset:35840
	ds_read_b64_tr_b16 v[52:53], v79 offset:37376
	s_waitcnt lgkmcnt(2)
	v_mfma_f32_32x32x16_bf16 v[34:49], v[58:61], v[54:57], v[34:49]
	ds_read_b64_tr_b16 v[60:61], v79 offset:37440
	ds_read_b64_tr_b16 v[58:59], v79 offset:35904
	v_add_f32_e32 v1, v159, v1
	v_add_f32_e32 v170, v71, v169
	v_add_f32_e32 v1, v168, v1
	v_add_f32_e32 v172, v72, v171
	v_add_f32_e32 v1, v170, v1
	v_add_f32_e32 v1, v172, v1
	v_add_f32_e32 v175, v74, v174
	v_cvt_pk_bf16_f32 v54, v174, v179
	v_cvt_pk_bf16_f32 v55, v180, v181
	v_cvt_pk_bf16_f32 v56, v78, v63
	v_cvt_pk_bf16_f32 v57, v64, v65
	v_add_f32_e32 v1, v173, v1
	v_add_f32_e32 v1, v175, v1
	s_waitcnt lgkmcnt(2)
	v_mfma_f32_32x32x16_bf16 v[18:33], v[50:53], v[54:57], v[18:33]
	v_add_f32_e32 v50, v75, v179
	v_add_f32_e32 v51, v76, v180
	v_add_f32_e32 v1, v50, v1
	v_add_f32_e32 v52, v77, v181
	v_add_f32_e32 v1, v51, v1
	v_add_f32_e32 v53, v62, v78
	v_add_f32_e32 v1, v52, v1
	s_waitcnt lgkmcnt(0)
	v_mfma_f32_32x32x16_bf16 v[34:49], v[58:61], v[54:57], v[34:49]
	v_add_f32_e32 v62, v182, v63
	v_add_f32_e32 v1, v53, v1
	v_add_f32_e32 v63, v66, v64
	v_add_f32_e32 v1, v62, v1
	v_add_f32_e32 v64, v67, v65
	v_add_f32_e32 v1, v63, v1
	v_add_f32_e32 v1, v64, v1

; #define LAS __attribute__((address_space(3)))
; DI void attn_sample_phase(const Args& a, LAS unsigned char* lds, int vcu, int G, int tid, int lane, int wave) {
;     ...
;             { const LAS unsigned char* c8b = C8 + (j & 1) * 8704; const LAS float* spe = SSPE + (j & 1) * 32;
; #pragma unroll
;                 for (int kb = 0; kb < 2; ++kb) { f32x4 acc[4] = {};
; #pragma unroll
;                     for (int ks = 0; ks < 2; ++ks) { const LAS unsigned char* ap = c8b + (kb * 16 + r16) * 272 + 128 * ks + 32 * q4;
;                         const u32x4 x0 = *(const LAS u32x4*)ap, x1 = *(const LAS u32x4*)(ap + 16);
;                         const v8i_t af = {(int)x0.x, (int)x0.y, (int)x0.z, (int)x0.w, (int)x1.x, (int)x1.y, (int)x1.z, (int)x1.w};
; #pragma unroll
;                         for (int nb = 0; nb < 4; ++nb) acc[nb] = __builtin_amdgcn_mfma_scale_f32_16x16x128_f8f6f4(af, wf8[nb][ks], acc[nb], 0, 0, 0, 0x7F7F7F7F, 0, 0x7F7F7F7F); }
;                     f32x4 sq = (acc[0] * acc[0] + acc[1] * acc[1] + acc[2] * acc[2] + acc[3] * acc[3]) * (1.f / 256.f);
;                     sq.x = row16_sum(sq.x); sq.y = row16_sum(sq.y); sq.z = row16_sum(sq.z); sq.w = row16_sum(sq.w);
;                     if (r16 == 0) { const f32x4 pe = *(const LAS f32x4*)(spe + kb * 16 + 4 * q4); f32x4 r;
;                         r.x = __builtin_amdgcn_rsqf((sq.x + pe.x) * (1.f / 96.f) + EPS); r.y = __builtin_amdgcn_rsqf((sq.y + pe.y) * (1.f / 96.f) + EPS);
;                         r.z = __builtin_amdgcn_rsqf((sq.z + pe.z) * (1.f / 96.f) + EPS); r.w = __builtin_amdgcn_rsqf((sq.w + pe.w) * (1.f / 96.f) + EPS);
;                         *(LAS f32x4*)(RI + wave * 32 + kb * 16 + 4 * q4) = r; } } }
.LBB0_904:
	s_add_i32 s26, s25, -2
	s_and_b32 s8, s26, 1
	s_mul_i32 s9, s8, 0x2200
	v_add_u32_e32 v2, s9, v202
	s_lshl_b32 s8, s8, 7
	v_add_u32_e32 v254, s8, v194
	ds_read_b128 v[212:215], v2 offset:56832
	ds_read_b128 v[216:219], v2 offset:56848
	ds_read_b128 v[236:239], v2 offset:56960
	ds_read_b128 v[240:243], v2 offset:56976
	ds_read_b128 v[246:249], v2 offset:61184
	ds_read_b128 v[250:253], v2 offset:61200
	ds_read_b128 v[232:235], v254
	s_waitcnt lgkmcnt(5)
	v_mfma_scale_f32_16x16x128_f8f6f4 v[220:223], v[212:219], v[36:43], 0, v208, v208 op_sel_hi:[0,0,0]
	s_waitcnt lgkmcnt(3)
	v_mfma_scale_f32_16x16x128_f8f6f4 v[220:223], v[236:243], v[44:51], v[220:223], v208, v208 op_sel_hi:[0,0,0]
	v_mfma_scale_f32_16x16x128_f8f6f4 v[136:139], v[212:219], v[20:27], 0, v208, v208 op_sel_hi:[0,0,0]
	v_mfma_scale_f32_16x16x128_f8f6f4 v[136:139], v[236:243], v[28:35], v[136:139], v208, v208 op_sel_hi:[0,0,0]
	v_mfma_scale_f32_16x16x128_f8f6f4 v[224:227], v[212:219], v[52:59], 0, v208, v208 op_sel_hi:[0,0,0]
	v_mfma_scale_f32_16x16x128_f8f6f4 v[224:227], v[236:243], v[60:67], v[224:227], v208, v208 op_sel_hi:[0,0,0]
	v_mfma_scale_f32_16x16x128_f8f6f4 v[228:231], v[212:219], v[68:75], 0, v208, v208 op_sel_hi:[0,0,0]
	v_mfma_scale_f32_16x16x128_f8f6f4 v[228:231], v[236:243], v[76:83], v[228:231], v208, v208 op_sel_hi:[0,0,0]
	ds_read_b128 v[212:215], v2 offset:61312
	ds_read_b128 v[216:219], v2 offset:61328
	s_nop 3
	v_mul_f32_e32 v236, v220, v220
	v_mul_f32_e32 v237, v221, v221
	v_mul_f32_e32 v238, v222, v222
	v_mul_f32_e32 v239, v223, v223
	v_fmac_f32_e32 v236, v136, v136
	v_fmac_f32_e32 v237, v137, v137
	v_fmac_f32_e32 v238, v138, v138
	v_fmac_f32_e32 v239, v139, v139
	v_fmac_f32_e32 v236, v224, v224
	v_fmac_f32_e32 v237, v225, v225
	v_fmac_f32_e32 v238, v226, v226
	v_fmac_f32_e32 v239, v227, v227
	v_fmac_f32_e32 v236, v228, v228
	v_fmac_f32_e32 v237, v229, v229
	v_fmac_f32_e32 v238, v230, v230
	v_fmac_f32_e32 v239, v231, v231
	v_pk_mul_f32 v[236:237], v[236:237], s[14:15] op_sel_hi:[1,0]
	v_pk_mul_f32 v[238:239], v[238:239], s[14:15] op_sel_hi:[1,0]
	s_waitcnt lgkmcnt(0)
; #define LAS __attribute__((address_space(3)))
; DI void attn_sample_phase(const Args& a, LAS unsigned char* lds, int vcu, int G, int tid, int lane, int wave) {
;     ...
;             { const LAS unsigned char* c8b = C8 + (j & 1) * 8704; const LAS float* spe = SSPE + (j & 1) * 32;
; #pragma unroll
;                 for (int kb = 0; kb < 2; ++kb) { f32x4 acc[4] = {};
; #pragma unroll
;                     for (int ks = 0; ks < 2; ++ks) { const LAS unsigned char* ap = c8b + (kb * 16 + r16) * 272 + 128 * ks + 32 * q4;
;                         const u32x4 x0 = *(const LAS u32x4*)ap, x1 = *(const LAS u32x4*)(ap + 16);
;                         const v8i_t af = {(int)x0.x, (int)x0.y, (int)x0.z, (int)x0.w, (int)x1.x, (int)x1.y, (int)x1.z, (int)x1.w};
; #pragma unroll
;                         for (int nb = 0; nb < 4; ++nb) acc[nb] = __builtin_amdgcn_mfma_scale_f32_16x16x128_f8f6f4(af, wf8[nb][ks], acc[nb], 0, 0, 0, 0x7F7F7F7F, 0, 0x7F7F7F7F); }
;                     f32x4 sq = (acc[0] * acc[0] + acc[1] * acc[1] + acc[2] * acc[2] + acc[3] * acc[3]) * (1.f / 256.f);
;                     sq.x = row16_sum(sq.x); sq.y = row16_sum(sq.y); sq.z = row16_sum(sq.z); sq.w = row16_sum(sq.w);
;                     if (r16 == 0) { const f32x4 pe = *(const LAS f32x4*)(spe + kb * 16 + 4 * q4); f32x4 r;
;                         r.x = __builtin_amdgcn_rsqf((sq.x + pe.x) * (1.f / 96.f) + EPS); r.y = __builtin_amdgcn_rsqf((sq.y + pe.y) * (1.f / 96.f) + EPS);
;                         r.z = __builtin_amdgcn_rsqf((sq.z + pe.z) * (1.f / 96.f) + EPS); r.w = __builtin_amdgcn_rsqf((sq.w + pe.w) * (1.f / 96.f) + EPS);
;                         *(LAS f32x4*)(RI + wave * 32 + kb * 16 + 4 * q4) = r; } } }
	v_mfma_scale_f32_16x16x128_f8f6f4 v[220:223], v[246:253], v[36:43], 0, v208, v208 op_sel_hi:[0,0,0]
	v_add_f32_dpp v236, v236, v236 row_ror:8 row_mask:0xf bank_mask:0xf bound_ctrl:1
	v_add_f32_dpp v237, v237, v237 row_ror:8 row_mask:0xf bank_mask:0xf bound_ctrl:1
	v_add_f32_dpp v238, v238, v238 row_ror:8 row_mask:0xf bank_mask:0xf bound_ctrl:1
	v_add_f32_dpp v239, v239, v239 row_ror:8 row_mask:0xf bank_mask:0xf bound_ctrl:1
	v_mfma_scale_f32_16x16x128_f8f6f4 v[220:223], v[212:219], v[44:51], v[220:223], v208, v208 op_sel_hi:[0,0,0]
	v_add_f32_dpp v236, v236, v236 row_ror:4 row_mask:0xf bank_mask:0xf bound_ctrl:1
	v_add_f32_dpp v237, v237, v237 row_ror:4 row_mask:0xf bank_mask:0xf bound_ctrl:1
	v_add_f32_dpp v238, v238, v238 row_ror:4 row_mask:0xf bank_mask:0xf bound_ctrl:1
	v_add_f32_dpp v239, v239, v239 row_ror:4 row_mask:0xf bank_mask:0xf bound_ctrl:1
	v_mfma_scale_f32_16x16x128_f8f6f4 v[224:227], v[246:253], v[20:27], 0, v208, v208 op_sel_hi:[0,0,0]
	v_add_f32_dpp v236, v236, v236 quad_perm:[2,3,0,1] row_mask:0xf bank_mask:0xf bound_ctrl:1
	v_add_f32_dpp v237, v237, v237 quad_perm:[2,3,0,1] row_mask:0xf bank_mask:0xf bound_ctrl:1
	v_add_f32_dpp v238, v238, v238 quad_perm:[2,3,0,1] row_mask:0xf bank_mask:0xf bound_ctrl:1
	v_add_f32_dpp v239, v239, v239 quad_perm:[2,3,0,1] row_mask:0xf bank_mask:0xf bound_ctrl:1
	v_mfma_scale_f32_16x16x128_f8f6f4 v[224:227], v[212:219], v[28:35], v[224:227], v208, v208 op_sel_hi:[0,0,0]
	v_add_f32_dpp v236, v236, v236 quad_perm:[1,0,3,2] row_mask:0xf bank_mask:0xf bound_ctrl:1
	v_add_f32_dpp v237, v237, v237 quad_perm:[1,0,3,2] row_mask:0xf bank_mask:0xf bound_ctrl:1
	v_add_f32_dpp v238, v238, v238 quad_perm:[1,0,3,2] row_mask:0xf bank_mask:0xf bound_ctrl:1
	v_add_f32_dpp v239, v239, v239 quad_perm:[1,0,3,2] row_mask:0xf bank_mask:0xf bound_ctrl:1
	v_mfma_scale_f32_16x16x128_f8f6f4 v[228:231], v[246:253], v[52:59], 0, v208, v208 op_sel_hi:[0,0,0]
	v_add_f32_e32 v236, v236, v232
	v_add_f32_e32 v237, v237, v233
	v_add_f32_e32 v238, v238, v234
	v_add_f32_e32 v239, v239, v235
	v_mfma_scale_f32_16x16x128_f8f6f4 v[228:231], v[212:219], v[60:67], v[228:231], v208, v208 op_sel_hi:[0,0,0]
	v_fmamk_f32 v236, v236, 0x3c2aaaab, v209
	v_fmamk_f32 v237, v237, 0x3c2aaaab, v209
	v_fmamk_f32 v238, v238, 0x3c2aaaab, v209
	v_fmamk_f32 v239, v239, 0x3c2aaaab, v209
	v_mfma_scale_f32_16x16x128_f8f6f4 v[136:139], v[246:253], v[68:75], 0, v208, v208 op_sel_hi:[0,0,0]
	v_rsq_f32_e32 v236, v236
	v_rsq_f32_e32 v237, v237
	v_rsq_f32_e32 v238, v238
	v_rsq_f32_e32 v239, v239
	v_mfma_scale_f32_16x16x128_f8f6f4 v[136:139], v[212:219], v[76:83], v[136:139], v208, v208 op_sel_hi:[0,0,0]
	s_and_saveexec_b64 s[18:19], s[6:7]
	ds_write_b128 v195, v[236:239]
	s_or_b64 exec, exec, s[18:19]
	ds_read_b128 v[232:235], v254 offset:64
	v_mul_f32_e32 v240, v220, v220
	v_mul_f32_e32 v241, v221, v221
	v_mul_f32_e32 v242, v222, v222
	v_mul_f32_e32 v243, v223, v223
	v_fmac_f32_e32 v240, v224, v224
	v_fmac_f32_e32 v241, v225, v225
	v_fmac_f32_e32 v242, v226, v226
	v_fmac_f32_e32 v243, v227, v227
	v_fmac_f32_e32 v240, v228, v228
	v_fmac_f32_e32 v241, v229, v229
	v_fmac_f32_e32 v242, v230, v230
	v_fmac_f32_e32 v243, v231, v231
	v_fmac_f32_e32 v240, v136, v136
	v_fmac_f32_e32 v241, v137, v137
	v_fmac_f32_e32 v242, v138, v138
	v_fmac_f32_e32 v243, v139, v139
	v_pk_mul_f32 v[240:241], v[240:241], s[14:15] op_sel_hi:[1,0]
	v_pk_mul_f32 v[242:243], v[242:243], s[14:15] op_sel_hi:[1,0]
	s_waitcnt lgkmcnt(0)
	s_nop 0
	v_add_f32_dpp v240, v240, v240 row_ror:8 row_mask:0xf bank_mask:0xf bound_ctrl:1
	v_add_f32_dpp v241, v241, v241 row_ror:8 row_mask:0xf bank_mask:0xf bound_ctrl:1
	v_add_f32_dpp v242, v242, v242 row_ror:8 row_mask:0xf bank_mask:0xf bound_ctrl:1
	v_add_f32_dpp v243, v243, v243 row_ror:8 row_mask:0xf bank_mask:0xf bound_ctrl:1
	v_add_f32_dpp v240, v240, v240 row_ror:4 row_mask:0xf bank_mask:0xf bound_ctrl:1
	v_add_f32_dpp v241, v241, v241 row_ror:4 row_mask:0xf bank_mask:0xf bound_ctrl:1
	v_add_f32_dpp v242, v242, v242 row_ror:4 row_mask:0xf bank_mask:0xf bound_ctrl:1
	v_add_f32_dpp v243, v243, v243 row_ror:4 row_mask:0xf bank_mask:0xf bound_ctrl:1
	v_add_f32_dpp v240, v240, v240 quad_perm:[2,3,0,1] row_mask:0xf bank_mask:0xf bound_ctrl:1
	v_add_f32_dpp v241, v241, v241 quad_perm:[2,3,0,1] row_mask:0xf bank_mask:0xf bound_ctrl:1
	v_add_f32_dpp v242, v242, v242 quad_perm:[2,3,0,1] row_mask:0xf bank_mask:0xf bound_ctrl:1
	v_add_f32_dpp v243, v243, v243 quad_perm:[2,3,0,1] row_mask:0xf bank_mask:0xf bound_ctrl:1
	v_add_f32_dpp v240, v240, v240 quad_perm:[1,0,3,2] row_mask:0xf bank_mask:0xf bound_ctrl:1
	v_add_f32_dpp v241, v241, v241 quad_perm:[1,0,3,2] row_mask:0xf bank_mask:0xf bound_ctrl:1
	v_add_f32_dpp v242, v242, v242 quad_perm:[1,0,3,2] row_mask:0xf bank_mask:0xf bound_ctrl:1
	v_add_f32_dpp v243, v243, v243 quad_perm:[1,0,3,2] row_mask:0xf bank_mask:0xf bound_ctrl:1
	v_add_f32_e32 v240, v240, v232
	v_add_f32_e32 v241, v241, v233
	v_add_f32_e32 v242, v242, v234
	v_add_f32_e32 v243, v243, v235
	v_fmamk_f32 v240, v240, 0x3c2aaaab, v209
	v_fmamk_f32 v241, v241, 0x3c2aaaab, v209
	v_fmamk_f32 v242, v242, 0x3c2aaaab, v209
	v_fmamk_f32 v243, v243, 0x3c2aaaab, v209
	v_rsq_f32_e32 v240, v240
	v_rsq_f32_e32 v241, v241
	v_rsq_f32_e32 v242, v242
	v_rsq_f32_e32 v243, v243
	s_and_saveexec_b64 s[18:19], s[6:7]
	ds_write_b128 v195, v[240:243] offset:64
	s_or_b64 exec, exec, s[18:19]

; DI unsigned pk2(float lo, float hi) { f32x2 v = {lo, hi}; bf16x2_t b = __builtin_convertvector(v, bf16x2_t); return __builtin_bit_cast(unsigned, b); }
; DI float sigmoidf_(float x) { return 1.f / (1.f + __expf(-x)); }
;     DI void operator()(const f32x4 (&acc)[2][2][4][2], const Unit& u, int wr, int wc, int fr, int fq) const {
;     ...
;             for (int m = 0; m < 4; ++m) { const int row = row0 + ai * HALF + m * 16;
;                 const float* bp = (row < MP) ? base0 + (size_t)row * DM : base1 + (size_t)(row - MP) * DM;
;                 float r = 1.f; if (MODE == 1) r = __builtin_amdgcn_rsqf(ssin[row] * (1.f / DM) + EPS);
;                 float s = 0.f;
; #pragma unroll
;                 for (int bj = 0; bj < 2; ++bj)
; #pragma unroll
;                     for (int n = 0; n < 2; ++n) { const int col = col0 + bj * HALF + n * 16;
;                         f32x4 v = acc[ai][bj][m][n];
;                         if (MODE == 1) { const u32x2 pw = *(const u32x2*)(PP + (size_t)row * DM + col);
;                             v[0] = sigmoidf_(v[0] * r) * bflo(pw.x); v[1] = sigmoidf_(v[1] * r) * bfhi(pw.x); v[2] = sigmoidf_(v[2] * r) * bflo(pw.y); v[3] = sigmoidf_(v[3] * r) * bfhi(pw.y); }
;                         f32x4 h;
;                         if (baseb) { const u32x2 bw = *(const u32x2*)(baseb + (size_t)row * DM + col); h = (f32x4){bflo(bw.x), bfhi(bw.x), bflo(bw.y), bfhi(bw.y)} + v; }
;                         else h = *(const f32x4*)(bp + col) + v;
;                         if (H) *(f32x4*)(H + (size_t)row * DM + col) = h;
;                         if (XB) { u32x2 w; w.x = pk2(h[0], h[1]); w.y = pk2(h[2], h[3]); *(u32x2*)(XB + (size_t)row * DM + col) = w; }
;                         s += (h[0] * h[0] + h[1] * h[1]) + (h[2] * h[2] + h[3] * h[3]); }
;                 if (ssout) { s += __shfl_xor(s, 16); s += __shfl_xor(s, 32); if (fq == 0) atomicAdd(ssout + row, s); } }
.LBB0_1423:
	v_lshl_add_u32 v148, s4, 8, v1
	v_ashrrev_i32_e32 v147, 31, v148
	v_cmp_gt_i32_e32 vcc, s52, v148
	v_lshl_or_b32 v146, s6, 8, v143
	s_nop 0
	v_cndmask_b32_e32 v149, 0, v147, vcc
	v_lshl_add_u64 v[150:151], v[148:149], 2, s[16:17]
	global_load_dword v173, v[150:151], off
	v_lshlrev_b64 v[150:151], 11, v[148:149]
	v_ashrrev_i32_e32 v147, 31, v146
	v_lshl_add_u64 v[152:153], s[18:19], 0, v[150:151]
	v_lshlrev_b64 v[146:147], 1, v[146:147]
	v_lshl_add_u64 v[154:155], v[152:153], 0, v[146:147]
	v_lshl_add_u64 v[152:153], s[92:93], 0, v[150:151]
	v_lshl_add_u64 v[152:153], v[152:153], 0, v[146:147]
	global_load_dwordx2 v[158:159], v[154:155], off
	global_load_dwordx2 v[164:165], v[152:153], off
	global_load_dwordx2 v[156:157], v[154:155], off offset:32
	global_load_dwordx2 v[160:161], v[154:155], off offset:256
	global_load_dwordx2 v[162:163], v[152:153], off offset:32
	global_load_dwordx2 v[166:167], v[152:153], off offset:256
	s_nop 0
	global_load_dwordx2 v[154:155], v[154:155], off offset:288
	v_lshl_add_u64 v[150:151], s[14:15], 0, v[150:151]
	v_lshl_add_u64 v[150:151], v[150:151], 0, v[146:147]
	s_waitcnt vmcnt(0)
	v_fmamk_f32 v173, v173, 0x3a800000, v171
	v_rsq_f32_e32 v173, v173
	v_lshlrev_b32_e32 v174, 16, v158
	v_mul_f32_e32 v126, v126, v173
	v_mul_f32_e32 v127, v127, v173
	v_mul_f32_e32 v122, v122, v173
	v_mul_f32_e32 v123, v123, v173
	v_mul_f32_e32 v126, 0xbfb8aa3b, v126
	v_mul_f32_e32 v127, 0xbfb8aa3b, v127
	v_mul_f32_e32 v178, 0xbfb8aa3b, v122
	v_mul_f32_e32 v179, 0xbfb8aa3b, v123
	v_exp_f32_e32 v122, v126
	v_exp_f32_e32 v123, v127
	v_mul_f32_e32 v128, v128, v173
	v_mul_f32_e32 v129, v129, v173
	v_mul_f32_e32 v128, 0xbfb8aa3b, v128
	v_pk_add_f32 v[122:123], v[122:123], 1.0 op_sel_hi:[1,0]
	v_mul_f32_e32 v129, 0xbfb8aa3b, v129
	v_exp_f32_e32 v126, v128
	v_exp_f32_e32 v128, v178
	v_exp_f32_e32 v127, v129
	s_nop 0
	v_pk_add_f32 v[126:127], v[126:127], 1.0 op_sel_hi:[1,0]
	v_exp_f32_e32 v129, v179
	v_rcp_f32_e32 v123, v123
	v_and_b32_e32 v175, 0xffff0000, v158
	v_lshlrev_b32_e32 v176, 16, v164
	v_and_b32_e32 v177, 0xffff0000, v164
	v_rcp_f32_e32 v122, v122
	s_nop 0
	v_pk_fma_f32 v[122:123], v[122:123], v[174:175], v[176:177]
	v_mul_f32_e32 v176, v123, v123
	v_cvt_pk_bf16_f32 v174, v122, v123
	v_fmac_f32_e32 v176, v122, v122
	v_pk_add_f32 v[122:123], v[128:129], 1.0 op_sel_hi:[1,0]
	v_rcp_f32_e32 v127, v127
	v_lshlrev_b32_e32 v158, 16, v159
	v_and_b32_e32 v159, 0xffff0000, v159
	v_lshlrev_b32_e32 v164, 16, v165
	v_and_b32_e32 v165, 0xffff0000, v165
	v_rcp_f32_e32 v126, v126
	s_nop 0
	v_pk_fma_f32 v[126:127], v[126:127], v[158:159], v[164:165]
	v_mul_f32_e32 v124, v124, v173
	v_cvt_pk_bf16_f32 v175, v126, v127
	v_mul_f32_e32 v127, v127, v127
	v_fmac_f32_e32 v127, v126, v126
	v_add_f32_e32 v164, v176, v127
	v_mul_f32_e32 v125, v125, v173
	v_rcp_f32_e32 v127, v123
	v_mul_f32_e32 v124, 0xbfb8aa3b, v124
	v_mul_f32_e32 v125, 0xbfb8aa3b, v125
	v_exp_f32_e32 v124, v124
	v_exp_f32_e32 v125, v125
	s_nop 0
	v_pk_add_f32 v[124:125], v[124:125], 1.0 op_sel_hi:[1,0]
	v_rcp_f32_e32 v126, v122
	v_lshlrev_b32_e32 v128, 16, v156
	v_and_b32_e32 v129, 0xffff0000, v156
	v_rcp_f32_e32 v123, v125
	v_mul_f32_e32 v118, v118, v173
	v_mul_f32_e32 v119, v119, v173
	v_mul_f32_e32 v118, 0xbfb8aa3b, v118
	v_mul_f32_e32 v119, 0xbfb8aa3b, v119
	v_exp_f32_e32 v118, v118
	v_exp_f32_e32 v119, v119
	v_rcp_f32_e32 v122, v124
	v_lshlrev_b32_e32 v124, 16, v157
	v_and_b32_e32 v125, 0xffff0000, v157
	v_lshlrev_b32_e32 v156, 16, v162
	v_and_b32_e32 v157, 0xffff0000, v162
	v_lshlrev_b32_e32 v158, 16, v163
	v_and_b32_e32 v159, 0xffff0000, v163
	v_pk_fma_f32 v[126:127], v[126:127], v[128:129], v[156:157]
	v_pk_add_f32 v[118:119], v[118:119], 1.0 op_sel_hi:[1,0]
	v_pk_fma_f32 v[122:123], v[122:123], v[124:125], v[158:159]
	v_cvt_pk_bf16_f32 v124, v126, v127
	v_mul_f32_e32 v125, v127, v127
	v_fmac_f32_e32 v125, v126, v126
	v_mul_f32_e32 v126, v123, v123
	v_fmac_f32_e32 v126, v122, v122
	v_add_f32_e32 v125, v125, v126
	v_mul_f32_e32 v120, v120, v173
	v_mul_f32_e32 v121, v121, v173
	v_rcp_f32_e32 v119, v119
	v_mul_f32_e32 v120, 0xbfb8aa3b, v120
	v_mul_f32_e32 v121, 0xbfb8aa3b, v121
	v_exp_f32_e32 v120, v120
	v_exp_f32_e32 v121, v121
	s_nop 0
	v_pk_add_f32 v[120:121], v[120:121], 1.0 op_sel_hi:[1,0]
	v_rcp_f32_e32 v118, v118
	v_lshlrev_b32_e32 v126, 16, v160
	v_and_b32_e32 v127, 0xffff0000, v160
	v_rcp_f32_e32 v121, v121
	v_mul_f32_e32 v114, v114, v173
	v_lshlrev_b32_e32 v156, 16, v166
	v_and_b32_e32 v157, 0xffff0000, v166
	v_pk_fma_f32 v[118:119], v[118:119], v[126:127], v[156:157]
	global_load_dwordx2 v[126:127], v[152:153], off offset:288
	v_mul_f32_e32 v115, v115, v173
	v_mul_f32_e32 v114, 0xbfb8aa3b, v114
	v_mul_f32_e32 v115, 0xbfb8aa3b, v115
	v_exp_f32_e32 v114, v114
	v_exp_f32_e32 v115, v115
	v_rcp_f32_e32 v120, v120
	v_lshlrev_b32_e32 v128, 16, v161
	v_pk_add_f32 v[114:115], v[114:115], 1.0 op_sel_hi:[1,0]
	v_and_b32_e32 v129, 0xffff0000, v161
	v_lshlrev_b32_e32 v158, 16, v167
	v_and_b32_e32 v159, 0xffff0000, v167
	v_pk_fma_f32 v[120:121], v[120:121], v[128:129], v[158:159]
	v_mul_f32_e32 v128, v119, v119
	v_mul_f32_e32 v129, v121, v121
	v_fmac_f32_e32 v128, v118, v118
	v_fmac_f32_e32 v129, v120, v120
	v_add_f32_e32 v125, v164, v125
	v_add_f32_e32 v128, v128, v129
	v_add_f32_e32 v125, v125, v128
	v_mul_f32_e32 v116, v116, v173
	v_mul_f32_e32 v117, v117, v173
	v_mul_f32_e32 v116, 0xbfb8aa3b, v116
	v_mul_f32_e32 v117, 0xbfb8aa3b, v117
	v_rcp_f32_e32 v115, v115
	v_exp_f32_e32 v116, v116
	v_exp_f32_e32 v117, v117
	s_nop 0
	v_pk_add_f32 v[116:117], v[116:117], 1.0 op_sel_hi:[1,0]
	v_rcp_f32_e32 v114, v114
	v_lshlrev_b32_e32 v128, 16, v154
	v_and_b32_e32 v129, 0xffff0000, v154
	v_rcp_f32_e32 v117, v117
	v_cvt_pk_bf16_f32 v118, v118, v119
	v_rcp_f32_e32 v116, v116
	v_lshlrev_b32_e32 v152, 16, v155
	v_and_b32_e32 v153, 0xffff0000, v155
	s_waitcnt vmcnt(0)
; DI unsigned pk2(float lo, float hi) { f32x2 v = {lo, hi}; bf16x2_t b = __builtin_convertvector(v, bf16x2_t); return __builtin_bit_cast(unsigned, b); }
; DI float sigmoidf_(float x) { return 1.f / (1.f + __expf(-x)); }
;     DI void operator()(const f32x4 (&acc)[2][2][4][2], const Unit& u, int wr, int wc, int fr, int fq) const {
;     ...
;             for (int m = 0; m < 4; ++m) { const int row = row0 + ai * HALF + m * 16;
;                 const float* bp = (row < MP) ? base0 + (size_t)row * DM : base1 + (size_t)(row - MP) * DM;
;                 float r = 1.f; if (MODE == 1) r = __builtin_amdgcn_rsqf(ssin[row] * (1.f / DM) + EPS);
;                 float s = 0.f;
; #pragma unroll
;                 for (int bj = 0; bj < 2; ++bj)
; #pragma unroll
;                     for (int n = 0; n < 2; ++n) { const int col = col0 + bj * HALF + n * 16;
;                         f32x4 v = acc[ai][bj][m][n];
;                         if (MODE == 1) { const u32x2 pw = *(const u32x2*)(PP + (size_t)row * DM + col);
;                             v[0] = sigmoidf_(v[0] * r) * bflo(pw.x); v[1] = sigmoidf_(v[1] * r) * bfhi(pw.x); v[2] = sigmoidf_(v[2] * r) * bflo(pw.y); v[3] = sigmoidf_(v[3] * r) * bfhi(pw.y); }
;                         f32x4 h;
;                         if (baseb) { const u32x2 bw = *(const u32x2*)(baseb + (size_t)row * DM + col); h = (f32x4){bflo(bw.x), bfhi(bw.x), bflo(bw.y), bfhi(bw.y)} + v; }
;                         else h = *(const f32x4*)(bp + col) + v;
;                         if (H) *(f32x4*)(H + (size_t)row * DM + col) = h;
;                         if (XB) { u32x2 w; w.x = pk2(h[0], h[1]); w.y = pk2(h[2], h[3]); *(u32x2*)(XB + (size_t)row * DM + col) = w; }
;                         s += (h[0] * h[0] + h[1] * h[1]) + (h[2] * h[2] + h[3] * h[3]); }
;                 if (ssout) { s += __shfl_xor(s, 16); s += __shfl_xor(s, 32); if (fq == 0) atomicAdd(ssout + row, s); } }
	v_lshlrev_b32_e32 v154, 16, v126
	v_and_b32_e32 v155, 0xffff0000, v126
	v_lshlrev_b32_e32 v126, 16, v127
	v_and_b32_e32 v127, 0xffff0000, v127
	v_pk_fma_f32 v[116:117], v[116:117], v[152:153], v[126:127]
	v_pk_fma_f32 v[126:127], v[114:115], v[128:129], v[154:155]
	v_mul_f32_e32 v115, v117, v117
	v_mul_f32_e32 v114, v127, v127
	v_fmac_f32_e32 v114, v126, v126
	v_fmac_f32_e32 v115, v116, v116
	v_add_f32_e32 v114, v114, v115
	v_add_f32_e32 v114, v125, v114
	v_and_b32_e32 v125, 64, v172
	v_xor_b32_e32 v115, 16, v172
	v_add_u32_e32 v128, 64, v125
	v_cmp_lt_i32_e32 vcc, v115, v128
	v_cvt_pk_bf16_f32 v119, v120, v121
	v_cvt_pk_bf16_f32 v125, v122, v123
	v_cndmask_b32_e32 v115, v172, v115, vcc
	v_lshlrev_b32_e32 v154, 2, v115
	ds_bpermute_b32 v115, v154, v114
	global_store_dwordx2 v[150:151], v[118:119], off offset:256
	v_cvt_pk_bf16_f32 v118, v126, v127
	v_cvt_pk_bf16_f32 v119, v116, v117
	global_store_dwordx2 v[150:151], v[174:175], off
	s_waitcnt lgkmcnt(0)
	v_add_f32_e32 v114, v114, v115
	v_xor_b32_e32 v115, 32, v172
	v_cmp_lt_i32_e32 vcc, v115, v128
	global_store_dwordx2 v[150:151], v[124:125], off offset:32
	global_store_dwordx2 v[150:151], v[118:119], off offset:288
	v_cndmask_b32_e32 v115, v172, v115, vcc
	v_lshlrev_b32_e32 v155, 2, v115
	ds_bpermute_b32 v115, v155, v114
	s_and_saveexec_b64 s[4:5], s[0:1]
	s_cbranch_execz .LBB0_1425
	v_lshl_add_u64 v[116:117], v[148:149], 2, s[12:13]
	s_waitcnt lgkmcnt(0)
	v_add_f32_e32 v114, v114, v115
	global_atomic_add_f32 v[116:117], v114, off
.LBB0_1425:
	s_or_b64 exec, exec, s[4:5]
	v_or_b32_e32 v114, 16, v148
	s_waitcnt lgkmcnt(0)
	v_ashrrev_i32_e32 v115, 31, v114
	v_cmp_gt_i32_e32 vcc, s52, v114
	s_nop 1
	v_cndmask_b32_e32 v115, 0, v115, vcc
	v_lshl_add_u64 v[116:117], v[114:115], 2, s[16:17]
	global_load_dword v149, v[116:117], off
	v_lshlrev_b64 v[116:117], 11, v[114:115]
	v_lshl_add_u64 v[118:119], s[18:19], 0, v[116:117]
	v_lshl_add_u64 v[120:121], v[118:119], 0, v[146:147]
	v_lshl_add_u64 v[118:119], s[92:93], 0, v[116:117]
	v_lshl_add_u64 v[118:119], v[118:119], 0, v[146:147]
	global_load_dwordx2 v[124:125], v[120:121], off
	global_load_dwordx2 v[128:129], v[118:119], off
	global_load_dwordx2 v[122:123], v[120:121], off offset:32
	global_load_dwordx2 v[126:127], v[120:121], off offset:256
	global_load_dwordx2 v[150:151], v[118:119], off offset:32
	global_load_dwordx2 v[152:153], v[118:119], off offset:256
	s_nop 0
	global_load_dwordx2 v[120:121], v[120:121], off offset:288
	v_lshl_add_u64 v[116:117], s[14:15], 0, v[116:117]
	v_lshl_add_u64 v[116:117], v[116:117], 0, v[146:147]
	s_waitcnt vmcnt(7)
	v_fmamk_f32 v149, v149, 0x3a800000, v171
	v_rsq_f32_e32 v149, v149
	s_waitcnt vmcnt(6)
	v_lshlrev_b32_e32 v156, 16, v124
	v_mul_f32_e32 v110, v110, v149
	v_mul_f32_e32 v111, v111, v149
	v_mul_f32_e32 v106, v106, v149
	v_mul_f32_e32 v107, v107, v149
	v_mul_f32_e32 v110, 0xbfb8aa3b, v110
	v_mul_f32_e32 v111, 0xbfb8aa3b, v111
	v_mul_f32_e32 v160, 0xbfb8aa3b, v106
	v_mul_f32_e32 v161, 0xbfb8aa3b, v107
	v_exp_f32_e32 v106, v110
	v_exp_f32_e32 v107, v111
	v_mul_f32_e32 v112, v112, v149
	v_mul_f32_e32 v113, v113, v149
	v_mul_f32_e32 v112, 0xbfb8aa3b, v112
	v_mul_f32_e32 v113, 0xbfb8aa3b, v113
	v_exp_f32_e32 v110, v112
	v_exp_f32_e32 v111, v113
	v_pk_add_f32 v[106:107], v[106:107], 1.0 op_sel_hi:[1,0]
	v_exp_f32_e32 v112, v160
	v_pk_add_f32 v[110:111], v[110:111], 1.0 op_sel_hi:[1,0]
	v_exp_f32_e32 v113, v161
	v_rcp_f32_e32 v107, v107
	v_and_b32_e32 v157, 0xffff0000, v124
	s_waitcnt vmcnt(5)
	v_lshlrev_b32_e32 v158, 16, v128
	v_and_b32_e32 v159, 0xffff0000, v128
	v_rcp_f32_e32 v106, v106
	s_nop 0
	v_pk_fma_f32 v[106:107], v[106:107], v[156:157], v[158:159]
	v_pk_add_f32 v[112:113], v[112:113], 1.0 op_sel_hi:[1,0]
	v_rcp_f32_e32 v111, v111
	v_cvt_pk_bf16_f32 v156, v106, v107
	v_mul_f32_e32 v107, v107, v107
	v_lshlrev_b32_e32 v124, 16, v125
	v_and_b32_e32 v125, 0xffff0000, v125
	v_lshlrev_b32_e32 v128, 16, v129
	v_and_b32_e32 v129, 0xffff0000, v129
	v_rcp_f32_e32 v110, v110
	v_fmac_f32_e32 v107, v106, v106
	v_pk_fma_f32 v[110:111], v[110:111], v[124:125], v[128:129]
	v_cvt_pk_bf16_f32 v157, v110, v111
	v_mul_f32_e32 v111, v111, v111
	v_fmac_f32_e32 v111, v110, v110
	v_add_f32_e32 v128, v107, v111
	v_rcp_f32_e32 v111, v113
	v_mul_f32_e32 v106, v108, v149
	v_mul_f32_e32 v107, v109, v149
	v_mul_f32_e32 v106, 0xbfb8aa3b, v106
	v_mul_f32_e32 v107, 0xbfb8aa3b, v107
	v_exp_f32_e32 v106, v106
	v_exp_f32_e32 v107, v107
	v_rcp_f32_e32 v110, v112
	v_pk_add_f32 v[106:107], v[106:107], 1.0 op_sel_hi:[1,0]
	s_waitcnt vmcnt(4)
	v_lshlrev_b32_e32 v108, 16, v122
	v_and_b32_e32 v109, 0xffff0000, v122
	v_mul_f32_e32 v102, v102, v149
	v_mul_f32_e32 v103, v103, v149
	v_rcp_f32_e32 v107, v107
	v_mul_f32_e32 v102, 0xbfb8aa3b, v102
	v_mul_f32_e32 v103, 0xbfb8aa3b, v103
	v_exp_f32_e32 v102, v102
	v_exp_f32_e32 v103, v103
	v_rcp_f32_e32 v106, v106
	v_lshlrev_b32_e32 v112, 16, v123
	v_and_b32_e32 v113, 0xffff0000, v123
	s_waitcnt vmcnt(2)
	v_lshlrev_b32_e32 v122, 16, v150
	v_and_b32_e32 v123, 0xffff0000, v150
	v_pk_fma_f32 v[110:111], v[110:111], v[108:109], v[122:123]
	v_pk_add_f32 v[102:103], v[102:103], 1.0 op_sel_hi:[1,0]
	v_lshlrev_b32_e32 v124, 16, v151
	v_and_b32_e32 v125, 0xffff0000, v151
	v_cvt_pk_bf16_f32 v108, v110, v111
	v_mul_f32_e32 v109, v111, v111
	v_pk_fma_f32 v[106:107], v[106:107], v[112:113], v[124:125]
	v_fmac_f32_e32 v109, v110, v110
	v_mul_f32_e32 v110, v107, v107
	v_fmac_f32_e32 v110, v106, v106
	v_add_f32_e32 v109, v109, v110
	v_mul_f32_e32 v104, v104, v149
	v_mul_f32_e32 v105, v105, v149
	v_rcp_f32_e32 v103, v103
	v_mul_f32_e32 v104, 0xbfb8aa3b, v104
	v_mul_f32_e32 v105, 0xbfb8aa3b, v105
	v_exp_f32_e32 v104, v104
	v_exp_f32_e32 v105, v105
	s_nop 0
	v_pk_add_f32 v[104:105], v[104:105], 1.0 op_sel_hi:[1,0]
	v_rcp_f32_e32 v102, v102
	v_lshlrev_b32_e32 v110, 16, v126
	v_and_b32_e32 v111, 0xffff0000, v126
	v_rcp_f32_e32 v105, v105
	v_mul_f32_e32 v98, v98, v149
	s_waitcnt vmcnt(1)
; DI unsigned pk2(float lo, float hi) { f32x2 v = {lo, hi}; bf16x2_t b = __builtin_convertvector(v, bf16x2_t); return __builtin_bit_cast(unsigned, b); }
; DI float sigmoidf_(float x) { return 1.f / (1.f + __expf(-x)); }
;     DI void operator()(const f32x4 (&acc)[2][2][4][2], const Unit& u, int wr, int wc, int fr, int fq) const {
;     ...
;             for (int m = 0; m < 4; ++m) { const int row = row0 + ai * HALF + m * 16;
;                 const float* bp = (row < MP) ? base0 + (size_t)row * DM : base1 + (size_t)(row - MP) * DM;
;                 float r = 1.f; if (MODE == 1) r = __builtin_amdgcn_rsqf(ssin[row] * (1.f / DM) + EPS);
;                 float s = 0.f;
; #pragma unroll
;                 for (int bj = 0; bj < 2; ++bj)
; #pragma unroll
;                     for (int n = 0; n < 2; ++n) { const int col = col0 + bj * HALF + n * 16;
;                         f32x4 v = acc[ai][bj][m][n];
;                         if (MODE == 1) { const u32x2 pw = *(const u32x2*)(PP + (size_t)row * DM + col);
;                             v[0] = sigmoidf_(v[0] * r) * bflo(pw.x); v[1] = sigmoidf_(v[1] * r) * bfhi(pw.x); v[2] = sigmoidf_(v[2] * r) * bflo(pw.y); v[3] = sigmoidf_(v[3] * r) * bfhi(pw.y); }
;                         f32x4 h;
;                         if (baseb) { const u32x2 bw = *(const u32x2*)(baseb + (size_t)row * DM + col); h = (f32x4){bflo(bw.x), bfhi(bw.x), bflo(bw.y), bfhi(bw.y)} + v; }
;                         else h = *(const f32x4*)(bp + col) + v;
;                         if (H) *(f32x4*)(H + (size_t)row * DM + col) = h;
;                         if (XB) { u32x2 w; w.x = pk2(h[0], h[1]); w.y = pk2(h[2], h[3]); *(u32x2*)(XB + (size_t)row * DM + col) = w; }
;                         s += (h[0] * h[0] + h[1] * h[1]) + (h[2] * h[2] + h[3] * h[3]); }
;                 if (ssout) { s += __shfl_xor(s, 16); s += __shfl_xor(s, 32); if (fq == 0) atomicAdd(ssout + row, s); } }
	v_lshlrev_b32_e32 v122, 16, v152
	v_and_b32_e32 v123, 0xffff0000, v152
	v_pk_fma_f32 v[102:103], v[102:103], v[110:111], v[122:123]
	global_load_dwordx2 v[110:111], v[118:119], off offset:288
	v_mul_f32_e32 v99, v99, v149
	v_mul_f32_e32 v98, 0xbfb8aa3b, v98
	v_mul_f32_e32 v99, 0xbfb8aa3b, v99
	v_exp_f32_e32 v98, v98
	v_exp_f32_e32 v99, v99
	v_rcp_f32_e32 v104, v104
	v_lshlrev_b32_e32 v112, 16, v127
	v_pk_add_f32 v[98:99], v[98:99], 1.0 op_sel_hi:[1,0]
	v_and_b32_e32 v113, 0xffff0000, v127
	v_lshlrev_b32_e32 v124, 16, v153
	v_and_b32_e32 v125, 0xffff0000, v153
	v_pk_fma_f32 v[104:105], v[104:105], v[112:113], v[124:125]
	v_mul_f32_e32 v112, v103, v103
	v_mul_f32_e32 v113, v105, v105
	v_fmac_f32_e32 v112, v102, v102
	v_fmac_f32_e32 v113, v104, v104
	v_add_f32_e32 v109, v128, v109
	v_add_f32_e32 v112, v112, v113
	v_add_f32_e32 v109, v109, v112
	v_mul_f32_e32 v100, v100, v149
	v_mul_f32_e32 v101, v101, v149
	v_mul_f32_e32 v100, 0xbfb8aa3b, v100
	v_mul_f32_e32 v101, 0xbfb8aa3b, v101
	v_rcp_f32_e32 v99, v99
	v_exp_f32_e32 v100, v100
	v_exp_f32_e32 v101, v101
	s_nop 0
	v_pk_add_f32 v[100:101], v[100:101], 1.0 op_sel_hi:[1,0]
	v_rcp_f32_e32 v98, v98
	s_waitcnt vmcnt(1)
	v_lshlrev_b32_e32 v112, 16, v120
	v_and_b32_e32 v113, 0xffff0000, v120
	v_rcp_f32_e32 v101, v101
	v_cvt_pk_bf16_f32 v102, v102, v103
	v_rcp_f32_e32 v100, v100
	v_lshlrev_b32_e32 v118, 16, v121
	v_and_b32_e32 v119, 0xffff0000, v121
	s_waitcnt vmcnt(0)
	v_lshlrev_b32_e32 v120, 16, v110
	v_and_b32_e32 v121, 0xffff0000, v110
	v_lshlrev_b32_e32 v110, 16, v111
	v_and_b32_e32 v111, 0xffff0000, v111
	v_pk_fma_f32 v[100:101], v[100:101], v[118:119], v[110:111]
	v_pk_fma_f32 v[110:111], v[98:99], v[112:113], v[120:121]
	v_mul_f32_e32 v99, v101, v101
	v_mul_f32_e32 v98, v111, v111
	v_fmac_f32_e32 v98, v110, v110
	v_fmac_f32_e32 v99, v100, v100
	v_add_f32_e32 v98, v98, v99
	v_add_f32_e32 v98, v109, v98
	ds_bpermute_b32 v99, v154, v98
	v_cvt_pk_bf16_f32 v103, v104, v105
	v_cvt_pk_bf16_f32 v109, v106, v107
	global_store_dwordx2 v[116:117], v[102:103], off offset:256
	v_cvt_pk_bf16_f32 v102, v110, v111
	s_waitcnt lgkmcnt(0)
	v_add_f32_e32 v98, v98, v99
	ds_bpermute_b32 v99, v155, v98
	v_cvt_pk_bf16_f32 v103, v100, v101
	global_store_dwordx2 v[116:117], v[156:157], off
	global_store_dwordx2 v[116:117], v[108:109], off offset:32
	global_store_dwordx2 v[116:117], v[102:103], off offset:288
	s_and_saveexec_b64 s[4:5], s[0:1]
	s_cbranch_execz .LBB0_1427
	v_lshl_add_u64 v[100:101], v[114:115], 2, s[12:13]
	s_waitcnt lgkmcnt(0)
	v_add_f32_e32 v98, v98, v99
	global_atomic_add_f32 v[100:101], v98, off
.LBB0_1427:
	s_or_b64 exec, exec, s[4:5]
	v_or_b32_e32 v98, 32, v148
	s_waitcnt lgkmcnt(0)
	v_ashrrev_i32_e32 v99, 31, v98
	v_cmp_gt_i32_e32 vcc, s52, v98
	s_nop 1
	v_cndmask_b32_e32 v99, 0, v99, vcc
	v_lshl_add_u64 v[100:101], v[98:99], 2, s[16:17]
	global_load_dword v118, v[100:101], off
	v_lshlrev_b64 v[100:101], 11, v[98:99]
	v_lshl_add_u64 v[102:103], s[18:19], 0, v[100:101]
	v_lshl_add_u64 v[104:105], v[102:103], 0, v[146:147]
	v_lshl_add_u64 v[102:103], s[92:93], 0, v[100:101]
	v_lshl_add_u64 v[102:103], v[102:103], 0, v[146:147]
	global_load_dwordx2 v[108:109], v[104:105], off
	global_load_dwordx2 v[112:113], v[102:103], off
	global_load_dwordx2 v[106:107], v[104:105], off offset:32
	global_load_dwordx2 v[110:111], v[104:105], off offset:256
	global_load_dwordx2 v[114:115], v[102:103], off offset:32
	global_load_dwordx2 v[116:117], v[102:103], off offset:256
	s_nop 0
	global_load_dwordx2 v[104:105], v[104:105], off offset:288
	v_lshl_add_u64 v[100:101], s[14:15], 0, v[100:101]
	v_lshl_add_u64 v[100:101], v[100:101], 0, v[146:147]
	s_waitcnt vmcnt(7)
	v_fmamk_f32 v118, v118, 0x3a800000, v171
	v_rsq_f32_e32 v122, v118
	s_waitcnt vmcnt(6)
	v_lshlrev_b32_e32 v118, 16, v108
	v_mul_f32_e32 v94, v94, v122
	v_mul_f32_e32 v95, v95, v122
	v_mul_f32_e32 v90, v90, v122
	v_mul_f32_e32 v91, v91, v122
	v_mul_f32_e32 v94, 0xbfb8aa3b, v94
	v_mul_f32_e32 v95, 0xbfb8aa3b, v95
	v_mul_f32_e32 v123, 0xbfb8aa3b, v90
	v_mul_f32_e32 v124, 0xbfb8aa3b, v91
	v_exp_f32_e32 v90, v94
	v_exp_f32_e32 v91, v95
	v_mul_f32_e32 v96, v96, v122
	v_mul_f32_e32 v97, v97, v122
	v_mul_f32_e32 v96, 0xbfb8aa3b, v96
	v_mul_f32_e32 v97, 0xbfb8aa3b, v97
	v_exp_f32_e32 v94, v96
	v_exp_f32_e32 v95, v97
	v_pk_add_f32 v[90:91], v[90:91], 1.0 op_sel_hi:[1,0]
	v_exp_f32_e32 v96, v123
	v_pk_add_f32 v[94:95], v[94:95], 1.0 op_sel_hi:[1,0]
	v_exp_f32_e32 v97, v124
	v_rcp_f32_e32 v91, v91
	v_and_b32_e32 v119, 0xffff0000, v108
	s_waitcnt vmcnt(5)
	v_lshlrev_b32_e32 v120, 16, v112
	v_and_b32_e32 v121, 0xffff0000, v112
	v_rcp_f32_e32 v90, v90
	s_nop 0
	v_pk_fma_f32 v[90:91], v[90:91], v[118:119], v[120:121]
	v_pk_add_f32 v[96:97], v[96:97], 1.0 op_sel_hi:[1,0]
	v_rcp_f32_e32 v95, v95
	v_cvt_pk_bf16_f32 v118, v90, v91
	v_mul_f32_e32 v91, v91, v91
	v_lshlrev_b32_e32 v108, 16, v109
	v_and_b32_e32 v109, 0xffff0000, v109
	v_lshlrev_b32_e32 v112, 16, v113
	v_and_b32_e32 v113, 0xffff0000, v113
	v_rcp_f32_e32 v94, v94
	v_fmac_f32_e32 v91, v90, v90
	v_pk_fma_f32 v[94:95], v[94:95], v[108:109], v[112:113]
	v_cvt_pk_bf16_f32 v119, v94, v95
	v_mul_f32_e32 v95, v95, v95
	v_fmac_f32_e32 v95, v94, v94
	v_add_f32_e32 v112, v91, v95
	v_rcp_f32_e32 v95, v97
	v_mul_f32_e32 v90, v92, v122
	v_mul_f32_e32 v91, v93, v122
	v_mul_f32_e32 v90, 0xbfb8aa3b, v90
	v_mul_f32_e32 v91, 0xbfb8aa3b, v91
	v_exp_f32_e32 v90, v90
	v_exp_f32_e32 v91, v91
	v_rcp_f32_e32 v94, v96
	v_pk_add_f32 v[90:91], v[90:91], 1.0 op_sel_hi:[1,0]
	s_waitcnt vmcnt(4)
; DI unsigned pk2(float lo, float hi) { f32x2 v = {lo, hi}; bf16x2_t b = __builtin_convertvector(v, bf16x2_t); return __builtin_bit_cast(unsigned, b); }
; DI float sigmoidf_(float x) { return 1.f / (1.f + __expf(-x)); }
;     DI void operator()(const f32x4 (&acc)[2][2][4][2], const Unit& u, int wr, int wc, int fr, int fq) const {
;     ...
;             for (int m = 0; m < 4; ++m) { const int row = row0 + ai * HALF + m * 16;
;                 const float* bp = (row < MP) ? base0 + (size_t)row * DM : base1 + (size_t)(row - MP) * DM;
;                 float r = 1.f; if (MODE == 1) r = __builtin_amdgcn_rsqf(ssin[row] * (1.f / DM) + EPS);
;                 float s = 0.f;
; #pragma unroll
;                 for (int bj = 0; bj < 2; ++bj)
; #pragma unroll
;                     for (int n = 0; n < 2; ++n) { const int col = col0 + bj * HALF + n * 16;
;                         f32x4 v = acc[ai][bj][m][n];
;                         if (MODE == 1) { const u32x2 pw = *(const u32x2*)(PP + (size_t)row * DM + col);
;                             v[0] = sigmoidf_(v[0] * r) * bflo(pw.x); v[1] = sigmoidf_(v[1] * r) * bfhi(pw.x); v[2] = sigmoidf_(v[2] * r) * bflo(pw.y); v[3] = sigmoidf_(v[3] * r) * bfhi(pw.y); }
;                         f32x4 h;
;                         if (baseb) { const u32x2 bw = *(const u32x2*)(baseb + (size_t)row * DM + col); h = (f32x4){bflo(bw.x), bfhi(bw.x), bflo(bw.y), bfhi(bw.y)} + v; }
;                         else h = *(const f32x4*)(bp + col) + v;
;                         if (H) *(f32x4*)(H + (size_t)row * DM + col) = h;
;                         if (XB) { u32x2 w; w.x = pk2(h[0], h[1]); w.y = pk2(h[2], h[3]); *(u32x2*)(XB + (size_t)row * DM + col) = w; }
;                         s += (h[0] * h[0] + h[1] * h[1]) + (h[2] * h[2] + h[3] * h[3]); }
;                 if (ssout) { s += __shfl_xor(s, 16); s += __shfl_xor(s, 32); if (fq == 0) atomicAdd(ssout + row, s); } }
	v_lshlrev_b32_e32 v92, 16, v106
	v_and_b32_e32 v93, 0xffff0000, v106
	v_mul_f32_e32 v86, v86, v122
	v_mul_f32_e32 v87, v87, v122
	v_rcp_f32_e32 v91, v91
	v_mul_f32_e32 v86, 0xbfb8aa3b, v86
	v_mul_f32_e32 v87, 0xbfb8aa3b, v87
	v_exp_f32_e32 v86, v86
	v_exp_f32_e32 v87, v87
	v_rcp_f32_e32 v90, v90
	v_lshlrev_b32_e32 v96, 16, v107
	v_and_b32_e32 v97, 0xffff0000, v107
	s_waitcnt vmcnt(2)
	v_lshlrev_b32_e32 v106, 16, v114
	v_and_b32_e32 v107, 0xffff0000, v114
	v_pk_fma_f32 v[94:95], v[94:95], v[92:93], v[106:107]
	v_pk_add_f32 v[86:87], v[86:87], 1.0 op_sel_hi:[1,0]
	v_lshlrev_b32_e32 v108, 16, v115
	v_and_b32_e32 v109, 0xffff0000, v115
	v_cvt_pk_bf16_f32 v92, v94, v95
	v_mul_f32_e32 v93, v95, v95
	v_pk_fma_f32 v[90:91], v[90:91], v[96:97], v[108:109]
	v_fmac_f32_e32 v93, v94, v94
	v_mul_f32_e32 v94, v91, v91
	v_fmac_f32_e32 v94, v90, v90
	v_add_f32_e32 v93, v93, v94
	v_mul_f32_e32 v88, v88, v122
	v_mul_f32_e32 v89, v89, v122
	v_rcp_f32_e32 v87, v87
	v_mul_f32_e32 v88, 0xbfb8aa3b, v88
	v_mul_f32_e32 v89, 0xbfb8aa3b, v89
	v_exp_f32_e32 v88, v88
	v_exp_f32_e32 v89, v89
	s_nop 0
	v_pk_add_f32 v[88:89], v[88:89], 1.0 op_sel_hi:[1,0]
	v_rcp_f32_e32 v86, v86
	v_lshlrev_b32_e32 v94, 16, v110
	v_and_b32_e32 v95, 0xffff0000, v110
	v_rcp_f32_e32 v89, v89
	v_mul_f32_e32 v82, v82, v122
	s_waitcnt vmcnt(1)
	v_lshlrev_b32_e32 v106, 16, v116
	v_and_b32_e32 v107, 0xffff0000, v116
	v_pk_fma_f32 v[86:87], v[86:87], v[94:95], v[106:107]
	global_load_dwordx2 v[94:95], v[102:103], off offset:288
	v_mul_f32_e32 v83, v83, v122
	v_mul_f32_e32 v82, 0xbfb8aa3b, v82
	v_mul_f32_e32 v83, 0xbfb8aa3b, v83
	v_exp_f32_e32 v82, v82
	v_exp_f32_e32 v83, v83
	v_rcp_f32_e32 v88, v88
	v_lshlrev_b32_e32 v96, 16, v111
	v_pk_add_f32 v[82:83], v[82:83], 1.0 op_sel_hi:[1,0]
	v_and_b32_e32 v97, 0xffff0000, v111
	v_lshlrev_b32_e32 v108, 16, v117
	v_and_b32_e32 v109, 0xffff0000, v117
	v_pk_fma_f32 v[88:89], v[88:89], v[96:97], v[108:109]
	v_mul_f32_e32 v96, v87, v87
	v_mul_f32_e32 v97, v89, v89
	v_fmac_f32_e32 v96, v86, v86
	v_fmac_f32_e32 v97, v88, v88
	v_add_f32_e32 v93, v112, v93
	v_add_f32_e32 v96, v96, v97
	v_add_f32_e32 v93, v93, v96
	v_mul_f32_e32 v84, v84, v122
	v_mul_f32_e32 v85, v85, v122
	v_mul_f32_e32 v84, 0xbfb8aa3b, v84
	v_mul_f32_e32 v85, 0xbfb8aa3b, v85
	v_rcp_f32_e32 v83, v83
	v_exp_f32_e32 v84, v84
	v_exp_f32_e32 v85, v85
	s_nop 0
	v_pk_add_f32 v[84:85], v[84:85], 1.0 op_sel_hi:[1,0]
	v_rcp_f32_e32 v82, v82
	s_waitcnt vmcnt(1)
	v_lshlrev_b32_e32 v96, 16, v104
	v_and_b32_e32 v97, 0xffff0000, v104
	v_rcp_f32_e32 v85, v85
	v_cvt_pk_bf16_f32 v86, v86, v87
	v_rcp_f32_e32 v84, v84
	v_lshlrev_b32_e32 v102, 16, v105
	v_and_b32_e32 v103, 0xffff0000, v105
	s_waitcnt vmcnt(0)
	v_lshlrev_b32_e32 v104, 16, v94
	v_and_b32_e32 v105, 0xffff0000, v94
	v_lshlrev_b32_e32 v94, 16, v95
	v_and_b32_e32 v95, 0xffff0000, v95
	v_pk_fma_f32 v[84:85], v[84:85], v[102:103], v[94:95]
	v_pk_fma_f32 v[94:95], v[82:83], v[96:97], v[104:105]
	v_mul_f32_e32 v83, v85, v85
	v_mul_f32_e32 v82, v95, v95
	v_fmac_f32_e32 v82, v94, v94
	v_fmac_f32_e32 v83, v84, v84
	v_add_f32_e32 v82, v82, v83
	v_add_f32_e32 v82, v93, v82
	ds_bpermute_b32 v83, v154, v82
	v_cvt_pk_bf16_f32 v87, v88, v89
	v_cvt_pk_bf16_f32 v93, v90, v91
	global_store_dwordx2 v[100:101], v[86:87], off offset:256
	v_cvt_pk_bf16_f32 v86, v94, v95
	s_waitcnt lgkmcnt(0)
	v_add_f32_e32 v82, v82, v83
	ds_bpermute_b32 v83, v155, v82
	v_cvt_pk_bf16_f32 v87, v84, v85
	global_store_dwordx2 v[100:101], v[118:119], off
	global_store_dwordx2 v[100:101], v[92:93], off offset:32
	global_store_dwordx2 v[100:101], v[86:87], off offset:288
	s_and_saveexec_b64 s[4:5], s[0:1]
	s_cbranch_execz .LBB0_1429
	v_lshl_add_u64 v[84:85], v[98:99], 2, s[12:13]
	s_waitcnt lgkmcnt(0)
	v_add_f32_e32 v82, v82, v83
	global_atomic_add_f32 v[84:85], v82, off
.LBB0_1429:
	s_or_b64 exec, exec, s[4:5]
	v_or_b32_e32 v82, 48, v148
	s_waitcnt lgkmcnt(0)
	v_ashrrev_i32_e32 v83, 31, v82
	v_cmp_gt_i32_e32 vcc, s52, v82
	s_nop 1
	v_cndmask_b32_e32 v83, 0, v83, vcc
	v_lshl_add_u64 v[84:85], v[82:83], 2, s[16:17]
	global_load_dword v102, v[84:85], off
	v_lshlrev_b64 v[84:85], 11, v[82:83]
	v_lshl_add_u64 v[86:87], s[18:19], 0, v[84:85]
	v_lshl_add_u64 v[88:89], v[86:87], 0, v[146:147]
	v_lshl_add_u64 v[86:87], s[92:93], 0, v[84:85]
	v_lshl_add_u64 v[86:87], v[86:87], 0, v[146:147]
	global_load_dwordx2 v[92:93], v[88:89], off
	global_load_dwordx2 v[96:97], v[86:87], off
	global_load_dwordx2 v[90:91], v[88:89], off offset:32
	global_load_dwordx2 v[94:95], v[88:89], off offset:256
	global_load_dwordx2 v[98:99], v[86:87], off offset:32
	global_load_dwordx2 v[100:101], v[86:87], off offset:256
	s_nop 0
	global_load_dwordx2 v[88:89], v[88:89], off offset:288
	v_lshl_add_u64 v[84:85], s[14:15], 0, v[84:85]
	v_lshl_add_u64 v[84:85], v[84:85], 0, v[146:147]
	s_waitcnt vmcnt(7)
	v_fmamk_f32 v102, v102, 0x3a800000, v171
	v_rsq_f32_e32 v106, v102
	s_waitcnt vmcnt(6)
	v_lshlrev_b32_e32 v102, 16, v92
	v_mul_f32_e32 v78, v78, v106
	v_mul_f32_e32 v79, v79, v106
	v_mul_f32_e32 v74, v74, v106
	v_mul_f32_e32 v75, v75, v106
	v_mul_f32_e32 v78, 0xbfb8aa3b, v78
	v_mul_f32_e32 v79, 0xbfb8aa3b, v79
	v_mul_f32_e32 v107, 0xbfb8aa3b, v74
	v_mul_f32_e32 v108, 0xbfb8aa3b, v75
	v_exp_f32_e32 v74, v78
	v_exp_f32_e32 v75, v79
	v_mul_f32_e32 v80, v80, v106
	v_mul_f32_e32 v81, v81, v106
	v_mul_f32_e32 v80, 0xbfb8aa3b, v80
	v_mul_f32_e32 v81, 0xbfb8aa3b, v81
	v_exp_f32_e32 v78, v80
	v_exp_f32_e32 v79, v81
	v_pk_add_f32 v[74:75], v[74:75], 1.0 op_sel_hi:[1,0]
	v_exp_f32_e32 v80, v107
	v_pk_add_f32 v[78:79], v[78:79], 1.0 op_sel_hi:[1,0]
	v_exp_f32_e32 v81, v108
	v_rcp_f32_e32 v75, v75
	v_and_b32_e32 v103, 0xffff0000, v92
	s_waitcnt vmcnt(5)
; DI unsigned pk2(float lo, float hi) { f32x2 v = {lo, hi}; bf16x2_t b = __builtin_convertvector(v, bf16x2_t); return __builtin_bit_cast(unsigned, b); }
; DI float sigmoidf_(float x) { return 1.f / (1.f + __expf(-x)); }
;     DI void operator()(const f32x4 (&acc)[2][2][4][2], const Unit& u, int wr, int wc, int fr, int fq) const {
;     ...
;             for (int m = 0; m < 4; ++m) { const int row = row0 + ai * HALF + m * 16;
;                 const float* bp = (row < MP) ? base0 + (size_t)row * DM : base1 + (size_t)(row - MP) * DM;
;                 float r = 1.f; if (MODE == 1) r = __builtin_amdgcn_rsqf(ssin[row] * (1.f / DM) + EPS);
;                 float s = 0.f;
; #pragma unroll
;                 for (int bj = 0; bj < 2; ++bj)
; #pragma unroll
;                     for (int n = 0; n < 2; ++n) { const int col = col0 + bj * HALF + n * 16;
;                         f32x4 v = acc[ai][bj][m][n];
;                         if (MODE == 1) { const u32x2 pw = *(const u32x2*)(PP + (size_t)row * DM + col);
;                             v[0] = sigmoidf_(v[0] * r) * bflo(pw.x); v[1] = sigmoidf_(v[1] * r) * bfhi(pw.x); v[2] = sigmoidf_(v[2] * r) * bflo(pw.y); v[3] = sigmoidf_(v[3] * r) * bfhi(pw.y); }
;                         f32x4 h;
;                         if (baseb) { const u32x2 bw = *(const u32x2*)(baseb + (size_t)row * DM + col); h = (f32x4){bflo(bw.x), bfhi(bw.x), bflo(bw.y), bfhi(bw.y)} + v; }
;                         else h = *(const f32x4*)(bp + col) + v;
;                         if (H) *(f32x4*)(H + (size_t)row * DM + col) = h;
;                         if (XB) { u32x2 w; w.x = pk2(h[0], h[1]); w.y = pk2(h[2], h[3]); *(u32x2*)(XB + (size_t)row * DM + col) = w; }
;                         s += (h[0] * h[0] + h[1] * h[1]) + (h[2] * h[2] + h[3] * h[3]); }
;                 if (ssout) { s += __shfl_xor(s, 16); s += __shfl_xor(s, 32); if (fq == 0) atomicAdd(ssout + row, s); } }
	v_lshlrev_b32_e32 v104, 16, v96
	v_and_b32_e32 v105, 0xffff0000, v96
	v_rcp_f32_e32 v74, v74
	s_nop 0
	v_pk_fma_f32 v[74:75], v[74:75], v[102:103], v[104:105]
	v_pk_add_f32 v[80:81], v[80:81], 1.0 op_sel_hi:[1,0]
	v_rcp_f32_e32 v79, v79
	v_cvt_pk_bf16_f32 v102, v74, v75
	v_mul_f32_e32 v75, v75, v75
	v_lshlrev_b32_e32 v92, 16, v93
	v_and_b32_e32 v93, 0xffff0000, v93
	v_lshlrev_b32_e32 v96, 16, v97
	v_and_b32_e32 v97, 0xffff0000, v97
	v_rcp_f32_e32 v78, v78
	v_fmac_f32_e32 v75, v74, v74
	v_pk_fma_f32 v[78:79], v[78:79], v[92:93], v[96:97]
	v_cvt_pk_bf16_f32 v103, v78, v79
	v_mul_f32_e32 v79, v79, v79
	v_fmac_f32_e32 v79, v78, v78
	v_add_f32_e32 v96, v75, v79
	v_rcp_f32_e32 v79, v81
	v_mul_f32_e32 v74, v76, v106
	v_mul_f32_e32 v75, v77, v106
	v_mul_f32_e32 v74, 0xbfb8aa3b, v74
	v_mul_f32_e32 v75, 0xbfb8aa3b, v75
	v_exp_f32_e32 v74, v74
	v_exp_f32_e32 v75, v75
	v_rcp_f32_e32 v78, v80
	v_pk_add_f32 v[74:75], v[74:75], 1.0 op_sel_hi:[1,0]
	s_waitcnt vmcnt(4)
	v_lshlrev_b32_e32 v76, 16, v90
	v_and_b32_e32 v77, 0xffff0000, v90
	v_mul_f32_e32 v70, v70, v106
	v_mul_f32_e32 v71, v71, v106
	v_rcp_f32_e32 v75, v75
	v_mul_f32_e32 v70, 0xbfb8aa3b, v70
	v_mul_f32_e32 v71, 0xbfb8aa3b, v71
	v_exp_f32_e32 v70, v70
	v_exp_f32_e32 v71, v71
	v_rcp_f32_e32 v74, v74
	v_lshlrev_b32_e32 v80, 16, v91
	v_and_b32_e32 v81, 0xffff0000, v91
	s_waitcnt vmcnt(2)
	v_lshlrev_b32_e32 v90, 16, v98
	v_and_b32_e32 v91, 0xffff0000, v98
	v_pk_fma_f32 v[78:79], v[78:79], v[76:77], v[90:91]
	v_pk_add_f32 v[70:71], v[70:71], 1.0 op_sel_hi:[1,0]
	v_lshlrev_b32_e32 v92, 16, v99
	v_and_b32_e32 v93, 0xffff0000, v99
	v_cvt_pk_bf16_f32 v76, v78, v79
	v_mul_f32_e32 v77, v79, v79
	v_pk_fma_f32 v[74:75], v[74:75], v[80:81], v[92:93]
	v_fmac_f32_e32 v77, v78, v78
	v_mul_f32_e32 v78, v75, v75
	v_fmac_f32_e32 v78, v74, v74
	v_add_f32_e32 v77, v77, v78
	v_mul_f32_e32 v72, v72, v106
	v_mul_f32_e32 v73, v73, v106
	v_rcp_f32_e32 v71, v71
	v_mul_f32_e32 v72, 0xbfb8aa3b, v72
	v_mul_f32_e32 v73, 0xbfb8aa3b, v73
	v_exp_f32_e32 v72, v72
	v_exp_f32_e32 v73, v73
	s_nop 0
	v_pk_add_f32 v[72:73], v[72:73], 1.0 op_sel_hi:[1,0]
	v_rcp_f32_e32 v70, v70
	v_lshlrev_b32_e32 v78, 16, v94
	v_and_b32_e32 v79, 0xffff0000, v94
	v_rcp_f32_e32 v73, v73
	v_mul_f32_e32 v66, v66, v106
	s_waitcnt vmcnt(1)
	v_lshlrev_b32_e32 v90, 16, v100
	v_and_b32_e32 v91, 0xffff0000, v100
	v_pk_fma_f32 v[70:71], v[70:71], v[78:79], v[90:91]
	global_load_dwordx2 v[78:79], v[86:87], off offset:288
	v_mul_f32_e32 v67, v67, v106
	v_mul_f32_e32 v66, 0xbfb8aa3b, v66
	v_mul_f32_e32 v67, 0xbfb8aa3b, v67
	v_exp_f32_e32 v66, v66
	v_exp_f32_e32 v67, v67
	v_rcp_f32_e32 v72, v72
	v_lshlrev_b32_e32 v80, 16, v95
	v_pk_add_f32 v[66:67], v[66:67], 1.0 op_sel_hi:[1,0]
	v_and_b32_e32 v81, 0xffff0000, v95
	v_lshlrev_b32_e32 v92, 16, v101
	v_and_b32_e32 v93, 0xffff0000, v101
	v_pk_fma_f32 v[72:73], v[72:73], v[80:81], v[92:93]
	v_mul_f32_e32 v80, v71, v71
	v_mul_f32_e32 v81, v73, v73
	v_fmac_f32_e32 v80, v70, v70
	v_fmac_f32_e32 v81, v72, v72
	v_add_f32_e32 v77, v96, v77
	v_add_f32_e32 v80, v80, v81
	v_add_f32_e32 v77, v77, v80
	v_mul_f32_e32 v68, v68, v106
	v_mul_f32_e32 v69, v69, v106
	v_mul_f32_e32 v68, 0xbfb8aa3b, v68
	v_mul_f32_e32 v69, 0xbfb8aa3b, v69
	v_rcp_f32_e32 v67, v67
	v_exp_f32_e32 v68, v68
	v_exp_f32_e32 v69, v69
	s_nop 0
	v_pk_add_f32 v[68:69], v[68:69], 1.0 op_sel_hi:[1,0]
	v_rcp_f32_e32 v66, v66
	s_waitcnt vmcnt(1)
	v_lshlrev_b32_e32 v80, 16, v88
	v_and_b32_e32 v81, 0xffff0000, v88
	v_rcp_f32_e32 v69, v69
	v_cvt_pk_bf16_f32 v70, v70, v71
	v_rcp_f32_e32 v68, v68
	v_lshlrev_b32_e32 v86, 16, v89
	v_and_b32_e32 v87, 0xffff0000, v89
	s_waitcnt vmcnt(0)
	v_lshlrev_b32_e32 v88, 16, v78
	v_and_b32_e32 v89, 0xffff0000, v78
	v_lshlrev_b32_e32 v78, 16, v79
	v_and_b32_e32 v79, 0xffff0000, v79
	v_pk_fma_f32 v[68:69], v[68:69], v[86:87], v[78:79]
	v_pk_fma_f32 v[78:79], v[66:67], v[80:81], v[88:89]
	v_mul_f32_e32 v67, v69, v69
	v_mul_f32_e32 v66, v79, v79
	v_fmac_f32_e32 v66, v78, v78
	v_fmac_f32_e32 v67, v68, v68
	v_add_f32_e32 v66, v66, v67
	v_add_f32_e32 v66, v77, v66
	ds_bpermute_b32 v67, v154, v66
	v_cvt_pk_bf16_f32 v71, v72, v73
	v_cvt_pk_bf16_f32 v77, v74, v75
	global_store_dwordx2 v[84:85], v[70:71], off offset:256
	v_cvt_pk_bf16_f32 v70, v78, v79
	s_waitcnt lgkmcnt(0)
	v_add_f32_e32 v66, v66, v67
	ds_bpermute_b32 v67, v155, v66
	v_cvt_pk_bf16_f32 v71, v68, v69
	global_store_dwordx2 v[84:85], v[102:103], off
	global_store_dwordx2 v[84:85], v[76:77], off offset:32
	global_store_dwordx2 v[84:85], v[70:71], off offset:288
	s_and_saveexec_b64 s[4:5], s[0:1]
	s_cbranch_execz .LBB0_1431
	v_lshl_add_u64 v[68:69], v[82:83], 2, s[12:13]
	s_waitcnt lgkmcnt(0)
	v_add_f32_e32 v66, v66, v67
	global_atomic_add_f32 v[68:69], v66, off
; DI unsigned pk2(float lo, float hi) { f32x2 v = {lo, hi}; bf16x2_t b = __builtin_convertvector(v, bf16x2_t); return __builtin_bit_cast(unsigned, b); }
; DI float sigmoidf_(float x) { return 1.f / (1.f + __expf(-x)); }
;     DI void operator()(const f32x4 (&acc)[2][2][4][2], const Unit& u, int wr, int wc, int fr, int fq) const {
;     ...
;             for (int m = 0; m < 4; ++m) { const int row = row0 + ai * HALF + m * 16;
;                 const float* bp = (row < MP) ? base0 + (size_t)row * DM : base1 + (size_t)(row - MP) * DM;
;                 float r = 1.f; if (MODE == 1) r = __builtin_amdgcn_rsqf(ssin[row] * (1.f / DM) + EPS);
;                 float s = 0.f;
; #pragma unroll
;                 for (int bj = 0; bj < 2; ++bj)
; #pragma unroll
;                     for (int n = 0; n < 2; ++n) { const int col = col0 + bj * HALF + n * 16;
;                         f32x4 v = acc[ai][bj][m][n];
;                         if (MODE == 1) { const u32x2 pw = *(const u32x2*)(PP + (size_t)row * DM + col);
;                             v[0] = sigmoidf_(v[0] * r) * bflo(pw.x); v[1] = sigmoidf_(v[1] * r) * bfhi(pw.x); v[2] = sigmoidf_(v[2] * r) * bflo(pw.y); v[3] = sigmoidf_(v[3] * r) * bfhi(pw.y); }
;                         f32x4 h;
;                         if (baseb) { const u32x2 bw = *(const u32x2*)(baseb + (size_t)row * DM + col); h = (f32x4){bflo(bw.x), bfhi(bw.x), bflo(bw.y), bfhi(bw.y)} + v; }
;                         else h = *(const f32x4*)(bp + col) + v;
;                         if (H) *(f32x4*)(H + (size_t)row * DM + col) = h;
;                         if (XB) { u32x2 w; w.x = pk2(h[0], h[1]); w.y = pk2(h[2], h[3]); *(u32x2*)(XB + (size_t)row * DM + col) = w; }
;                         s += (h[0] * h[0] + h[1] * h[1]) + (h[2] * h[2] + h[3] * h[3]); }
;                 if (ssout) { s += __shfl_xor(s, 16); s += __shfl_xor(s, 32); if (fq == 0) atomicAdd(ssout + row, s); } }
.LBB0_1431:
	s_or_b64 exec, exec, s[4:5]
	v_add_u32_e32 v66, 0x80, v148
	s_waitcnt lgkmcnt(0)
	v_ashrrev_i32_e32 v67, 31, v66
	v_cmp_gt_i32_e32 vcc, s59, v148
	s_nop 1
	v_cndmask_b32_e32 v67, 0, v67, vcc
	v_lshl_add_u64 v[68:69], v[66:67], 2, s[16:17]
	global_load_dword v86, v[68:69], off
	v_lshlrev_b64 v[68:69], 11, v[66:67]
	v_lshl_add_u64 v[70:71], s[18:19], 0, v[68:69]
	v_lshl_add_u64 v[72:73], v[70:71], 0, v[146:147]
	v_lshl_add_u64 v[70:71], s[92:93], 0, v[68:69]
	v_lshl_add_u64 v[70:71], v[70:71], 0, v[146:147]
	global_load_dwordx2 v[76:77], v[72:73], off
	global_load_dwordx2 v[80:81], v[70:71], off
	global_load_dwordx2 v[74:75], v[72:73], off offset:32
	global_load_dwordx2 v[78:79], v[72:73], off offset:256
	global_load_dwordx2 v[82:83], v[70:71], off offset:32
	global_load_dwordx2 v[84:85], v[70:71], off offset:256
	s_nop 0
	global_load_dwordx2 v[72:73], v[72:73], off offset:288
	v_lshl_add_u64 v[68:69], s[14:15], 0, v[68:69]
	v_lshl_add_u64 v[68:69], v[68:69], 0, v[146:147]
	s_waitcnt vmcnt(7)
	v_fmamk_f32 v86, v86, 0x3a800000, v171
	v_rsq_f32_e32 v90, v86
	s_waitcnt vmcnt(6)
	v_lshlrev_b32_e32 v86, 16, v76
	v_mul_f32_e32 v62, v62, v90
	v_mul_f32_e32 v63, v63, v90
	v_mul_f32_e32 v58, v58, v90
	v_mul_f32_e32 v59, v59, v90
	v_mul_f32_e32 v62, 0xbfb8aa3b, v62
	v_mul_f32_e32 v63, 0xbfb8aa3b, v63
	v_mul_f32_e32 v91, 0xbfb8aa3b, v58
	v_mul_f32_e32 v92, 0xbfb8aa3b, v59
	v_exp_f32_e32 v58, v62
	v_exp_f32_e32 v59, v63
	v_mul_f32_e32 v64, v64, v90
	v_mul_f32_e32 v65, v65, v90
	v_mul_f32_e32 v64, 0xbfb8aa3b, v64
	v_mul_f32_e32 v65, 0xbfb8aa3b, v65
	v_exp_f32_e32 v62, v64
	v_exp_f32_e32 v63, v65
	v_pk_add_f32 v[58:59], v[58:59], 1.0 op_sel_hi:[1,0]
	v_exp_f32_e32 v64, v91
	v_pk_add_f32 v[62:63], v[62:63], 1.0 op_sel_hi:[1,0]
	v_exp_f32_e32 v65, v92
	v_rcp_f32_e32 v59, v59
	v_and_b32_e32 v87, 0xffff0000, v76
	s_waitcnt vmcnt(5)
	v_lshlrev_b32_e32 v88, 16, v80
	v_and_b32_e32 v89, 0xffff0000, v80
	v_rcp_f32_e32 v58, v58
	s_nop 0
	v_pk_fma_f32 v[58:59], v[58:59], v[86:87], v[88:89]
	v_pk_add_f32 v[64:65], v[64:65], 1.0 op_sel_hi:[1,0]
	v_rcp_f32_e32 v63, v63
	v_cvt_pk_bf16_f32 v86, v58, v59
	v_mul_f32_e32 v59, v59, v59
	v_lshlrev_b32_e32 v76, 16, v77
	v_and_b32_e32 v77, 0xffff0000, v77
	v_lshlrev_b32_e32 v80, 16, v81
	v_and_b32_e32 v81, 0xffff0000, v81
	v_rcp_f32_e32 v62, v62
	v_fmac_f32_e32 v59, v58, v58
	v_pk_fma_f32 v[62:63], v[62:63], v[76:77], v[80:81]
	v_cvt_pk_bf16_f32 v87, v62, v63
	v_mul_f32_e32 v63, v63, v63
	v_fmac_f32_e32 v63, v62, v62
	v_add_f32_e32 v80, v59, v63
	v_rcp_f32_e32 v63, v65
	v_mul_f32_e32 v58, v60, v90
	v_mul_f32_e32 v59, v61, v90
	v_mul_f32_e32 v58, 0xbfb8aa3b, v58
	v_mul_f32_e32 v59, 0xbfb8aa3b, v59
	v_exp_f32_e32 v58, v58
	v_exp_f32_e32 v59, v59
	v_rcp_f32_e32 v62, v64
	v_pk_add_f32 v[58:59], v[58:59], 1.0 op_sel_hi:[1,0]
	s_waitcnt vmcnt(4)
	v_lshlrev_b32_e32 v60, 16, v74
	v_and_b32_e32 v61, 0xffff0000, v74
	v_mul_f32_e32 v54, v54, v90
	v_mul_f32_e32 v55, v55, v90
	v_rcp_f32_e32 v59, v59
	v_mul_f32_e32 v54, 0xbfb8aa3b, v54
	v_mul_f32_e32 v55, 0xbfb8aa3b, v55
	v_exp_f32_e32 v54, v54
	v_exp_f32_e32 v55, v55
	v_rcp_f32_e32 v58, v58
	v_lshlrev_b32_e32 v64, 16, v75
	v_and_b32_e32 v65, 0xffff0000, v75
	s_waitcnt vmcnt(2)
	v_lshlrev_b32_e32 v74, 16, v82
	v_and_b32_e32 v75, 0xffff0000, v82
	v_pk_fma_f32 v[62:63], v[62:63], v[60:61], v[74:75]
	v_pk_add_f32 v[54:55], v[54:55], 1.0 op_sel_hi:[1,0]
	v_lshlrev_b32_e32 v76, 16, v83
	v_and_b32_e32 v77, 0xffff0000, v83
	v_cvt_pk_bf16_f32 v60, v62, v63
	v_mul_f32_e32 v61, v63, v63
	v_pk_fma_f32 v[58:59], v[58:59], v[64:65], v[76:77]
	v_fmac_f32_e32 v61, v62, v62
	v_mul_f32_e32 v62, v59, v59
	v_fmac_f32_e32 v62, v58, v58
	v_add_f32_e32 v61, v61, v62
	v_mul_f32_e32 v56, v56, v90
	v_mul_f32_e32 v57, v57, v90
	v_rcp_f32_e32 v55, v55
	v_mul_f32_e32 v56, 0xbfb8aa3b, v56
	v_mul_f32_e32 v57, 0xbfb8aa3b, v57
	v_exp_f32_e32 v56, v56
	v_exp_f32_e32 v57, v57
	s_nop 0
	v_pk_add_f32 v[56:57], v[56:57], 1.0 op_sel_hi:[1,0]
	v_rcp_f32_e32 v54, v54
	v_lshlrev_b32_e32 v62, 16, v78
	v_and_b32_e32 v63, 0xffff0000, v78
	v_rcp_f32_e32 v57, v57
	v_mul_f32_e32 v50, v50, v90
	s_waitcnt vmcnt(1)
	v_lshlrev_b32_e32 v74, 16, v84
	v_and_b32_e32 v75, 0xffff0000, v84
	v_pk_fma_f32 v[54:55], v[54:55], v[62:63], v[74:75]
	global_load_dwordx2 v[62:63], v[70:71], off offset:288
	v_mul_f32_e32 v51, v51, v90
	v_mul_f32_e32 v50, 0xbfb8aa3b, v50
	v_mul_f32_e32 v51, 0xbfb8aa3b, v51
	v_exp_f32_e32 v50, v50
	v_exp_f32_e32 v51, v51
	v_rcp_f32_e32 v56, v56
	v_lshlrev_b32_e32 v64, 16, v79
	v_pk_add_f32 v[50:51], v[50:51], 1.0 op_sel_hi:[1,0]
	v_and_b32_e32 v65, 0xffff0000, v79
	v_lshlrev_b32_e32 v76, 16, v85
	v_and_b32_e32 v77, 0xffff0000, v85
	v_pk_fma_f32 v[56:57], v[56:57], v[64:65], v[76:77]
	v_mul_f32_e32 v64, v55, v55
	v_mul_f32_e32 v65, v57, v57
	v_fmac_f32_e32 v64, v54, v54
	v_fmac_f32_e32 v65, v56, v56
	v_add_f32_e32 v61, v80, v61
	v_add_f32_e32 v64, v64, v65
	v_add_f32_e32 v61, v61, v64
	v_mul_f32_e32 v52, v52, v90
	v_mul_f32_e32 v53, v53, v90
	v_mul_f32_e32 v52, 0xbfb8aa3b, v52
	v_mul_f32_e32 v53, 0xbfb8aa3b, v53
	v_rcp_f32_e32 v51, v51
	v_exp_f32_e32 v52, v52
	v_exp_f32_e32 v53, v53
	s_nop 0
	v_pk_add_f32 v[52:53], v[52:53], 1.0 op_sel_hi:[1,0]
	v_rcp_f32_e32 v50, v50
	s_waitcnt vmcnt(1)
	v_lshlrev_b32_e32 v64, 16, v72
	v_and_b32_e32 v65, 0xffff0000, v72
	v_rcp_f32_e32 v53, v53
	v_cvt_pk_bf16_f32 v54, v54, v55
	v_rcp_f32_e32 v52, v52
	v_lshlrev_b32_e32 v70, 16, v73
	v_and_b32_e32 v71, 0xffff0000, v73
	s_waitcnt vmcnt(0)
	v_lshlrev_b32_e32 v72, 16, v62
	v_and_b32_e32 v73, 0xffff0000, v62
	v_lshlrev_b32_e32 v62, 16, v63
	v_and_b32_e32 v63, 0xffff0000, v63
	v_pk_fma_f32 v[52:53], v[52:53], v[70:71], v[62:63]
	v_pk_fma_f32 v[62:63], v[50:51], v[64:65], v[72:73]
	v_mul_f32_e32 v51, v53, v53
	v_mul_f32_e32 v50, v63, v63
	v_fmac_f32_e32 v50, v62, v62
	v_fmac_f32_e32 v51, v52, v52
	v_add_f32_e32 v50, v50, v51
	v_add_f32_e32 v50, v61, v50
	ds_bpermute_b32 v51, v154, v50
	v_cvt_pk_bf16_f32 v55, v56, v57
	v_cvt_pk_bf16_f32 v61, v58, v59
	global_store_dwordx2 v[68:69], v[54:55], off offset:256
	v_cvt_pk_bf16_f32 v54, v62, v63
	s_waitcnt lgkmcnt(0)
	v_add_f32_e32 v50, v50, v51
	ds_bpermute_b32 v51, v155, v50
	v_cvt_pk_bf16_f32 v55, v52, v53
	global_store_dwordx2 v[68:69], v[86:87], off
	global_store_dwordx2 v[68:69], v[60:61], off offset:32
	global_store_dwordx2 v[68:69], v[54:55], off offset:288
	s_and_saveexec_b64 s[4:5], s[0:1]
	s_cbranch_execz .LBB0_1433
	v_lshl_add_u64 v[52:53], v[66:67], 2, s[12:13]
	s_waitcnt lgkmcnt(0)
	v_add_f32_e32 v50, v50, v51
	global_atomic_add_f32 v[52:53], v50, off
; DI unsigned pk2(float lo, float hi) { f32x2 v = {lo, hi}; bf16x2_t b = __builtin_convertvector(v, bf16x2_t); return __builtin_bit_cast(unsigned, b); }
; DI float sigmoidf_(float x) { return 1.f / (1.f + __expf(-x)); }
;     DI void operator()(const f32x4 (&acc)[2][2][4][2], const Unit& u, int wr, int wc, int fr, int fq) const {
;     ...
;             for (int m = 0; m < 4; ++m) { const int row = row0 + ai * HALF + m * 16;
;                 const float* bp = (row < MP) ? base0 + (size_t)row * DM : base1 + (size_t)(row - MP) * DM;
;                 float r = 1.f; if (MODE == 1) r = __builtin_amdgcn_rsqf(ssin[row] * (1.f / DM) + EPS);
;                 float s = 0.f;
; #pragma unroll
;                 for (int bj = 0; bj < 2; ++bj)
; #pragma unroll
;                     for (int n = 0; n < 2; ++n) { const int col = col0 + bj * HALF + n * 16;
;                         f32x4 v = acc[ai][bj][m][n];
;                         if (MODE == 1) { const u32x2 pw = *(const u32x2*)(PP + (size_t)row * DM + col);
;                             v[0] = sigmoidf_(v[0] * r) * bflo(pw.x); v[1] = sigmoidf_(v[1] * r) * bfhi(pw.x); v[2] = sigmoidf_(v[2] * r) * bflo(pw.y); v[3] = sigmoidf_(v[3] * r) * bfhi(pw.y); }
;                         f32x4 h;
;                         if (baseb) { const u32x2 bw = *(const u32x2*)(baseb + (size_t)row * DM + col); h = (f32x4){bflo(bw.x), bfhi(bw.x), bflo(bw.y), bfhi(bw.y)} + v; }
;                         else h = *(const f32x4*)(bp + col) + v;
;                         if (H) *(f32x4*)(H + (size_t)row * DM + col) = h;
;                         if (XB) { u32x2 w; w.x = pk2(h[0], h[1]); w.y = pk2(h[2], h[3]); *(u32x2*)(XB + (size_t)row * DM + col) = w; }
;                         s += (h[0] * h[0] + h[1] * h[1]) + (h[2] * h[2] + h[3] * h[3]); }
;                 if (ssout) { s += __shfl_xor(s, 16); s += __shfl_xor(s, 32); if (fq == 0) atomicAdd(ssout + row, s); } }
.LBB0_1433:
	s_or_b64 exec, exec, s[4:5]
	v_add_u32_e32 v50, 0x90, v148
	s_waitcnt lgkmcnt(0)
	v_ashrrev_i32_e32 v51, 31, v50
	v_cmp_gt_i32_e32 vcc, s60, v148
	s_nop 1
	v_cndmask_b32_e32 v51, 0, v51, vcc
	v_lshl_add_u64 v[52:53], v[50:51], 2, s[16:17]
	global_load_dword v70, v[52:53], off
	v_lshlrev_b64 v[52:53], 11, v[50:51]
	v_lshl_add_u64 v[54:55], s[18:19], 0, v[52:53]
	v_lshl_add_u64 v[56:57], v[54:55], 0, v[146:147]
	v_lshl_add_u64 v[54:55], s[92:93], 0, v[52:53]
	v_lshl_add_u64 v[54:55], v[54:55], 0, v[146:147]
	global_load_dwordx2 v[60:61], v[56:57], off
	global_load_dwordx2 v[64:65], v[54:55], off
	global_load_dwordx2 v[58:59], v[56:57], off offset:32
	global_load_dwordx2 v[62:63], v[56:57], off offset:256
	global_load_dwordx2 v[66:67], v[54:55], off offset:32
	global_load_dwordx2 v[68:69], v[54:55], off offset:256
	s_nop 0
	global_load_dwordx2 v[56:57], v[56:57], off offset:288
	v_lshl_add_u64 v[52:53], s[14:15], 0, v[52:53]
	v_lshl_add_u64 v[52:53], v[52:53], 0, v[146:147]
	s_waitcnt vmcnt(7)
	v_fmamk_f32 v70, v70, 0x3a800000, v171
	v_rsq_f32_e32 v74, v70
	s_waitcnt vmcnt(6)
	v_lshlrev_b32_e32 v70, 16, v60
	v_mul_f32_e32 v46, v46, v74
	v_mul_f32_e32 v47, v47, v74
	v_mul_f32_e32 v42, v42, v74
	v_mul_f32_e32 v43, v43, v74
	v_mul_f32_e32 v46, 0xbfb8aa3b, v46
	v_mul_f32_e32 v47, 0xbfb8aa3b, v47
	v_mul_f32_e32 v75, 0xbfb8aa3b, v42
	v_mul_f32_e32 v76, 0xbfb8aa3b, v43
	v_exp_f32_e32 v42, v46
	v_exp_f32_e32 v43, v47
	v_mul_f32_e32 v48, v48, v74
	v_mul_f32_e32 v49, v49, v74
	v_mul_f32_e32 v48, 0xbfb8aa3b, v48
	v_mul_f32_e32 v49, 0xbfb8aa3b, v49
	v_exp_f32_e32 v46, v48
	v_exp_f32_e32 v47, v49
	v_pk_add_f32 v[42:43], v[42:43], 1.0 op_sel_hi:[1,0]
	v_exp_f32_e32 v48, v75
	v_pk_add_f32 v[46:47], v[46:47], 1.0 op_sel_hi:[1,0]
	v_exp_f32_e32 v49, v76
	v_rcp_f32_e32 v43, v43
	v_and_b32_e32 v71, 0xffff0000, v60
	s_waitcnt vmcnt(5)
	v_lshlrev_b32_e32 v72, 16, v64
	v_and_b32_e32 v73, 0xffff0000, v64
	v_rcp_f32_e32 v42, v42
	s_nop 0
	v_pk_fma_f32 v[42:43], v[42:43], v[70:71], v[72:73]
	v_pk_add_f32 v[48:49], v[48:49], 1.0 op_sel_hi:[1,0]
	v_rcp_f32_e32 v47, v47
	v_cvt_pk_bf16_f32 v70, v42, v43
	v_mul_f32_e32 v43, v43, v43
	v_lshlrev_b32_e32 v60, 16, v61
	v_and_b32_e32 v61, 0xffff0000, v61
	v_lshlrev_b32_e32 v64, 16, v65
	v_and_b32_e32 v65, 0xffff0000, v65
	v_rcp_f32_e32 v46, v46
	v_fmac_f32_e32 v43, v42, v42
	v_pk_fma_f32 v[46:47], v[46:47], v[60:61], v[64:65]
	v_cvt_pk_bf16_f32 v71, v46, v47
	v_mul_f32_e32 v47, v47, v47
	v_fmac_f32_e32 v47, v46, v46
	v_add_f32_e32 v64, v43, v47
	v_rcp_f32_e32 v47, v49
	v_mul_f32_e32 v42, v44, v74
	v_mul_f32_e32 v43, v45, v74
	v_mul_f32_e32 v42, 0xbfb8aa3b, v42
	v_mul_f32_e32 v43, 0xbfb8aa3b, v43
	v_exp_f32_e32 v42, v42
	v_exp_f32_e32 v43, v43
	v_rcp_f32_e32 v46, v48
	v_pk_add_f32 v[42:43], v[42:43], 1.0 op_sel_hi:[1,0]
	s_waitcnt vmcnt(4)
	v_lshlrev_b32_e32 v44, 16, v58
	v_and_b32_e32 v45, 0xffff0000, v58
	v_mul_f32_e32 v38, v38, v74
	v_mul_f32_e32 v39, v39, v74
	v_rcp_f32_e32 v43, v43
	v_mul_f32_e32 v38, 0xbfb8aa3b, v38
	v_mul_f32_e32 v39, 0xbfb8aa3b, v39
	v_exp_f32_e32 v38, v38
	v_exp_f32_e32 v39, v39
	v_rcp_f32_e32 v42, v42
	v_lshlrev_b32_e32 v48, 16, v59
	v_and_b32_e32 v49, 0xffff0000, v59
	s_waitcnt vmcnt(2)
	v_lshlrev_b32_e32 v58, 16, v66
	v_and_b32_e32 v59, 0xffff0000, v66
	v_pk_fma_f32 v[46:47], v[46:47], v[44:45], v[58:59]
	v_pk_add_f32 v[38:39], v[38:39], 1.0 op_sel_hi:[1,0]
	v_lshlrev_b32_e32 v60, 16, v67
	v_and_b32_e32 v61, 0xffff0000, v67
	v_cvt_pk_bf16_f32 v44, v46, v47
	v_mul_f32_e32 v45, v47, v47
	v_pk_fma_f32 v[42:43], v[42:43], v[48:49], v[60:61]
	v_fmac_f32_e32 v45, v46, v46
	v_mul_f32_e32 v46, v43, v43
	v_fmac_f32_e32 v46, v42, v42
	v_add_f32_e32 v45, v45, v46
	v_mul_f32_e32 v40, v40, v74
	v_mul_f32_e32 v41, v41, v74
	v_rcp_f32_e32 v39, v39
	v_mul_f32_e32 v40, 0xbfb8aa3b, v40
	v_mul_f32_e32 v41, 0xbfb8aa3b, v41
	v_exp_f32_e32 v40, v40
	v_exp_f32_e32 v41, v41
	s_nop 0
	v_pk_add_f32 v[40:41], v[40:41], 1.0 op_sel_hi:[1,0]
	v_rcp_f32_e32 v38, v38
	v_lshlrev_b32_e32 v46, 16, v62
	v_and_b32_e32 v47, 0xffff0000, v62
	v_rcp_f32_e32 v41, v41
	v_mul_f32_e32 v34, v34, v74
	s_waitcnt vmcnt(1)
	v_lshlrev_b32_e32 v58, 16, v68
	v_and_b32_e32 v59, 0xffff0000, v68
	v_pk_fma_f32 v[38:39], v[38:39], v[46:47], v[58:59]
	global_load_dwordx2 v[46:47], v[54:55], off offset:288
	v_mul_f32_e32 v35, v35, v74
	v_mul_f32_e32 v34, 0xbfb8aa3b, v34
	v_mul_f32_e32 v35, 0xbfb8aa3b, v35
	v_exp_f32_e32 v34, v34
	v_exp_f32_e32 v35, v35
	v_rcp_f32_e32 v40, v40
	v_lshlrev_b32_e32 v48, 16, v63
	v_pk_add_f32 v[34:35], v[34:35], 1.0 op_sel_hi:[1,0]
	v_and_b32_e32 v49, 0xffff0000, v63
	v_lshlrev_b32_e32 v60, 16, v69
	v_and_b32_e32 v61, 0xffff0000, v69
	v_pk_fma_f32 v[40:41], v[40:41], v[48:49], v[60:61]
	v_mul_f32_e32 v48, v39, v39
	v_mul_f32_e32 v49, v41, v41
	v_fmac_f32_e32 v48, v38, v38
	v_fmac_f32_e32 v49, v40, v40
	v_add_f32_e32 v45, v64, v45
	v_add_f32_e32 v48, v48, v49
	v_add_f32_e32 v45, v45, v48
	v_mul_f32_e32 v36, v36, v74
	v_mul_f32_e32 v37, v37, v74
	v_mul_f32_e32 v36, 0xbfb8aa3b, v36
	v_mul_f32_e32 v37, 0xbfb8aa3b, v37
	v_rcp_f32_e32 v35, v35
	v_exp_f32_e32 v36, v36
	v_exp_f32_e32 v37, v37
	s_nop 0
	v_pk_add_f32 v[36:37], v[36:37], 1.0 op_sel_hi:[1,0]
	v_rcp_f32_e32 v34, v34
	s_waitcnt vmcnt(1)
	v_lshlrev_b32_e32 v48, 16, v56
	v_and_b32_e32 v49, 0xffff0000, v56
	v_rcp_f32_e32 v37, v37
	v_cvt_pk_bf16_f32 v38, v38, v39
	v_rcp_f32_e32 v36, v36
	v_lshlrev_b32_e32 v54, 16, v57
	v_and_b32_e32 v55, 0xffff0000, v57
	s_waitcnt vmcnt(0)
	v_lshlrev_b32_e32 v56, 16, v46
	v_and_b32_e32 v57, 0xffff0000, v46
	v_lshlrev_b32_e32 v46, 16, v47
	v_and_b32_e32 v47, 0xffff0000, v47
	v_pk_fma_f32 v[36:37], v[36:37], v[54:55], v[46:47]
	v_pk_fma_f32 v[46:47], v[34:35], v[48:49], v[56:57]
	v_mul_f32_e32 v35, v37, v37
	v_mul_f32_e32 v34, v47, v47
	v_fmac_f32_e32 v34, v46, v46
	v_fmac_f32_e32 v35, v36, v36
	v_add_f32_e32 v34, v34, v35
	v_add_f32_e32 v34, v45, v34
	ds_bpermute_b32 v35, v154, v34
	v_cvt_pk_bf16_f32 v39, v40, v41
	v_cvt_pk_bf16_f32 v45, v42, v43
	global_store_dwordx2 v[52:53], v[38:39], off offset:256
	v_cvt_pk_bf16_f32 v38, v46, v47
	s_waitcnt lgkmcnt(0)
	v_add_f32_e32 v34, v34, v35
	ds_bpermute_b32 v35, v155, v34
	v_cvt_pk_bf16_f32 v39, v36, v37
	global_store_dwordx2 v[52:53], v[70:71], off
	global_store_dwordx2 v[52:53], v[44:45], off offset:32
	global_store_dwordx2 v[52:53], v[38:39], off offset:288
	s_and_saveexec_b64 s[4:5], s[0:1]
	s_cbranch_execz .LBB0_1435
	v_lshl_add_u64 v[36:37], v[50:51], 2, s[12:13]
	s_waitcnt lgkmcnt(0)
	v_add_f32_e32 v34, v34, v35
	global_atomic_add_f32 v[36:37], v34, off
; DI unsigned pk2(float lo, float hi) { f32x2 v = {lo, hi}; bf16x2_t b = __builtin_convertvector(v, bf16x2_t); return __builtin_bit_cast(unsigned, b); }
; DI float sigmoidf_(float x) { return 1.f / (1.f + __expf(-x)); }
;     DI void operator()(const f32x4 (&acc)[2][2][4][2], const Unit& u, int wr, int wc, int fr, int fq) const {
;     ...
;             for (int m = 0; m < 4; ++m) { const int row = row0 + ai * HALF + m * 16;
;                 const float* bp = (row < MP) ? base0 + (size_t)row * DM : base1 + (size_t)(row - MP) * DM;
;                 float r = 1.f; if (MODE == 1) r = __builtin_amdgcn_rsqf(ssin[row] * (1.f / DM) + EPS);
;                 float s = 0.f;
; #pragma unroll
;                 for (int bj = 0; bj < 2; ++bj)
; #pragma unroll
;                     for (int n = 0; n < 2; ++n) { const int col = col0 + bj * HALF + n * 16;
;                         f32x4 v = acc[ai][bj][m][n];
;                         if (MODE == 1) { const u32x2 pw = *(const u32x2*)(PP + (size_t)row * DM + col);
;                             v[0] = sigmoidf_(v[0] * r) * bflo(pw.x); v[1] = sigmoidf_(v[1] * r) * bfhi(pw.x); v[2] = sigmoidf_(v[2] * r) * bflo(pw.y); v[3] = sigmoidf_(v[3] * r) * bfhi(pw.y); }
;                         f32x4 h;
;                         if (baseb) { const u32x2 bw = *(const u32x2*)(baseb + (size_t)row * DM + col); h = (f32x4){bflo(bw.x), bfhi(bw.x), bflo(bw.y), bfhi(bw.y)} + v; }
;                         else h = *(const f32x4*)(bp + col) + v;
;                         if (H) *(f32x4*)(H + (size_t)row * DM + col) = h;
;                         if (XB) { u32x2 w; w.x = pk2(h[0], h[1]); w.y = pk2(h[2], h[3]); *(u32x2*)(XB + (size_t)row * DM + col) = w; }
;                         s += (h[0] * h[0] + h[1] * h[1]) + (h[2] * h[2] + h[3] * h[3]); }
;                 if (ssout) { s += __shfl_xor(s, 16); s += __shfl_xor(s, 32); if (fq == 0) atomicAdd(ssout + row, s); } }
.LBB0_1435:
	s_or_b64 exec, exec, s[4:5]
	v_add_u32_e32 v34, 0xa0, v148
	s_waitcnt lgkmcnt(0)
	v_ashrrev_i32_e32 v35, 31, v34
	v_cmp_gt_i32_e32 vcc, s61, v148
	s_nop 1
	v_cndmask_b32_e32 v35, 0, v35, vcc
	v_lshl_add_u64 v[36:37], v[34:35], 2, s[16:17]
	global_load_dword v54, v[36:37], off
	v_lshlrev_b64 v[36:37], 11, v[34:35]
	v_lshl_add_u64 v[38:39], s[18:19], 0, v[36:37]
	v_lshl_add_u64 v[40:41], v[38:39], 0, v[146:147]
	v_lshl_add_u64 v[38:39], s[92:93], 0, v[36:37]
	v_lshl_add_u64 v[38:39], v[38:39], 0, v[146:147]
	global_load_dwordx2 v[44:45], v[40:41], off
	global_load_dwordx2 v[48:49], v[38:39], off
	global_load_dwordx2 v[42:43], v[40:41], off offset:32
	global_load_dwordx2 v[46:47], v[40:41], off offset:256
	global_load_dwordx2 v[50:51], v[38:39], off offset:32
	global_load_dwordx2 v[52:53], v[38:39], off offset:256
	s_nop 0
	global_load_dwordx2 v[40:41], v[40:41], off offset:288
	v_lshl_add_u64 v[36:37], s[14:15], 0, v[36:37]
	v_lshl_add_u64 v[36:37], v[36:37], 0, v[146:147]
	s_waitcnt vmcnt(7)
	v_fmamk_f32 v54, v54, 0x3a800000, v171
	v_rsq_f32_e32 v58, v54
	s_waitcnt vmcnt(6)
	v_lshlrev_b32_e32 v54, 16, v44
	v_mul_f32_e32 v30, v30, v58
	v_mul_f32_e32 v31, v31, v58
	v_mul_f32_e32 v26, v26, v58
	v_mul_f32_e32 v27, v27, v58
	v_mul_f32_e32 v30, 0xbfb8aa3b, v30
	v_mul_f32_e32 v31, 0xbfb8aa3b, v31
	v_mul_f32_e32 v59, 0xbfb8aa3b, v26
	v_mul_f32_e32 v60, 0xbfb8aa3b, v27
	v_exp_f32_e32 v26, v30
	v_exp_f32_e32 v27, v31
	v_mul_f32_e32 v32, v32, v58
	v_mul_f32_e32 v33, v33, v58
	v_mul_f32_e32 v32, 0xbfb8aa3b, v32
	v_mul_f32_e32 v33, 0xbfb8aa3b, v33
	v_exp_f32_e32 v30, v32
	v_exp_f32_e32 v31, v33
	v_pk_add_f32 v[26:27], v[26:27], 1.0 op_sel_hi:[1,0]
	v_exp_f32_e32 v32, v59
	v_pk_add_f32 v[30:31], v[30:31], 1.0 op_sel_hi:[1,0]
	v_exp_f32_e32 v33, v60
	v_rcp_f32_e32 v27, v27
	v_and_b32_e32 v55, 0xffff0000, v44
	s_waitcnt vmcnt(5)
	v_lshlrev_b32_e32 v56, 16, v48
	v_and_b32_e32 v57, 0xffff0000, v48
	v_rcp_f32_e32 v26, v26
	s_nop 0
	v_pk_fma_f32 v[26:27], v[26:27], v[54:55], v[56:57]
	v_pk_add_f32 v[32:33], v[32:33], 1.0 op_sel_hi:[1,0]
	v_rcp_f32_e32 v31, v31
	v_cvt_pk_bf16_f32 v54, v26, v27
	v_mul_f32_e32 v27, v27, v27
	v_lshlrev_b32_e32 v44, 16, v45
	v_and_b32_e32 v45, 0xffff0000, v45
	v_lshlrev_b32_e32 v48, 16, v49
	v_and_b32_e32 v49, 0xffff0000, v49
	v_rcp_f32_e32 v30, v30
	v_fmac_f32_e32 v27, v26, v26
	v_pk_fma_f32 v[30:31], v[30:31], v[44:45], v[48:49]
	v_cvt_pk_bf16_f32 v55, v30, v31
	v_mul_f32_e32 v31, v31, v31
	v_fmac_f32_e32 v31, v30, v30
	v_add_f32_e32 v48, v27, v31
	v_rcp_f32_e32 v31, v33
	v_mul_f32_e32 v26, v28, v58
	v_mul_f32_e32 v27, v29, v58
	v_mul_f32_e32 v26, 0xbfb8aa3b, v26
	v_mul_f32_e32 v27, 0xbfb8aa3b, v27
	v_exp_f32_e32 v26, v26
	v_exp_f32_e32 v27, v27
	v_rcp_f32_e32 v30, v32
	v_pk_add_f32 v[26:27], v[26:27], 1.0 op_sel_hi:[1,0]
	s_waitcnt vmcnt(4)
	v_lshlrev_b32_e32 v28, 16, v42
	v_and_b32_e32 v29, 0xffff0000, v42
	v_mul_f32_e32 v22, v22, v58
	v_mul_f32_e32 v23, v23, v58
	v_rcp_f32_e32 v27, v27
	v_mul_f32_e32 v22, 0xbfb8aa3b, v22
	v_mul_f32_e32 v23, 0xbfb8aa3b, v23
	v_exp_f32_e32 v22, v22
	v_exp_f32_e32 v23, v23
	v_rcp_f32_e32 v26, v26
	v_lshlrev_b32_e32 v32, 16, v43
	v_and_b32_e32 v33, 0xffff0000, v43
	s_waitcnt vmcnt(2)
	v_lshlrev_b32_e32 v42, 16, v50
	v_and_b32_e32 v43, 0xffff0000, v50
	v_pk_fma_f32 v[30:31], v[30:31], v[28:29], v[42:43]
	v_pk_add_f32 v[22:23], v[22:23], 1.0 op_sel_hi:[1,0]
	v_lshlrev_b32_e32 v44, 16, v51
	v_and_b32_e32 v45, 0xffff0000, v51
	v_cvt_pk_bf16_f32 v28, v30, v31
	v_mul_f32_e32 v29, v31, v31
	v_pk_fma_f32 v[26:27], v[26:27], v[32:33], v[44:45]
	v_fmac_f32_e32 v29, v30, v30
	v_mul_f32_e32 v30, v27, v27
	v_fmac_f32_e32 v30, v26, v26
	v_add_f32_e32 v29, v29, v30
	v_mul_f32_e32 v24, v24, v58
	v_mul_f32_e32 v25, v25, v58
	v_rcp_f32_e32 v23, v23
	v_mul_f32_e32 v24, 0xbfb8aa3b, v24
	v_mul_f32_e32 v25, 0xbfb8aa3b, v25
	v_exp_f32_e32 v24, v24
	v_exp_f32_e32 v25, v25
	s_nop 0
	v_pk_add_f32 v[24:25], v[24:25], 1.0 op_sel_hi:[1,0]
	v_rcp_f32_e32 v22, v22
	v_lshlrev_b32_e32 v30, 16, v46
	v_and_b32_e32 v31, 0xffff0000, v46
	v_rcp_f32_e32 v25, v25
	v_mul_f32_e32 v18, v18, v58
	s_waitcnt vmcnt(1)
	v_lshlrev_b32_e32 v42, 16, v52
	v_and_b32_e32 v43, 0xffff0000, v52
	v_pk_fma_f32 v[22:23], v[22:23], v[30:31], v[42:43]
	global_load_dwordx2 v[30:31], v[38:39], off offset:288
	v_mul_f32_e32 v19, v19, v58
	v_mul_f32_e32 v18, 0xbfb8aa3b, v18
	v_mul_f32_e32 v19, 0xbfb8aa3b, v19
	v_exp_f32_e32 v18, v18
	v_exp_f32_e32 v19, v19
	v_rcp_f32_e32 v24, v24
	v_lshlrev_b32_e32 v32, 16, v47
	v_pk_add_f32 v[18:19], v[18:19], 1.0 op_sel_hi:[1,0]
	v_and_b32_e32 v33, 0xffff0000, v47
	v_lshlrev_b32_e32 v44, 16, v53
	v_and_b32_e32 v45, 0xffff0000, v53
	v_pk_fma_f32 v[24:25], v[24:25], v[32:33], v[44:45]
	v_mul_f32_e32 v32, v23, v23
	v_mul_f32_e32 v33, v25, v25
	v_fmac_f32_e32 v32, v22, v22
	v_fmac_f32_e32 v33, v24, v24
	v_add_f32_e32 v29, v48, v29
	v_add_f32_e32 v32, v32, v33
	v_add_f32_e32 v29, v29, v32
	v_mul_f32_e32 v20, v20, v58
	v_mul_f32_e32 v21, v21, v58
	v_mul_f32_e32 v20, 0xbfb8aa3b, v20
	v_mul_f32_e32 v21, 0xbfb8aa3b, v21
	v_rcp_f32_e32 v19, v19
	v_exp_f32_e32 v20, v20
	v_exp_f32_e32 v21, v21
	s_nop 0
	v_pk_add_f32 v[20:21], v[20:21], 1.0 op_sel_hi:[1,0]
	v_rcp_f32_e32 v18, v18
	s_waitcnt vmcnt(1)
	v_lshlrev_b32_e32 v32, 16, v40
	v_and_b32_e32 v33, 0xffff0000, v40
	v_rcp_f32_e32 v21, v21
	v_cvt_pk_bf16_f32 v22, v22, v23
	v_rcp_f32_e32 v20, v20
	v_lshlrev_b32_e32 v38, 16, v41
	v_and_b32_e32 v39, 0xffff0000, v41
	s_waitcnt vmcnt(0)
	v_lshlrev_b32_e32 v40, 16, v30
	v_and_b32_e32 v41, 0xffff0000, v30
	v_lshlrev_b32_e32 v30, 16, v31
	v_and_b32_e32 v31, 0xffff0000, v31
	v_pk_fma_f32 v[20:21], v[20:21], v[38:39], v[30:31]
	v_pk_fma_f32 v[30:31], v[18:19], v[32:33], v[40:41]
	v_mul_f32_e32 v19, v21, v21
	v_mul_f32_e32 v18, v31, v31
	v_fmac_f32_e32 v18, v30, v30
	v_fmac_f32_e32 v19, v20, v20
	v_add_f32_e32 v18, v18, v19
	v_add_f32_e32 v18, v29, v18
	ds_bpermute_b32 v19, v154, v18
	v_cvt_pk_bf16_f32 v23, v24, v25
	v_cvt_pk_bf16_f32 v29, v26, v27
	global_store_dwordx2 v[36:37], v[22:23], off offset:256
	v_cvt_pk_bf16_f32 v22, v30, v31
	s_waitcnt lgkmcnt(0)
	v_add_f32_e32 v18, v18, v19
	ds_bpermute_b32 v19, v155, v18
	v_cvt_pk_bf16_f32 v23, v20, v21
	global_store_dwordx2 v[36:37], v[54:55], off
	global_store_dwordx2 v[36:37], v[28:29], off offset:32
	global_store_dwordx2 v[36:37], v[22:23], off offset:288
	s_and_saveexec_b64 s[4:5], s[0:1]
	s_cbranch_execz .LBB0_1437
	v_lshl_add_u64 v[20:21], v[34:35], 2, s[12:13]
	s_waitcnt lgkmcnt(0)
	v_add_f32_e32 v18, v18, v19
	global_atomic_add_f32 v[20:21], v18, off

; #define LAS __attribute__((address_space(3)))
; DI unsigned pk2(float lo, float hi) { f32x2 v = {lo, hi}; bf16x2_t b = __builtin_convertvector(v, bf16x2_t); return __builtin_bit_cast(unsigned, b); }
; DI float sigmoidf_(float x) { return 1.f / (1.f + __expf(-x)); }
;     DI void operator()(LAS unsigned char*, int row, int tn, int ni, int fq, f32x4 v, int) const {
;         const int grow = MP + row, col = tn * 32 + 16 * ni + 4 * fq;
;         if (MODE == 1) { const float r = __builtin_amdgcn_rsqf(ssin[grow] * (1.f / DM) + EPS); const u32x2 pw = *(const u32x2*)(PP + (size_t)grow * DM + col);
;             v[0] = sigmoidf_(v[0] * r) * bflo(pw.x); v[1] = sigmoidf_(v[1] * r) * bfhi(pw.x); v[2] = sigmoidf_(v[2] * r) * bflo(pw.y); v[3] = sigmoidf_(v[3] * r) * bfhi(pw.y); }
;         f32x4 h;
;         if (baseb) { const u32x2 bw = *(const u32x2*)(baseb + (size_t)grow * DM + col); h = (f32x4){bflo(bw.x), bfhi(bw.x), bflo(bw.y), bfhi(bw.y)} + v; }
;         else h = *(const f32x4*)(basef + (size_t)row * DM + col) + v;
;         if (H) *(f32x4*)(H + (size_t)grow * DM + col) = h;
;         if (XB) { u32x2 w; w.x = pk2(h[0], h[1]); w.y = pk2(h[2], h[3]); *(u32x2*)(XB + (size_t)grow * DM + col) = w; }
;         if (ssout) { float s = (h[0] * h[0] + h[1] * h[1]) + (h[2] * h[2] + h[3] * h[3]); s += __shfl_xor(s, 16); s += __shfl_xor(s, 32); if (fq == 0) atomicAdd(ssout + grow, s); }
;     }
.LBB0_1458:
	v_or_b32_e32 v6, s4, v28
	v_lshlrev_b32_e32 v14, 2, v6
	global_load_dword v15, v14, s[16:17]
	v_add_u32_e32 v16, s5, v23
	v_lshlrev_b32_e32 v6, 11, v6
	v_ashrrev_i32_e32 v17, 31, v16
	v_lshl_add_u64 v[18:19], s[18:19], 0, v[6:7]
	v_lshlrev_b64 v[16:17], 1, v[16:17]
	v_lshl_add_u64 v[36:37], s[92:93], 0, v[6:7]
	v_lshl_add_u64 v[18:19], v[18:19], 0, v[16:17]
	v_lshl_add_u64 v[36:37], v[36:37], 0, v[16:17]
	global_load_dwordx2 v[18:19], v[18:19], off
	v_and_b32_e32 v39, 64, v35
	global_load_dwordx2 v[36:37], v[36:37], off
	v_xor_b32_e32 v38, 16, v35
	v_add_u32_e32 v42, 64, v39
	v_cmp_lt_i32_e32 vcc, v38, v42
	s_waitcnt vmcnt(0)
	v_fmamk_f32 v15, v15, 0x3a800000, v34
	v_rsq_f32_e32 v15, v15
	v_cndmask_b32_e32 v38, v35, v38, vcc
	v_lshlrev_b32_e32 v43, 2, v38
	v_mul_f32_e32 v2, v2, v15
	v_mul_f32_e32 v3, v3, v15
	v_mul_f32_e32 v2, 0xbfb8aa3b, v2
	v_mul_f32_e32 v3, 0xbfb8aa3b, v3
	v_mul_f32_e32 v4, v4, v15
	v_mul_f32_e32 v5, v5, v15
	v_exp_f32_e32 v2, v2
	v_exp_f32_e32 v3, v3
	v_mul_f32_e32 v4, 0xbfb8aa3b, v4
	v_mul_f32_e32 v5, 0xbfb8aa3b, v5
	v_exp_f32_e32 v4, v4
	v_exp_f32_e32 v5, v5
	v_pk_add_f32 v[2:3], v[2:3], 1.0 op_sel_hi:[1,0]
	v_lshlrev_b32_e32 v38, 16, v18
	v_pk_add_f32 v[4:5], v[4:5], 1.0 op_sel_hi:[1,0]
	v_div_scale_f32 v47, s[4:5], v5, v5, 1.0
	v_rcp_f32_e32 v53, v47
	s_nop 0
	v_fma_f32 v57, -v47, v53, 1.0
	v_div_scale_f32 v48, s[4:5], 1.0, v5, 1.0
	v_fmac_f32_e32 v53, v57, v53
	v_div_scale_f32 v50, s[6:7], 1.0, v4, 1.0
	v_mul_f32_e32 v57, v48, v53
	v_fma_f32 v61, -v47, v57, v48
	v_fmac_f32_e32 v57, v61, v53
	v_fma_f32 v45, -v47, v57, v48
	v_rcp_f32_e32 v3, v3
	v_rcp_f32_e32 v2, v2
	v_rcp_f32_e32 v5, v5
	v_and_b32_e32 v39, 0xffff0000, v18
	v_lshlrev_b32_e32 v18, 16, v19
	v_and_b32_e32 v19, 0xffff0000, v19
	v_lshlrev_b32_e32 v40, 16, v36
	v_and_b32_e32 v41, 0xffff0000, v36
	v_lshlrev_b32_e32 v36, 16, v37
	v_and_b32_e32 v37, 0xffff0000, v37
	v_rcp_f32_e32 v4, v4
	v_pk_fma_f32 v[2:3], v[2:3], v[38:39], v[40:41]
	v_pk_fma_f32 v[4:5], v[4:5], v[18:19], v[36:37]
	v_mul_f32_e32 v15, v3, v3
	v_mul_f32_e32 v18, v5, v5
	v_fmac_f32_e32 v15, v2, v2
	v_fmac_f32_e32 v18, v4, v4
	v_add_f32_e32 v15, v15, v18
	ds_bpermute_b32 v19, v43, v15
	v_xor_b32_e32 v18, 32, v35
	v_cmp_lt_i32_e32 vcc, v18, v42
	s_nop 1
	v_cndmask_b32_e32 v36, v35, v18, vcc
	v_cvt_pk_bf16_f32 v18, v2, v3
	s_waitcnt lgkmcnt(0)
	v_add_f32_e32 v2, v15, v19
	v_lshlrev_b32_e32 v3, 2, v36
	ds_bpermute_b32 v3, v3, v2
	v_cvt_pk_bf16_f32 v19, v4, v5
	v_lshl_add_u64 v[4:5], s[14:15], 0, v[6:7]
	v_lshl_add_u64 v[4:5], v[4:5], 0, v[16:17]
	global_store_dwordx2 v[4:5], v[18:19], off
	s_and_saveexec_b64 s[2:3], s[0:1]
	s_cbranch_execz .LBB0_1445
	s_waitcnt lgkmcnt(0)
	v_add_f32_e32 v2, v2, v3
	global_atomic_add_f32 v14, v2, s[12:13]
	s_branch .LBB0_1445

; #define LAS __attribute__((address_space(3)))
; DI unsigned pk2(float lo, float hi) { f32x2 v = {lo, hi}; bf16x2_t b = __builtin_convertvector(v, bf16x2_t); return __builtin_bit_cast(unsigned, b); }
; DI float sigmoidf_(float x) { return 1.f / (1.f + __expf(-x)); }
;     DI void operator()(LAS unsigned char* lds, int row, int tn, int ni, int fq, f32x4 v, int tid) const {
;         LAS f32x4* X = (LAS f32x4*)(lds + 4 * SLOT);
;         const int lr = row & 63;
;         if (ni == 1) X[lr * 4 + fq] = v;
;         asm volatile("s_waitcnt lgkmcnt(0)\n\ts_barrier" ::: "memory");
;         if (ni == 0) { const f32x4 gt = X[lr * 4 + fq]; const int grow = MP + row, col = tn * 16 + 4 * fq;
;             const u32x2 bw = *(const u32x2*)(baseb + (size_t)grow * DM + col); f32x4 h = {bflo(bw.x), bfhi(bw.x), bflo(bw.y), bfhi(bw.y)};
; #pragma unroll
;             for (int j = 0; j < 4; ++j) h[j] += v[j] * sigmoidf_(gt[j]);
;             u32x2 w; w.x = pk2(h[0], h[1]); w.y = pk2(h[2], h[3]); *(u32x2*)(XB + (size_t)grow * DM + col) = w;
;             float s = (h[0] * h[0] + h[1] * h[1]) + (h[2] * h[2] + h[3] * h[3]); s += __shfl_xor(s, 16); s += __shfl_xor(s, 32); if (fq == 0) atomicAdd(ssout + grow, s); }
;     }
.LBB0_1793:
	s_waitcnt lgkmcnt(0)
	s_barrier
	s_andn2_b64 vcc, exec, s[0:1]
	s_cbranch_vccnz .LBB0_1778
	v_or_b32_e32 v14, s6, v28
	v_or_b32_e32 v16, s7, v23
	v_lshlrev_b32_e32 v6, 11, v14
	v_ashrrev_i32_e32 v17, 31, v16
	v_lshl_add_u64 v[18:19], s[14:15], 0, v[6:7]
	v_lshlrev_b64 v[36:37], 1, v[16:17]
	v_lshl_add_u64 v[16:17], v[18:19], 0, v[36:37]
	global_load_dwordx2 v[38:39], v[16:17], off
	ds_read_b128 v[16:19], v34
	v_and_b32_e32 v40, 64, v35
	v_add_u32_e32 v42, 64, v40
	v_xor_b32_e32 v15, 16, v35
	s_waitcnt lgkmcnt(0)
	v_mul_f32_e32 v16, 0xbfb8aa3b, v16
	v_mul_f32_e32 v17, 0xbfb8aa3b, v17
	v_exp_f32_e32 v16, v16
	v_exp_f32_e32 v17, v17
	v_mul_f32_e32 v18, 0xbfb8aa3b, v18
	v_mul_f32_e32 v19, 0xbfb8aa3b, v19
	v_exp_f32_e32 v18, v18
	v_exp_f32_e32 v19, v19
	v_pk_add_f32 v[16:17], v[16:17], 1.0 op_sel_hi:[1,0]
	v_pk_add_f32 v[18:19], v[18:19], 1.0 op_sel_hi:[1,0]
	v_rcp_f32_e32 v17, v17
	v_rcp_f32_e32 v16, v16
	v_rcp_f32_e32 v19, v19
	v_rcp_f32_e32 v18, v18
	v_cmp_lt_i32_e32 vcc, v15, v42
	s_waitcnt vmcnt(0)
	v_lshlrev_b32_e32 v40, 16, v38
	v_and_b32_e32 v41, 0xffff0000, v38
	v_lshlrev_b32_e32 v38, 16, v39
	v_and_b32_e32 v39, 0xffff0000, v39
	v_pk_fma_f32 v[2:3], v[2:3], v[16:17], v[40:41]
	v_pk_fma_f32 v[4:5], v[4:5], v[18:19], v[38:39]
	v_pk_mul_f32 v[16:17], v[2:3], v[2:3]
	v_pk_mul_f32 v[18:19], v[4:5], v[4:5]
	v_add_f32_e32 v16, v16, v17
	v_add_f32_e32 v18, v18, v19
	v_cndmask_b32_e32 v15, v35, v15, vcc
	v_add_f32_e32 v17, v16, v18
	v_lshlrev_b32_e32 v15, 2, v15
	ds_bpermute_b32 v15, v15, v17
	v_cvt_pk_bf16_f32 v16, v2, v3
	v_xor_b32_e32 v3, 32, v35
	v_cmp_lt_i32_e32 vcc, v3, v42
	s_waitcnt lgkmcnt(0)
	v_add_f32_e32 v2, v17, v15
	v_cndmask_b32_e32 v3, v35, v3, vcc
	v_lshlrev_b32_e32 v3, 2, v3
	ds_bpermute_b32 v3, v3, v2
	v_cvt_pk_bf16_f32 v17, v4, v5
	v_lshl_add_u64 v[4:5], s[92:93], 0, v[6:7]
	v_lshl_add_u64 v[4:5], v[4:5], 0, v[36:37]
	global_store_dwordx2 v[4:5], v[16:17], off
	s_and_saveexec_b64 s[4:5], s[2:3]
	s_cbranch_execz .LBB0_1777
	v_lshlrev_b32_e32 v4, 2, v14
	s_waitcnt lgkmcnt(0)
	v_add_f32_e32 v2, v2, v3
	global_atomic_add_f32 v4, v2, s[12:13]
	s_branch .LBB0_1777

; DI float sigmoidf_(float x) { return 1.f / (1.f + __expf(-x)); }
;     DI void operator()(const f32x4 (&acc)[2][2][4][2], const Unit& u, int wr, int wc, int fr, int fq) const {
;     ...
;             for (int m = 0; m < 4; ++m) { const int row = row0 + ai * HALF + m * 16;
;                 const float* bp = (row < MP) ? base0 + (size_t)row * DM : base1 + (size_t)(row - MP) * DM;
;                 float r = 1.f; if (MODE == 1) r = __builtin_amdgcn_rsqf(ssin[row] * (1.f / DM) + EPS);
;                 float s = 0.f;
; #pragma unroll
;                 for (int bj = 0; bj < 2; ++bj)
; #pragma unroll
;                     for (int n = 0; n < 2; ++n) { const int col = col0 + bj * HALF + n * 16;
;                         f32x4 v = acc[ai][bj][m][n];
;                         if (MODE == 1) { const u32x2 pw = *(const u32x2*)(PP + (size_t)row * DM + col);
;                             v[0] = sigmoidf_(v[0] * r) * bflo(pw.x); v[1] = sigmoidf_(v[1] * r) * bfhi(pw.x); v[2] = sigmoidf_(v[2] * r) * bflo(pw.y); v[3] = sigmoidf_(v[3] * r) * bfhi(pw.y); }
;                         f32x4 h;
;                         if (baseb) { const u32x2 bw = *(const u32x2*)(baseb + (size_t)row * DM + col); h = (f32x4){bflo(bw.x), bfhi(bw.x), bflo(bw.y), bfhi(bw.y)} + v; }
;                         else h = *(const f32x4*)(bp + col) + v;
;                         if (H) *(f32x4*)(H + (size_t)row * DM + col) = h;
.LBB0_2067:
	s_andn2_b64 vcc, exec, s[24:25]
	s_cbranch_vccnz .LBB0_2069
	v_lshl_add_u32 v150, s2, 8, v1
	v_ashrrev_i32_e32 v146, 31, v150
	v_cmp_gt_i32_e32 vcc, s45, v150
	v_lshl_or_b32 v148, s3, 8, v143
	v_ashrrev_i32_e32 v149, 31, v148
	v_cndmask_b32_e32 v151, 0, v146, vcc
	v_lshl_add_u64 v[146:147], v[150:151], 2, s[10:11]
	global_load_dword v166, v[146:147], off
	v_lshlrev_b64 v[152:153], 11, v[150:151]
	v_lshl_add_u64 v[154:155], s[12:13], 0, v[152:153]
	v_lshlrev_b64 v[146:147], 1, v[148:149]
	v_lshl_add_u64 v[152:153], s[14:15], 0, v[152:153]
	v_lshl_add_u64 v[156:157], v[154:155], 0, v[146:147]
	v_lshl_add_u64 v[154:155], v[152:153], 0, v[146:147]
	global_load_dwordx2 v[162:163], v[156:157], off
	global_load_dwordx2 v[164:165], v[154:155], off
	v_lshlrev_b64 v[152:153], 12, v[150:151]
	v_lshlrev_b64 v[148:149], 2, v[148:149]
	v_lshl_add_u64 v[152:153], s[48:49], 0, v[152:153]
	v_lshl_add_u64 v[152:153], v[152:153], 0, v[148:149]
	s_waitcnt vmcnt(0)
	v_fmamk_f32 v151, v166, 0x3a800000, v161
	v_rsq_f32_e32 v151, v151
	v_lshlrev_b32_e32 v166, 16, v162
	v_mul_f32_e32 v126, v126, v151
	v_mul_f32_e32 v127, v127, v151
	v_mul_f32_e32 v126, 0xbfb8aa3b, v126
	v_mul_f32_e32 v127, 0xbfb8aa3b, v127
	v_mul_f32_e32 v128, v128, v151
	v_mul_f32_e32 v129, v129, v151
	v_exp_f32_e32 v126, v126
	v_exp_f32_e32 v127, v127
	v_mul_f32_e32 v128, 0xbfb8aa3b, v128
	v_mul_f32_e32 v129, 0xbfb8aa3b, v129
	v_exp_f32_e32 v128, v128
	v_exp_f32_e32 v129, v129
	v_pk_add_f32 v[126:127], v[126:127], 1.0 op_sel_hi:[1,0]
	v_and_b32_e32 v167, 0xffff0000, v162
	v_pk_add_f32 v[128:129], v[128:129], 1.0 op_sel_hi:[1,0]
	v_rcp_f32_e32 v127, v127
	v_rcp_f32_e32 v126, v126
	v_rcp_f32_e32 v129, v129
	v_lshlrev_b32_e32 v162, 16, v163
	v_and_b32_e32 v163, 0xffff0000, v163
	v_lshlrev_b32_e32 v168, 16, v164
	v_and_b32_e32 v169, 0xffff0000, v164
	v_lshlrev_b32_e32 v164, 16, v165
	v_and_b32_e32 v165, 0xffff0000, v165
	v_rcp_f32_e32 v128, v128
	v_pk_fma_f32 v[126:127], v[126:127], v[166:167], v[168:169]
	v_pk_fma_f32 v[128:129], v[128:129], v[162:163], v[164:165]
	global_store_dwordx4 v[152:153], v[126:129], off
	global_load_dwordx2 v[126:127], v[156:157], off offset:32
	s_nop 0
	global_load_dwordx2 v[128:129], v[154:155], off offset:32
	v_mul_f32_e32 v122, v122, v151
	v_mul_f32_e32 v123, v123, v151
	v_mul_f32_e32 v122, 0xbfb8aa3b, v122
	v_mul_f32_e32 v123, 0xbfb8aa3b, v123
	v_mul_f32_e32 v124, v124, v151
	v_mul_f32_e32 v125, v125, v151
	v_exp_f32_e32 v122, v122
	v_exp_f32_e32 v123, v123
	v_mul_f32_e32 v124, 0xbfb8aa3b, v124
	v_mul_f32_e32 v125, 0xbfb8aa3b, v125
	v_exp_f32_e32 v124, v124
	v_exp_f32_e32 v125, v125
	v_pk_add_f32 v[122:123], v[122:123], 1.0 op_sel_hi:[1,0]
	v_mul_f32_e32 v118, v118, v151
	v_pk_add_f32 v[124:125], v[124:125], 1.0 op_sel_hi:[1,0]
	v_rcp_f32_e32 v123, v123
	v_rcp_f32_e32 v122, v122
	v_rcp_f32_e32 v125, v125
	v_rcp_f32_e32 v124, v124
	v_mul_f32_e32 v119, v119, v151
	v_mul_f32_e32 v118, 0xbfb8aa3b, v118
	v_mul_f32_e32 v119, 0xbfb8aa3b, v119
	v_mul_f32_e32 v120, v120, v151
	v_mul_f32_e32 v121, v121, v151
	v_exp_f32_e32 v118, v118
	v_exp_f32_e32 v119, v119
	v_mul_f32_e32 v120, 0xbfb8aa3b, v120
	s_waitcnt vmcnt(1)
	v_lshlrev_b32_e32 v162, 16, v126
	v_and_b32_e32 v163, 0xffff0000, v126
	v_lshlrev_b32_e32 v126, 16, v127
	v_and_b32_e32 v127, 0xffff0000, v127
	s_waitcnt vmcnt(0)
	v_lshlrev_b32_e32 v164, 16, v128
	v_and_b32_e32 v165, 0xffff0000, v128
	v_lshlrev_b32_e32 v128, 16, v129
	v_and_b32_e32 v129, 0xffff0000, v129
	v_pk_fma_f32 v[124:125], v[124:125], v[126:127], v[128:129]
	v_pk_fma_f32 v[122:123], v[122:123], v[162:163], v[164:165]
	global_store_dwordx4 v[152:153], v[122:125], off offset:64
	global_load_dwordx2 v[122:123], v[156:157], off offset:256
	s_nop 0
	global_load_dwordx2 v[124:125], v[154:155], off offset:256
	v_mul_f32_e32 v121, 0xbfb8aa3b, v121
	v_exp_f32_e32 v120, v120
	v_exp_f32_e32 v121, v121
	v_pk_add_f32 v[118:119], v[118:119], 1.0 op_sel_hi:[1,0]
	v_mul_f32_e32 v114, v114, v151
	v_pk_add_f32 v[120:121], v[120:121], 1.0 op_sel_hi:[1,0]
	v_rcp_f32_e32 v119, v119
	v_rcp_f32_e32 v118, v118
	v_rcp_f32_e32 v121, v121
	v_rcp_f32_e32 v120, v120
	v_mul_f32_e32 v115, v115, v151
	v_mul_f32_e32 v114, 0xbfb8aa3b, v114
	v_mul_f32_e32 v115, 0xbfb8aa3b, v115
	v_mul_f32_e32 v116, v116, v151
	v_mul_f32_e32 v117, v117, v151
	v_exp_f32_e32 v114, v114
	v_exp_f32_e32 v115, v115
	v_mul_f32_e32 v116, 0xbfb8aa3b, v116
	v_mul_f32_e32 v117, 0xbfb8aa3b, v117
	v_pk_add_f32 v[114:115], v[114:115], 1.0 op_sel_hi:[1,0]
	s_nop 0
	s_waitcnt vmcnt(1)
	v_lshlrev_b32_e32 v126, 16, v122
	v_and_b32_e32 v127, 0xffff0000, v122
	v_lshlrev_b32_e32 v122, 16, v123
	v_and_b32_e32 v123, 0xffff0000, v123
	s_waitcnt vmcnt(0)
	v_lshlrev_b32_e32 v128, 16, v124
	v_and_b32_e32 v129, 0xffff0000, v124
	v_lshlrev_b32_e32 v124, 16, v125
	v_and_b32_e32 v125, 0xffff0000, v125
	v_pk_fma_f32 v[120:121], v[120:121], v[122:123], v[124:125]
	v_pk_fma_f32 v[118:119], v[118:119], v[126:127], v[128:129]
	global_store_dwordx4 v[152:153], v[118:121], off offset:512
	global_load_dwordx2 v[118:119], v[156:157], off offset:288
	v_exp_f32_e32 v128, v116
	global_load_dwordx2 v[120:121], v[154:155], off offset:288
	v_exp_f32_e32 v129, v117
	s_nop 0
	v_pk_add_f32 v[128:129], v[128:129], 1.0 op_sel_hi:[1,0]
	v_or_b32_e32 v122, 16, v150
	v_ashrrev_i32_e32 v123, 31, v122
	v_cmp_gt_i32_e32 vcc, s45, v122
	s_nop 1
	v_cndmask_b32_e32 v123, 0, v123, vcc
	v_rcp_f32_e32 v115, v115
	v_rcp_f32_e32 v114, v114
	v_rcp_f32_e32 v129, v129
	v_rcp_f32_e32 v128, v128
	v_lshlrev_b64 v[124:125], 11, v[122:123]
	v_lshl_add_u64 v[126:127], v[122:123], 2, s[10:11]
	v_lshl_add_u64 v[116:117], s[12:13], 0, v[124:125]
	v_lshl_add_u64 v[116:117], v[116:117], 0, v[146:147]
	s_waitcnt vmcnt(1)
; DI float sigmoidf_(float x) { return 1.f / (1.f + __expf(-x)); }
;     DI void operator()(const f32x4 (&acc)[2][2][4][2], const Unit& u, int wr, int wc, int fr, int fq) const {
;     ...
;             for (int m = 0; m < 4; ++m) { const int row = row0 + ai * HALF + m * 16;
;                 const float* bp = (row < MP) ? base0 + (size_t)row * DM : base1 + (size_t)(row - MP) * DM;
;                 float r = 1.f; if (MODE == 1) r = __builtin_amdgcn_rsqf(ssin[row] * (1.f / DM) + EPS);
;                 float s = 0.f;
; #pragma unroll
;                 for (int bj = 0; bj < 2; ++bj)
; #pragma unroll
;                     for (int n = 0; n < 2; ++n) { const int col = col0 + bj * HALF + n * 16;
;                         f32x4 v = acc[ai][bj][m][n];
;                         if (MODE == 1) { const u32x2 pw = *(const u32x2*)(PP + (size_t)row * DM + col);
;                             v[0] = sigmoidf_(v[0] * r) * bflo(pw.x); v[1] = sigmoidf_(v[1] * r) * bfhi(pw.x); v[2] = sigmoidf_(v[2] * r) * bflo(pw.y); v[3] = sigmoidf_(v[3] * r) * bfhi(pw.y); }
;                         f32x4 h;
;                         if (baseb) { const u32x2 bw = *(const u32x2*)(baseb + (size_t)row * DM + col); h = (f32x4){bflo(bw.x), bfhi(bw.x), bflo(bw.y), bfhi(bw.y)} + v; }
;                         else h = *(const f32x4*)(bp + col) + v;
;                         if (H) *(f32x4*)(H + (size_t)row * DM + col) = h;
	v_lshlrev_b32_e32 v154, 16, v118
	v_and_b32_e32 v155, 0xffff0000, v118
	v_lshlrev_b32_e32 v118, 16, v119
	v_and_b32_e32 v119, 0xffff0000, v119
	s_waitcnt vmcnt(0)
	v_lshlrev_b32_e32 v156, 16, v120
	v_and_b32_e32 v157, 0xffff0000, v120
	v_lshlrev_b32_e32 v120, 16, v121
	v_and_b32_e32 v121, 0xffff0000, v121
	v_pk_fma_f32 v[120:121], v[128:129], v[118:119], v[120:121]
	v_pk_fma_f32 v[118:119], v[114:115], v[154:155], v[156:157]
	global_store_dwordx4 v[152:153], v[118:121], off offset:576
	global_load_dword v126, v[126:127], off
	s_nop 0
	global_load_dwordx2 v[120:121], v[116:117], off
	v_lshl_add_u64 v[114:115], s[14:15], 0, v[124:125]
	v_lshl_add_u64 v[118:119], v[114:115], 0, v[146:147]
	global_load_dwordx2 v[124:125], v[118:119], off
	v_lshlrev_b64 v[114:115], 12, v[122:123]
	v_lshl_add_u64 v[114:115], s[48:49], 0, v[114:115]
	v_lshl_add_u64 v[114:115], v[114:115], 0, v[148:149]
	s_waitcnt vmcnt(2)
	v_fmamk_f32 v127, v126, 0x3a800000, v161
	s_waitcnt vmcnt(1)
	v_lshlrev_b32_e32 v122, 16, v120
	v_and_b32_e32 v123, 0xffff0000, v120
	v_rsq_f32_e32 v120, v127
	v_lshlrev_b32_e32 v126, 16, v121
	v_and_b32_e32 v127, 0xffff0000, v121
	s_waitcnt vmcnt(0)
	v_lshlrev_b32_e32 v128, 16, v124
	v_mul_f32_e32 v110, v110, v120
	v_mul_f32_e32 v111, v111, v120
	v_mul_f32_e32 v110, 0xbfb8aa3b, v110
	v_mul_f32_e32 v111, 0xbfb8aa3b, v111
	v_mul_f32_e32 v112, v112, v120
	v_mul_f32_e32 v113, v113, v120
	v_exp_f32_e32 v110, v110
	v_exp_f32_e32 v111, v111
	v_mul_f32_e32 v112, 0xbfb8aa3b, v112
	v_mul_f32_e32 v113, 0xbfb8aa3b, v113
	v_exp_f32_e32 v112, v112
	v_exp_f32_e32 v113, v113
	v_pk_add_f32 v[110:111], v[110:111], 1.0 op_sel_hi:[1,0]
	v_and_b32_e32 v129, 0xffff0000, v124
	v_pk_add_f32 v[112:113], v[112:113], 1.0 op_sel_hi:[1,0]
	v_rcp_f32_e32 v111, v111
	v_rcp_f32_e32 v110, v110
	v_rcp_f32_e32 v113, v113
	v_lshlrev_b32_e32 v124, 16, v125
	v_and_b32_e32 v125, 0xffff0000, v125
	v_rcp_f32_e32 v112, v112
	v_pk_fma_f32 v[110:111], v[110:111], v[122:123], v[128:129]
	v_pk_fma_f32 v[112:113], v[112:113], v[126:127], v[124:125]
	global_store_dwordx4 v[114:115], v[110:113], off
	global_load_dwordx2 v[110:111], v[116:117], off offset:32
	s_nop 0
	global_load_dwordx2 v[112:113], v[118:119], off offset:32
	v_mul_f32_e32 v106, v106, v120
	v_mul_f32_e32 v107, v107, v120
	v_mul_f32_e32 v106, 0xbfb8aa3b, v106
	v_mul_f32_e32 v107, 0xbfb8aa3b, v107
	v_mul_f32_e32 v108, v108, v120
	v_mul_f32_e32 v109, v109, v120
	v_exp_f32_e32 v106, v106
	v_exp_f32_e32 v107, v107
	v_mul_f32_e32 v108, 0xbfb8aa3b, v108
	v_mul_f32_e32 v109, 0xbfb8aa3b, v109
	v_exp_f32_e32 v108, v108
	v_exp_f32_e32 v109, v109
	v_pk_add_f32 v[106:107], v[106:107], 1.0 op_sel_hi:[1,0]
	v_mul_f32_e32 v102, v102, v120
	v_pk_add_f32 v[108:109], v[108:109], 1.0 op_sel_hi:[1,0]
	v_rcp_f32_e32 v107, v107
	v_rcp_f32_e32 v106, v106
	v_rcp_f32_e32 v109, v109
	v_rcp_f32_e32 v108, v108
	v_mul_f32_e32 v103, v103, v120
	v_mul_f32_e32 v102, 0xbfb8aa3b, v102
	v_mul_f32_e32 v103, 0xbfb8aa3b, v103
	v_mul_f32_e32 v104, v104, v120
	v_mul_f32_e32 v105, v105, v120
	v_exp_f32_e32 v102, v102
	v_exp_f32_e32 v103, v103
	v_mul_f32_e32 v104, 0xbfb8aa3b, v104
	s_waitcnt vmcnt(1)
	v_lshlrev_b32_e32 v122, 16, v110
	v_and_b32_e32 v123, 0xffff0000, v110
	v_lshlrev_b32_e32 v110, 16, v111
	v_and_b32_e32 v111, 0xffff0000, v111
	s_waitcnt vmcnt(0)
	v_lshlrev_b32_e32 v124, 16, v112
	v_and_b32_e32 v125, 0xffff0000, v112
	v_lshlrev_b32_e32 v112, 16, v113
	v_and_b32_e32 v113, 0xffff0000, v113
	v_pk_fma_f32 v[108:109], v[108:109], v[110:111], v[112:113]
	v_pk_fma_f32 v[106:107], v[106:107], v[122:123], v[124:125]
	global_store_dwordx4 v[114:115], v[106:109], off offset:64
	global_load_dwordx2 v[106:107], v[116:117], off offset:256
	s_nop 0
	global_load_dwordx2 v[108:109], v[118:119], off offset:256
	v_mul_f32_e32 v105, 0xbfb8aa3b, v105
	v_exp_f32_e32 v104, v104
	v_exp_f32_e32 v105, v105
	v_pk_add_f32 v[102:103], v[102:103], 1.0 op_sel_hi:[1,0]
	v_mul_f32_e32 v98, v98, v120
	v_pk_add_f32 v[104:105], v[104:105], 1.0 op_sel_hi:[1,0]
	v_rcp_f32_e32 v103, v103
	v_rcp_f32_e32 v102, v102
	v_rcp_f32_e32 v105, v105
	v_rcp_f32_e32 v104, v104
	v_mul_f32_e32 v99, v99, v120
	v_mul_f32_e32 v98, 0xbfb8aa3b, v98
	v_mul_f32_e32 v99, 0xbfb8aa3b, v99
	v_mul_f32_e32 v100, v100, v120
	v_mul_f32_e32 v101, v101, v120
	v_exp_f32_e32 v98, v98
	v_exp_f32_e32 v99, v99
	v_mul_f32_e32 v100, 0xbfb8aa3b, v100
	v_mul_f32_e32 v101, 0xbfb8aa3b, v101
	v_pk_add_f32 v[98:99], v[98:99], 1.0 op_sel_hi:[1,0]
	s_waitcnt vmcnt(1)
	v_lshlrev_b32_e32 v110, 16, v106
	v_and_b32_e32 v111, 0xffff0000, v106
	v_lshlrev_b32_e32 v106, 16, v107
	v_and_b32_e32 v107, 0xffff0000, v107
	s_waitcnt vmcnt(0)
	v_lshlrev_b32_e32 v112, 16, v108
	v_and_b32_e32 v113, 0xffff0000, v108
	v_lshlrev_b32_e32 v108, 16, v109
	v_and_b32_e32 v109, 0xffff0000, v109
	v_pk_fma_f32 v[104:105], v[104:105], v[106:107], v[108:109]
	v_pk_fma_f32 v[102:103], v[102:103], v[110:111], v[112:113]
	global_store_dwordx4 v[114:115], v[102:105], off offset:512
	global_load_dwordx2 v[102:103], v[116:117], off offset:288
	v_exp_f32_e32 v112, v100
	global_load_dwordx2 v[104:105], v[118:119], off offset:288
	v_exp_f32_e32 v113, v101
	s_nop 0
	v_pk_add_f32 v[112:113], v[112:113], 1.0 op_sel_hi:[1,0]
	v_or_b32_e32 v106, 32, v150
	v_ashrrev_i32_e32 v107, 31, v106
	v_cmp_gt_i32_e32 vcc, s45, v106
	s_nop 1
	v_cndmask_b32_e32 v107, 0, v107, vcc
	v_rcp_f32_e32 v99, v99
	v_rcp_f32_e32 v98, v98
	v_rcp_f32_e32 v113, v113
	v_rcp_f32_e32 v112, v112
	v_lshlrev_b64 v[108:109], 11, v[106:107]
	v_lshl_add_u64 v[110:111], v[106:107], 2, s[10:11]
	v_lshl_add_u64 v[100:101], s[12:13], 0, v[108:109]
	v_lshl_add_u64 v[100:101], v[100:101], 0, v[146:147]
	s_waitcnt vmcnt(1)
; DI float sigmoidf_(float x) { return 1.f / (1.f + __expf(-x)); }
;     DI void operator()(const f32x4 (&acc)[2][2][4][2], const Unit& u, int wr, int wc, int fr, int fq) const {
;     ...
;             for (int m = 0; m < 4; ++m) { const int row = row0 + ai * HALF + m * 16;
;                 const float* bp = (row < MP) ? base0 + (size_t)row * DM : base1 + (size_t)(row - MP) * DM;
;                 float r = 1.f; if (MODE == 1) r = __builtin_amdgcn_rsqf(ssin[row] * (1.f / DM) + EPS);
;                 float s = 0.f;
; #pragma unroll
;                 for (int bj = 0; bj < 2; ++bj)
; #pragma unroll
;                     for (int n = 0; n < 2; ++n) { const int col = col0 + bj * HALF + n * 16;
;                         f32x4 v = acc[ai][bj][m][n];
;                         if (MODE == 1) { const u32x2 pw = *(const u32x2*)(PP + (size_t)row * DM + col);
;                             v[0] = sigmoidf_(v[0] * r) * bflo(pw.x); v[1] = sigmoidf_(v[1] * r) * bfhi(pw.x); v[2] = sigmoidf_(v[2] * r) * bflo(pw.y); v[3] = sigmoidf_(v[3] * r) * bfhi(pw.y); }
;                         f32x4 h;
;                         if (baseb) { const u32x2 bw = *(const u32x2*)(baseb + (size_t)row * DM + col); h = (f32x4){bflo(bw.x), bfhi(bw.x), bflo(bw.y), bfhi(bw.y)} + v; }
;                         else h = *(const f32x4*)(bp + col) + v;
;                         if (H) *(f32x4*)(H + (size_t)row * DM + col) = h;
	v_lshlrev_b32_e32 v116, 16, v102
	v_and_b32_e32 v117, 0xffff0000, v102
	v_lshlrev_b32_e32 v102, 16, v103
	v_and_b32_e32 v103, 0xffff0000, v103
	s_waitcnt vmcnt(0)
	v_lshlrev_b32_e32 v118, 16, v104
	v_and_b32_e32 v119, 0xffff0000, v104
	v_lshlrev_b32_e32 v104, 16, v105
	v_and_b32_e32 v105, 0xffff0000, v105
	v_pk_fma_f32 v[104:105], v[112:113], v[102:103], v[104:105]
	v_pk_fma_f32 v[102:103], v[98:99], v[116:117], v[118:119]
	global_store_dwordx4 v[114:115], v[102:105], off offset:576
	global_load_dword v110, v[110:111], off
	s_nop 0
	global_load_dwordx2 v[104:105], v[100:101], off
	v_lshl_add_u64 v[98:99], s[14:15], 0, v[108:109]
	v_lshl_add_u64 v[102:103], v[98:99], 0, v[146:147]
	global_load_dwordx2 v[108:109], v[102:103], off
	v_lshlrev_b64 v[98:99], 12, v[106:107]
	v_lshl_add_u64 v[98:99], s[48:49], 0, v[98:99]
	v_lshl_add_u64 v[98:99], v[98:99], 0, v[148:149]
	s_waitcnt vmcnt(2)
	v_fmamk_f32 v111, v110, 0x3a800000, v161
	s_waitcnt vmcnt(1)
	v_lshlrev_b32_e32 v106, 16, v104
	v_and_b32_e32 v107, 0xffff0000, v104
	v_rsq_f32_e32 v104, v111
	v_lshlrev_b32_e32 v110, 16, v105
	v_and_b32_e32 v111, 0xffff0000, v105
	s_waitcnt vmcnt(0)
	v_lshlrev_b32_e32 v112, 16, v108
	v_mul_f32_e32 v94, v94, v104
	v_mul_f32_e32 v95, v95, v104
	v_mul_f32_e32 v94, 0xbfb8aa3b, v94
	v_mul_f32_e32 v95, 0xbfb8aa3b, v95
	v_mul_f32_e32 v96, v96, v104
	v_mul_f32_e32 v97, v97, v104
	v_exp_f32_e32 v94, v94
	v_exp_f32_e32 v95, v95
	v_mul_f32_e32 v96, 0xbfb8aa3b, v96
	v_mul_f32_e32 v97, 0xbfb8aa3b, v97
	v_exp_f32_e32 v96, v96
	v_exp_f32_e32 v97, v97
	v_pk_add_f32 v[94:95], v[94:95], 1.0 op_sel_hi:[1,0]
	v_and_b32_e32 v113, 0xffff0000, v108
	v_pk_add_f32 v[96:97], v[96:97], 1.0 op_sel_hi:[1,0]
	v_rcp_f32_e32 v95, v95
	v_rcp_f32_e32 v94, v94
	v_rcp_f32_e32 v97, v97
	v_lshlrev_b32_e32 v108, 16, v109
	v_and_b32_e32 v109, 0xffff0000, v109
	v_rcp_f32_e32 v96, v96
	v_pk_fma_f32 v[94:95], v[94:95], v[106:107], v[112:113]
	v_pk_fma_f32 v[96:97], v[96:97], v[110:111], v[108:109]
	global_store_dwordx4 v[98:99], v[94:97], off
	global_load_dwordx2 v[94:95], v[100:101], off offset:32
	s_nop 0
	global_load_dwordx2 v[96:97], v[102:103], off offset:32
	v_mul_f32_e32 v90, v90, v104
	v_mul_f32_e32 v91, v91, v104
	v_mul_f32_e32 v90, 0xbfb8aa3b, v90
	v_mul_f32_e32 v91, 0xbfb8aa3b, v91
	v_mul_f32_e32 v92, v92, v104
	v_mul_f32_e32 v93, v93, v104
	v_exp_f32_e32 v90, v90
	v_exp_f32_e32 v91, v91
	v_mul_f32_e32 v92, 0xbfb8aa3b, v92
	v_mul_f32_e32 v93, 0xbfb8aa3b, v93
	v_exp_f32_e32 v92, v92
	v_exp_f32_e32 v93, v93
	v_pk_add_f32 v[90:91], v[90:91], 1.0 op_sel_hi:[1,0]
	v_mul_f32_e32 v86, v86, v104
	v_pk_add_f32 v[92:93], v[92:93], 1.0 op_sel_hi:[1,0]
	v_rcp_f32_e32 v91, v91
	v_rcp_f32_e32 v90, v90
	v_rcp_f32_e32 v93, v93
	v_rcp_f32_e32 v92, v92
	v_mul_f32_e32 v87, v87, v104
	v_mul_f32_e32 v86, 0xbfb8aa3b, v86
	v_mul_f32_e32 v87, 0xbfb8aa3b, v87
	v_mul_f32_e32 v88, v88, v104
	v_mul_f32_e32 v89, v89, v104
	v_exp_f32_e32 v86, v86
	v_exp_f32_e32 v87, v87
	v_mul_f32_e32 v88, 0xbfb8aa3b, v88
	s_waitcnt vmcnt(1)
	v_lshlrev_b32_e32 v106, 16, v94
	v_and_b32_e32 v107, 0xffff0000, v94
	v_lshlrev_b32_e32 v94, 16, v95
	v_and_b32_e32 v95, 0xffff0000, v95
	s_waitcnt vmcnt(0)
	v_lshlrev_b32_e32 v108, 16, v96
	v_and_b32_e32 v109, 0xffff0000, v96
	v_lshlrev_b32_e32 v96, 16, v97
	v_and_b32_e32 v97, 0xffff0000, v97
	v_pk_fma_f32 v[92:93], v[92:93], v[94:95], v[96:97]
	v_pk_fma_f32 v[90:91], v[90:91], v[106:107], v[108:109]
	global_store_dwordx4 v[98:99], v[90:93], off offset:64
	global_load_dwordx2 v[90:91], v[100:101], off offset:256
	s_nop 0
	global_load_dwordx2 v[92:93], v[102:103], off offset:256
	v_mul_f32_e32 v89, 0xbfb8aa3b, v89
	v_exp_f32_e32 v88, v88
	v_exp_f32_e32 v89, v89
	v_pk_add_f32 v[86:87], v[86:87], 1.0 op_sel_hi:[1,0]
	v_mul_f32_e32 v82, v82, v104
	v_pk_add_f32 v[88:89], v[88:89], 1.0 op_sel_hi:[1,0]
	v_rcp_f32_e32 v87, v87
	v_rcp_f32_e32 v86, v86
	v_rcp_f32_e32 v89, v89
	v_rcp_f32_e32 v88, v88
	v_mul_f32_e32 v83, v83, v104
	v_mul_f32_e32 v82, 0xbfb8aa3b, v82
	v_mul_f32_e32 v83, 0xbfb8aa3b, v83
	v_mul_f32_e32 v84, v84, v104
	v_mul_f32_e32 v85, v85, v104
	v_exp_f32_e32 v82, v82
	v_exp_f32_e32 v83, v83
	v_mul_f32_e32 v84, 0xbfb8aa3b, v84
	v_mul_f32_e32 v85, 0xbfb8aa3b, v85
	v_pk_add_f32 v[82:83], v[82:83], 1.0 op_sel_hi:[1,0]
	s_waitcnt vmcnt(1)
	v_lshlrev_b32_e32 v94, 16, v90
	v_and_b32_e32 v95, 0xffff0000, v90
	v_lshlrev_b32_e32 v90, 16, v91
	v_and_b32_e32 v91, 0xffff0000, v91
	s_waitcnt vmcnt(0)
	v_lshlrev_b32_e32 v96, 16, v92
	v_and_b32_e32 v97, 0xffff0000, v92
	v_lshlrev_b32_e32 v92, 16, v93
	v_and_b32_e32 v93, 0xffff0000, v93
	v_pk_fma_f32 v[88:89], v[88:89], v[90:91], v[92:93]
	v_pk_fma_f32 v[86:87], v[86:87], v[94:95], v[96:97]
	global_store_dwordx4 v[98:99], v[86:89], off offset:512
	global_load_dwordx2 v[86:87], v[100:101], off offset:288
	v_exp_f32_e32 v96, v84
	global_load_dwordx2 v[88:89], v[102:103], off offset:288
	v_exp_f32_e32 v97, v85
	s_nop 0
	v_pk_add_f32 v[96:97], v[96:97], 1.0 op_sel_hi:[1,0]
	v_or_b32_e32 v90, 48, v150
	v_ashrrev_i32_e32 v91, 31, v90
	v_cmp_gt_i32_e32 vcc, s45, v90
	s_nop 1
	v_cndmask_b32_e32 v91, 0, v91, vcc
	v_rcp_f32_e32 v83, v83
	v_rcp_f32_e32 v82, v82
	v_rcp_f32_e32 v97, v97
	v_rcp_f32_e32 v96, v96
	v_lshlrev_b64 v[92:93], 11, v[90:91]
	v_lshl_add_u64 v[94:95], v[90:91], 2, s[10:11]
	v_lshl_add_u64 v[84:85], s[12:13], 0, v[92:93]
	v_lshl_add_u64 v[84:85], v[84:85], 0, v[146:147]
	s_waitcnt vmcnt(1)
	v_lshlrev_b32_e32 v100, 16, v86
	v_and_b32_e32 v101, 0xffff0000, v86
	v_lshlrev_b32_e32 v86, 16, v87
	v_and_b32_e32 v87, 0xffff0000, v87
	s_waitcnt vmcnt(0)
; DI float sigmoidf_(float x) { return 1.f / (1.f + __expf(-x)); }
;     DI void operator()(const f32x4 (&acc)[2][2][4][2], const Unit& u, int wr, int wc, int fr, int fq) const {
;     ...
;             for (int m = 0; m < 4; ++m) { const int row = row0 + ai * HALF + m * 16;
;                 const float* bp = (row < MP) ? base0 + (size_t)row * DM : base1 + (size_t)(row - MP) * DM;
;                 float r = 1.f; if (MODE == 1) r = __builtin_amdgcn_rsqf(ssin[row] * (1.f / DM) + EPS);
;                 float s = 0.f;
; #pragma unroll
;                 for (int bj = 0; bj < 2; ++bj)
; #pragma unroll
;                     for (int n = 0; n < 2; ++n) { const int col = col0 + bj * HALF + n * 16;
;                         f32x4 v = acc[ai][bj][m][n];
;                         if (MODE == 1) { const u32x2 pw = *(const u32x2*)(PP + (size_t)row * DM + col);
;                             v[0] = sigmoidf_(v[0] * r) * bflo(pw.x); v[1] = sigmoidf_(v[1] * r) * bfhi(pw.x); v[2] = sigmoidf_(v[2] * r) * bflo(pw.y); v[3] = sigmoidf_(v[3] * r) * bfhi(pw.y); }
;                         f32x4 h;
;                         if (baseb) { const u32x2 bw = *(const u32x2*)(baseb + (size_t)row * DM + col); h = (f32x4){bflo(bw.x), bfhi(bw.x), bflo(bw.y), bfhi(bw.y)} + v; }
;                         else h = *(const f32x4*)(bp + col) + v;
;                         if (H) *(f32x4*)(H + (size_t)row * DM + col) = h;
	v_lshlrev_b32_e32 v102, 16, v88
	v_and_b32_e32 v103, 0xffff0000, v88
	v_lshlrev_b32_e32 v88, 16, v89
	v_and_b32_e32 v89, 0xffff0000, v89
	v_pk_fma_f32 v[88:89], v[96:97], v[86:87], v[88:89]
	v_pk_fma_f32 v[86:87], v[82:83], v[100:101], v[102:103]
	global_store_dwordx4 v[98:99], v[86:89], off offset:576
	global_load_dword v94, v[94:95], off
	s_nop 0
	global_load_dwordx2 v[88:89], v[84:85], off
	v_lshl_add_u64 v[82:83], s[14:15], 0, v[92:93]
	v_lshl_add_u64 v[86:87], v[82:83], 0, v[146:147]
	global_load_dwordx2 v[92:93], v[86:87], off
	v_lshlrev_b64 v[82:83], 12, v[90:91]
	v_lshl_add_u64 v[82:83], s[48:49], 0, v[82:83]
	v_lshl_add_u64 v[82:83], v[82:83], 0, v[148:149]
	s_waitcnt vmcnt(2)
	v_fmamk_f32 v95, v94, 0x3a800000, v161
	s_waitcnt vmcnt(1)
	v_lshlrev_b32_e32 v90, 16, v88
	v_and_b32_e32 v91, 0xffff0000, v88
	v_rsq_f32_e32 v88, v95
	v_lshlrev_b32_e32 v94, 16, v89
	v_and_b32_e32 v95, 0xffff0000, v89
	s_waitcnt vmcnt(0)
	v_lshlrev_b32_e32 v96, 16, v92
	v_mul_f32_e32 v78, v78, v88
	v_mul_f32_e32 v79, v79, v88
	v_mul_f32_e32 v78, 0xbfb8aa3b, v78
	v_mul_f32_e32 v79, 0xbfb8aa3b, v79
	v_mul_f32_e32 v80, v80, v88
	v_mul_f32_e32 v81, v81, v88
	v_exp_f32_e32 v78, v78
	v_exp_f32_e32 v79, v79
	v_mul_f32_e32 v80, 0xbfb8aa3b, v80
	v_mul_f32_e32 v81, 0xbfb8aa3b, v81
	v_exp_f32_e32 v80, v80
	v_exp_f32_e32 v81, v81
	v_pk_add_f32 v[78:79], v[78:79], 1.0 op_sel_hi:[1,0]
	v_and_b32_e32 v97, 0xffff0000, v92
	v_pk_add_f32 v[80:81], v[80:81], 1.0 op_sel_hi:[1,0]
	v_rcp_f32_e32 v79, v79
	v_rcp_f32_e32 v78, v78
	v_rcp_f32_e32 v81, v81
	v_lshlrev_b32_e32 v92, 16, v93
	v_and_b32_e32 v93, 0xffff0000, v93
	v_rcp_f32_e32 v80, v80
	v_pk_fma_f32 v[78:79], v[78:79], v[90:91], v[96:97]
	v_pk_fma_f32 v[80:81], v[80:81], v[94:95], v[92:93]
	global_store_dwordx4 v[82:83], v[78:81], off
	global_load_dwordx2 v[78:79], v[84:85], off offset:32
	s_nop 0
	global_load_dwordx2 v[80:81], v[86:87], off offset:32
	v_mul_f32_e32 v74, v74, v88
	v_mul_f32_e32 v75, v75, v88
	v_mul_f32_e32 v74, 0xbfb8aa3b, v74
	v_mul_f32_e32 v75, 0xbfb8aa3b, v75
	v_mul_f32_e32 v76, v76, v88
	v_mul_f32_e32 v77, v77, v88
	v_exp_f32_e32 v74, v74
	v_exp_f32_e32 v75, v75
	v_mul_f32_e32 v76, 0xbfb8aa3b, v76
	v_mul_f32_e32 v77, 0xbfb8aa3b, v77
	v_exp_f32_e32 v76, v76
	v_exp_f32_e32 v77, v77
	v_pk_add_f32 v[74:75], v[74:75], 1.0 op_sel_hi:[1,0]
	v_mul_f32_e32 v70, v70, v88
	v_pk_add_f32 v[76:77], v[76:77], 1.0 op_sel_hi:[1,0]
	v_rcp_f32_e32 v75, v75
	v_rcp_f32_e32 v74, v74
	v_rcp_f32_e32 v77, v77
	v_rcp_f32_e32 v76, v76
	v_mul_f32_e32 v71, v71, v88
	v_mul_f32_e32 v70, 0xbfb8aa3b, v70
	v_mul_f32_e32 v71, 0xbfb8aa3b, v71
	v_mul_f32_e32 v72, v72, v88
	v_mul_f32_e32 v73, v73, v88
	v_exp_f32_e32 v70, v70
	v_exp_f32_e32 v71, v71
	v_mul_f32_e32 v72, 0xbfb8aa3b, v72
	s_waitcnt vmcnt(1)
	v_lshlrev_b32_e32 v90, 16, v78
	v_and_b32_e32 v91, 0xffff0000, v78
	v_lshlrev_b32_e32 v78, 16, v79
	v_and_b32_e32 v79, 0xffff0000, v79
	s_waitcnt vmcnt(0)
	v_lshlrev_b32_e32 v92, 16, v80
	v_and_b32_e32 v93, 0xffff0000, v80
	v_lshlrev_b32_e32 v80, 16, v81
	v_and_b32_e32 v81, 0xffff0000, v81
	v_pk_fma_f32 v[76:77], v[76:77], v[78:79], v[80:81]
	v_pk_fma_f32 v[74:75], v[74:75], v[90:91], v[92:93]
	global_store_dwordx4 v[82:83], v[74:77], off offset:64
	global_load_dwordx2 v[74:75], v[84:85], off offset:256
	s_nop 0
	global_load_dwordx2 v[76:77], v[86:87], off offset:256
	v_mul_f32_e32 v73, 0xbfb8aa3b, v73
	v_exp_f32_e32 v72, v72
	v_exp_f32_e32 v73, v73
	v_pk_add_f32 v[70:71], v[70:71], 1.0 op_sel_hi:[1,0]
	v_mul_f32_e32 v66, v66, v88
	v_pk_add_f32 v[72:73], v[72:73], 1.0 op_sel_hi:[1,0]
	v_rcp_f32_e32 v71, v71
	v_rcp_f32_e32 v70, v70
	v_rcp_f32_e32 v73, v73
	v_rcp_f32_e32 v72, v72
	v_mul_f32_e32 v67, v67, v88
	v_mul_f32_e32 v66, 0xbfb8aa3b, v66
	v_mul_f32_e32 v67, 0xbfb8aa3b, v67
	v_mul_f32_e32 v68, v68, v88
	v_mul_f32_e32 v69, v69, v88
	v_exp_f32_e32 v66, v66
	v_exp_f32_e32 v67, v67
	v_mul_f32_e32 v68, 0xbfb8aa3b, v68
	v_mul_f32_e32 v69, 0xbfb8aa3b, v69
	v_cmp_gt_i32_e32 vcc, s55, v150
	v_pk_add_f32 v[66:67], v[66:67], 1.0 op_sel_hi:[1,0]
	s_waitcnt vmcnt(1)
	v_lshlrev_b32_e32 v78, 16, v74
	v_and_b32_e32 v79, 0xffff0000, v74
	v_lshlrev_b32_e32 v74, 16, v75
	v_and_b32_e32 v75, 0xffff0000, v75
	s_waitcnt vmcnt(0)
	v_lshlrev_b32_e32 v80, 16, v76
	v_and_b32_e32 v81, 0xffff0000, v76
	v_lshlrev_b32_e32 v76, 16, v77
	v_and_b32_e32 v77, 0xffff0000, v77
	v_pk_fma_f32 v[72:73], v[72:73], v[74:75], v[76:77]
	v_pk_fma_f32 v[70:71], v[70:71], v[78:79], v[80:81]
	global_store_dwordx4 v[82:83], v[70:73], off offset:512
	global_load_dwordx2 v[70:71], v[84:85], off offset:288
	v_exp_f32_e32 v80, v68
	global_load_dwordx2 v[72:73], v[86:87], off offset:288
	v_exp_f32_e32 v81, v69
	s_nop 0
	v_pk_add_f32 v[80:81], v[80:81], 1.0 op_sel_hi:[1,0]
	v_add_u32_e32 v74, 0x80, v150
	v_ashrrev_i32_e32 v75, 31, v74
	v_cndmask_b32_e32 v75, 0, v75, vcc
	v_rcp_f32_e32 v67, v67
	v_rcp_f32_e32 v66, v66
	v_rcp_f32_e32 v81, v81
	v_rcp_f32_e32 v80, v80
	v_lshlrev_b64 v[76:77], 11, v[74:75]
	v_lshl_add_u64 v[78:79], v[74:75], 2, s[10:11]
	v_lshl_add_u64 v[68:69], s[12:13], 0, v[76:77]
	v_lshl_add_u64 v[68:69], v[68:69], 0, v[146:147]
	s_waitcnt vmcnt(1)
	v_lshlrev_b32_e32 v84, 16, v70
	v_and_b32_e32 v85, 0xffff0000, v70
	v_lshlrev_b32_e32 v70, 16, v71
	v_and_b32_e32 v71, 0xffff0000, v71
	s_waitcnt vmcnt(0)
	v_lshlrev_b32_e32 v86, 16, v72
	v_and_b32_e32 v87, 0xffff0000, v72
	v_lshlrev_b32_e32 v72, 16, v73
	v_and_b32_e32 v73, 0xffff0000, v73
	v_pk_fma_f32 v[72:73], v[80:81], v[70:71], v[72:73]
	v_pk_fma_f32 v[70:71], v[66:67], v[84:85], v[86:87]
	global_store_dwordx4 v[82:83], v[70:73], off offset:576
	global_load_dword v78, v[78:79], off
	s_nop 0
	global_load_dwordx2 v[72:73], v[68:69], off
	v_lshl_add_u64 v[66:67], s[14:15], 0, v[76:77]
	v_lshl_add_u64 v[70:71], v[66:67], 0, v[146:147]
	global_load_dwordx2 v[76:77], v[70:71], off
	v_lshlrev_b64 v[66:67], 12, v[74:75]
	v_lshl_add_u64 v[66:67], s[48:49], 0, v[66:67]
	v_lshl_add_u64 v[66:67], v[66:67], 0, v[148:149]
	s_waitcnt vmcnt(2)
; DI float sigmoidf_(float x) { return 1.f / (1.f + __expf(-x)); }
;     DI void operator()(const f32x4 (&acc)[2][2][4][2], const Unit& u, int wr, int wc, int fr, int fq) const {
;     ...
;             for (int m = 0; m < 4; ++m) { const int row = row0 + ai * HALF + m * 16;
;                 const float* bp = (row < MP) ? base0 + (size_t)row * DM : base1 + (size_t)(row - MP) * DM;
;                 float r = 1.f; if (MODE == 1) r = __builtin_amdgcn_rsqf(ssin[row] * (1.f / DM) + EPS);
;                 float s = 0.f;
; #pragma unroll
;                 for (int bj = 0; bj < 2; ++bj)
; #pragma unroll
;                     for (int n = 0; n < 2; ++n) { const int col = col0 + bj * HALF + n * 16;
;                         f32x4 v = acc[ai][bj][m][n];
;                         if (MODE == 1) { const u32x2 pw = *(const u32x2*)(PP + (size_t)row * DM + col);
;                             v[0] = sigmoidf_(v[0] * r) * bflo(pw.x); v[1] = sigmoidf_(v[1] * r) * bfhi(pw.x); v[2] = sigmoidf_(v[2] * r) * bflo(pw.y); v[3] = sigmoidf_(v[3] * r) * bfhi(pw.y); }
;                         f32x4 h;
;                         if (baseb) { const u32x2 bw = *(const u32x2*)(baseb + (size_t)row * DM + col); h = (f32x4){bflo(bw.x), bfhi(bw.x), bflo(bw.y), bfhi(bw.y)} + v; }
;                         else h = *(const f32x4*)(bp + col) + v;
;                         if (H) *(f32x4*)(H + (size_t)row * DM + col) = h;
	v_fmamk_f32 v79, v78, 0x3a800000, v161
	s_waitcnt vmcnt(1)
	v_lshlrev_b32_e32 v74, 16, v72
	v_and_b32_e32 v75, 0xffff0000, v72
	v_rsq_f32_e32 v72, v79
	v_lshlrev_b32_e32 v78, 16, v73
	v_and_b32_e32 v79, 0xffff0000, v73
	s_waitcnt vmcnt(0)
	v_lshlrev_b32_e32 v80, 16, v76
	v_mul_f32_e32 v62, v62, v72
	v_mul_f32_e32 v63, v63, v72
	v_mul_f32_e32 v62, 0xbfb8aa3b, v62
	v_mul_f32_e32 v63, 0xbfb8aa3b, v63
	v_mul_f32_e32 v64, v64, v72
	v_mul_f32_e32 v65, v65, v72
	v_exp_f32_e32 v62, v62
	v_exp_f32_e32 v63, v63
	v_mul_f32_e32 v64, 0xbfb8aa3b, v64
	v_mul_f32_e32 v65, 0xbfb8aa3b, v65
	v_exp_f32_e32 v64, v64
	v_exp_f32_e32 v65, v65
	v_pk_add_f32 v[62:63], v[62:63], 1.0 op_sel_hi:[1,0]
	v_and_b32_e32 v81, 0xffff0000, v76
	v_pk_add_f32 v[64:65], v[64:65], 1.0 op_sel_hi:[1,0]
	v_rcp_f32_e32 v63, v63
	v_rcp_f32_e32 v62, v62
	v_rcp_f32_e32 v65, v65
	v_lshlrev_b32_e32 v76, 16, v77
	v_and_b32_e32 v77, 0xffff0000, v77
	v_rcp_f32_e32 v64, v64
	v_pk_fma_f32 v[62:63], v[62:63], v[74:75], v[80:81]
	v_pk_fma_f32 v[64:65], v[64:65], v[78:79], v[76:77]
	global_store_dwordx4 v[66:67], v[62:65], off
	global_load_dwordx2 v[62:63], v[68:69], off offset:32
	s_nop 0
	global_load_dwordx2 v[64:65], v[70:71], off offset:32
	v_mul_f32_e32 v58, v58, v72
	v_mul_f32_e32 v59, v59, v72
	v_mul_f32_e32 v58, 0xbfb8aa3b, v58
	v_mul_f32_e32 v59, 0xbfb8aa3b, v59
	v_mul_f32_e32 v60, v60, v72
	v_mul_f32_e32 v61, v61, v72
	v_exp_f32_e32 v58, v58
	v_exp_f32_e32 v59, v59
	v_mul_f32_e32 v60, 0xbfb8aa3b, v60
	v_mul_f32_e32 v61, 0xbfb8aa3b, v61
	v_exp_f32_e32 v60, v60
	v_exp_f32_e32 v61, v61
	v_pk_add_f32 v[58:59], v[58:59], 1.0 op_sel_hi:[1,0]
	v_mul_f32_e32 v54, v54, v72
	v_pk_add_f32 v[60:61], v[60:61], 1.0 op_sel_hi:[1,0]
	v_rcp_f32_e32 v59, v59
	v_rcp_f32_e32 v58, v58
	v_rcp_f32_e32 v61, v61
	v_rcp_f32_e32 v60, v60
	v_mul_f32_e32 v55, v55, v72
	v_mul_f32_e32 v54, 0xbfb8aa3b, v54
	v_mul_f32_e32 v55, 0xbfb8aa3b, v55
	v_mul_f32_e32 v56, v56, v72
	v_mul_f32_e32 v57, v57, v72
	v_exp_f32_e32 v54, v54
	v_exp_f32_e32 v55, v55
	v_mul_f32_e32 v56, 0xbfb8aa3b, v56
	s_waitcnt vmcnt(1)
	v_lshlrev_b32_e32 v74, 16, v62
	v_and_b32_e32 v75, 0xffff0000, v62
	v_lshlrev_b32_e32 v62, 16, v63
	v_and_b32_e32 v63, 0xffff0000, v63
	s_waitcnt vmcnt(0)
	v_lshlrev_b32_e32 v76, 16, v64
	v_and_b32_e32 v77, 0xffff0000, v64
	v_lshlrev_b32_e32 v64, 16, v65
	v_and_b32_e32 v65, 0xffff0000, v65
	v_pk_fma_f32 v[60:61], v[60:61], v[62:63], v[64:65]
	v_pk_fma_f32 v[58:59], v[58:59], v[74:75], v[76:77]
	global_store_dwordx4 v[66:67], v[58:61], off offset:64
	global_load_dwordx2 v[58:59], v[68:69], off offset:256
	s_nop 0
	global_load_dwordx2 v[60:61], v[70:71], off offset:256
	v_mul_f32_e32 v57, 0xbfb8aa3b, v57
	v_exp_f32_e32 v56, v56
	v_exp_f32_e32 v57, v57
	v_pk_add_f32 v[54:55], v[54:55], 1.0 op_sel_hi:[1,0]
	v_mul_f32_e32 v50, v50, v72
	v_pk_add_f32 v[56:57], v[56:57], 1.0 op_sel_hi:[1,0]
	v_rcp_f32_e32 v55, v55
	v_rcp_f32_e32 v54, v54
	v_rcp_f32_e32 v57, v57
	v_rcp_f32_e32 v56, v56
	v_mul_f32_e32 v51, v51, v72
	v_mul_f32_e32 v50, 0xbfb8aa3b, v50
	v_mul_f32_e32 v51, 0xbfb8aa3b, v51
	v_mul_f32_e32 v52, v52, v72
	v_mul_f32_e32 v53, v53, v72
	v_exp_f32_e32 v50, v50
	v_exp_f32_e32 v51, v51
	v_mul_f32_e32 v52, 0xbfb8aa3b, v52
	v_mul_f32_e32 v53, 0xbfb8aa3b, v53
	v_cmp_gt_i32_e32 vcc, s56, v150
	v_pk_add_f32 v[50:51], v[50:51], 1.0 op_sel_hi:[1,0]
	s_waitcnt vmcnt(1)
	v_lshlrev_b32_e32 v62, 16, v58
	v_and_b32_e32 v63, 0xffff0000, v58
	v_lshlrev_b32_e32 v58, 16, v59
	v_and_b32_e32 v59, 0xffff0000, v59
	s_waitcnt vmcnt(0)
	v_lshlrev_b32_e32 v64, 16, v60
	v_and_b32_e32 v65, 0xffff0000, v60
	v_lshlrev_b32_e32 v60, 16, v61
	v_and_b32_e32 v61, 0xffff0000, v61
	v_pk_fma_f32 v[56:57], v[56:57], v[58:59], v[60:61]
	v_pk_fma_f32 v[54:55], v[54:55], v[62:63], v[64:65]
	global_store_dwordx4 v[66:67], v[54:57], off offset:512
	global_load_dwordx2 v[54:55], v[68:69], off offset:288
	v_exp_f32_e32 v64, v52
	global_load_dwordx2 v[56:57], v[70:71], off offset:288
	v_exp_f32_e32 v65, v53
	s_nop 0
	v_pk_add_f32 v[64:65], v[64:65], 1.0 op_sel_hi:[1,0]
	v_add_u32_e32 v58, 0x90, v150
	v_ashrrev_i32_e32 v59, 31, v58
	v_cndmask_b32_e32 v59, 0, v59, vcc
	v_rcp_f32_e32 v51, v51
	v_rcp_f32_e32 v50, v50
	v_rcp_f32_e32 v65, v65
	v_rcp_f32_e32 v64, v64
	v_lshlrev_b64 v[60:61], 11, v[58:59]
	v_lshl_add_u64 v[62:63], v[58:59], 2, s[10:11]
	v_lshl_add_u64 v[52:53], s[12:13], 0, v[60:61]
	v_lshl_add_u64 v[52:53], v[52:53], 0, v[146:147]
	s_waitcnt vmcnt(1)
	v_lshlrev_b32_e32 v68, 16, v54
	v_and_b32_e32 v69, 0xffff0000, v54
	v_lshlrev_b32_e32 v54, 16, v55
	v_and_b32_e32 v55, 0xffff0000, v55
	s_waitcnt vmcnt(0)
	v_lshlrev_b32_e32 v70, 16, v56
	v_and_b32_e32 v71, 0xffff0000, v56
	v_lshlrev_b32_e32 v56, 16, v57
	v_and_b32_e32 v57, 0xffff0000, v57
	v_pk_fma_f32 v[56:57], v[64:65], v[54:55], v[56:57]
	v_pk_fma_f32 v[54:55], v[50:51], v[68:69], v[70:71]
	global_store_dwordx4 v[66:67], v[54:57], off offset:576
	global_load_dword v62, v[62:63], off
	s_nop 0
	global_load_dwordx2 v[56:57], v[52:53], off
	v_lshl_add_u64 v[50:51], s[14:15], 0, v[60:61]
	v_lshl_add_u64 v[54:55], v[50:51], 0, v[146:147]
	global_load_dwordx2 v[60:61], v[54:55], off
	v_lshlrev_b64 v[50:51], 12, v[58:59]
	v_lshl_add_u64 v[50:51], s[48:49], 0, v[50:51]
	v_lshl_add_u64 v[50:51], v[50:51], 0, v[148:149]
	s_waitcnt vmcnt(2)
	v_fmamk_f32 v63, v62, 0x3a800000, v161
	s_waitcnt vmcnt(1)
	v_lshlrev_b32_e32 v58, 16, v56
	v_and_b32_e32 v59, 0xffff0000, v56
	v_rsq_f32_e32 v56, v63
	v_lshlrev_b32_e32 v62, 16, v57
	v_and_b32_e32 v63, 0xffff0000, v57
	s_waitcnt vmcnt(0)
; DI float sigmoidf_(float x) { return 1.f / (1.f + __expf(-x)); }
;     DI void operator()(const f32x4 (&acc)[2][2][4][2], const Unit& u, int wr, int wc, int fr, int fq) const {
;     ...
;             for (int m = 0; m < 4; ++m) { const int row = row0 + ai * HALF + m * 16;
;                 const float* bp = (row < MP) ? base0 + (size_t)row * DM : base1 + (size_t)(row - MP) * DM;
;                 float r = 1.f; if (MODE == 1) r = __builtin_amdgcn_rsqf(ssin[row] * (1.f / DM) + EPS);
;                 float s = 0.f;
; #pragma unroll
;                 for (int bj = 0; bj < 2; ++bj)
; #pragma unroll
;                     for (int n = 0; n < 2; ++n) { const int col = col0 + bj * HALF + n * 16;
;                         f32x4 v = acc[ai][bj][m][n];
;                         if (MODE == 1) { const u32x2 pw = *(const u32x2*)(PP + (size_t)row * DM + col);
;                             v[0] = sigmoidf_(v[0] * r) * bflo(pw.x); v[1] = sigmoidf_(v[1] * r) * bfhi(pw.x); v[2] = sigmoidf_(v[2] * r) * bflo(pw.y); v[3] = sigmoidf_(v[3] * r) * bfhi(pw.y); }
;                         f32x4 h;
;                         if (baseb) { const u32x2 bw = *(const u32x2*)(baseb + (size_t)row * DM + col); h = (f32x4){bflo(bw.x), bfhi(bw.x), bflo(bw.y), bfhi(bw.y)} + v; }
;                         else h = *(const f32x4*)(bp + col) + v;
;                         if (H) *(f32x4*)(H + (size_t)row * DM + col) = h;
	v_lshlrev_b32_e32 v64, 16, v60
	v_mul_f32_e32 v46, v46, v56
	v_mul_f32_e32 v47, v47, v56
	v_mul_f32_e32 v46, 0xbfb8aa3b, v46
	v_mul_f32_e32 v47, 0xbfb8aa3b, v47
	v_mul_f32_e32 v48, v48, v56
	v_mul_f32_e32 v49, v49, v56
	v_exp_f32_e32 v46, v46
	v_exp_f32_e32 v47, v47
	v_mul_f32_e32 v48, 0xbfb8aa3b, v48
	v_mul_f32_e32 v49, 0xbfb8aa3b, v49
	v_exp_f32_e32 v48, v48
	v_exp_f32_e32 v49, v49
	v_pk_add_f32 v[46:47], v[46:47], 1.0 op_sel_hi:[1,0]
	v_and_b32_e32 v65, 0xffff0000, v60
	v_pk_add_f32 v[48:49], v[48:49], 1.0 op_sel_hi:[1,0]
	v_rcp_f32_e32 v47, v47
	v_rcp_f32_e32 v46, v46
	v_rcp_f32_e32 v49, v49
	v_lshlrev_b32_e32 v60, 16, v61
	v_and_b32_e32 v61, 0xffff0000, v61
	v_rcp_f32_e32 v48, v48
	v_pk_fma_f32 v[46:47], v[46:47], v[58:59], v[64:65]
	v_pk_fma_f32 v[48:49], v[48:49], v[62:63], v[60:61]
	global_store_dwordx4 v[50:51], v[46:49], off
	global_load_dwordx2 v[46:47], v[52:53], off offset:32
	s_nop 0
	global_load_dwordx2 v[48:49], v[54:55], off offset:32
	v_mul_f32_e32 v42, v42, v56
	v_mul_f32_e32 v43, v43, v56
	v_mul_f32_e32 v42, 0xbfb8aa3b, v42
	v_mul_f32_e32 v43, 0xbfb8aa3b, v43
	v_mul_f32_e32 v44, v44, v56
	v_mul_f32_e32 v45, v45, v56
	v_exp_f32_e32 v42, v42
	v_exp_f32_e32 v43, v43
	v_mul_f32_e32 v44, 0xbfb8aa3b, v44
	v_mul_f32_e32 v45, 0xbfb8aa3b, v45
	v_exp_f32_e32 v44, v44
	v_exp_f32_e32 v45, v45
	v_pk_add_f32 v[42:43], v[42:43], 1.0 op_sel_hi:[1,0]
	v_mul_f32_e32 v38, v38, v56
	v_pk_add_f32 v[44:45], v[44:45], 1.0 op_sel_hi:[1,0]
	v_rcp_f32_e32 v43, v43
	v_rcp_f32_e32 v42, v42
	v_rcp_f32_e32 v45, v45
	v_rcp_f32_e32 v44, v44
	v_mul_f32_e32 v39, v39, v56
	v_mul_f32_e32 v38, 0xbfb8aa3b, v38
	v_mul_f32_e32 v39, 0xbfb8aa3b, v39
	v_mul_f32_e32 v40, v40, v56
	v_mul_f32_e32 v41, v41, v56
	v_exp_f32_e32 v38, v38
	v_exp_f32_e32 v39, v39
	v_mul_f32_e32 v40, 0xbfb8aa3b, v40
	s_waitcnt vmcnt(1)
	v_lshlrev_b32_e32 v58, 16, v46
	v_and_b32_e32 v59, 0xffff0000, v46
	v_lshlrev_b32_e32 v46, 16, v47
	v_and_b32_e32 v47, 0xffff0000, v47
	s_waitcnt vmcnt(0)
	v_lshlrev_b32_e32 v60, 16, v48
	v_and_b32_e32 v61, 0xffff0000, v48
	v_lshlrev_b32_e32 v48, 16, v49
	v_and_b32_e32 v49, 0xffff0000, v49
	v_pk_fma_f32 v[44:45], v[44:45], v[46:47], v[48:49]
	v_pk_fma_f32 v[42:43], v[42:43], v[58:59], v[60:61]
	global_store_dwordx4 v[50:51], v[42:45], off offset:64
	global_load_dwordx2 v[42:43], v[52:53], off offset:256
	s_nop 0
	global_load_dwordx2 v[44:45], v[54:55], off offset:256
	v_mul_f32_e32 v41, 0xbfb8aa3b, v41
	v_exp_f32_e32 v40, v40
	v_exp_f32_e32 v41, v41
	v_pk_add_f32 v[38:39], v[38:39], 1.0 op_sel_hi:[1,0]
	v_mul_f32_e32 v34, v34, v56
	v_pk_add_f32 v[40:41], v[40:41], 1.0 op_sel_hi:[1,0]
	v_rcp_f32_e32 v39, v39
	v_rcp_f32_e32 v38, v38
	v_rcp_f32_e32 v41, v41
	v_rcp_f32_e32 v40, v40
	v_mul_f32_e32 v35, v35, v56
	v_mul_f32_e32 v34, 0xbfb8aa3b, v34
	v_mul_f32_e32 v35, 0xbfb8aa3b, v35
	v_mul_f32_e32 v36, v36, v56
	v_mul_f32_e32 v37, v37, v56
	v_exp_f32_e32 v34, v34
	v_exp_f32_e32 v35, v35
	v_mul_f32_e32 v36, 0xbfb8aa3b, v36
	v_mul_f32_e32 v37, 0xbfb8aa3b, v37
	v_cmp_gt_i32_e32 vcc, s57, v150
	v_pk_add_f32 v[34:35], v[34:35], 1.0 op_sel_hi:[1,0]
	s_waitcnt vmcnt(1)
	v_lshlrev_b32_e32 v46, 16, v42
	v_and_b32_e32 v47, 0xffff0000, v42
	v_lshlrev_b32_e32 v42, 16, v43
	v_and_b32_e32 v43, 0xffff0000, v43
	s_waitcnt vmcnt(0)
	v_lshlrev_b32_e32 v48, 16, v44
	v_and_b32_e32 v49, 0xffff0000, v44
	v_lshlrev_b32_e32 v44, 16, v45
	v_and_b32_e32 v45, 0xffff0000, v45
	v_pk_fma_f32 v[40:41], v[40:41], v[42:43], v[44:45]
	v_pk_fma_f32 v[38:39], v[38:39], v[46:47], v[48:49]
	global_store_dwordx4 v[50:51], v[38:41], off offset:512
	global_load_dwordx2 v[38:39], v[52:53], off offset:288
	v_exp_f32_e32 v48, v36
	global_load_dwordx2 v[40:41], v[54:55], off offset:288
	v_exp_f32_e32 v49, v37
	s_nop 0
	v_pk_add_f32 v[48:49], v[48:49], 1.0 op_sel_hi:[1,0]
	v_add_u32_e32 v42, 0xa0, v150
	v_ashrrev_i32_e32 v43, 31, v42
	v_cndmask_b32_e32 v43, 0, v43, vcc
	v_rcp_f32_e32 v35, v35
	v_rcp_f32_e32 v34, v34
	v_rcp_f32_e32 v49, v49
	v_rcp_f32_e32 v48, v48
	v_lshlrev_b64 v[44:45], 11, v[42:43]
	v_lshl_add_u64 v[46:47], v[42:43], 2, s[10:11]
	v_lshl_add_u64 v[36:37], s[12:13], 0, v[44:45]
	v_lshl_add_u64 v[36:37], v[36:37], 0, v[146:147]
	s_waitcnt vmcnt(1)
	v_lshlrev_b32_e32 v52, 16, v38
	v_and_b32_e32 v53, 0xffff0000, v38
	v_lshlrev_b32_e32 v38, 16, v39
	v_and_b32_e32 v39, 0xffff0000, v39
	s_waitcnt vmcnt(0)
	v_lshlrev_b32_e32 v54, 16, v40
	v_and_b32_e32 v55, 0xffff0000, v40
	v_lshlrev_b32_e32 v40, 16, v41
	v_and_b32_e32 v41, 0xffff0000, v41
	v_pk_fma_f32 v[40:41], v[48:49], v[38:39], v[40:41]
	v_pk_fma_f32 v[38:39], v[34:35], v[52:53], v[54:55]
	global_store_dwordx4 v[50:51], v[38:41], off offset:576
	global_load_dword v46, v[46:47], off
	s_nop 0
	global_load_dwordx2 v[40:41], v[36:37], off
	v_lshl_add_u64 v[34:35], s[14:15], 0, v[44:45]
	v_lshl_add_u64 v[38:39], v[34:35], 0, v[146:147]
	global_load_dwordx2 v[44:45], v[38:39], off
	v_lshlrev_b64 v[34:35], 12, v[42:43]
	v_lshl_add_u64 v[34:35], s[48:49], 0, v[34:35]
	v_lshl_add_u64 v[34:35], v[34:35], 0, v[148:149]
	s_waitcnt vmcnt(2)
	v_fmamk_f32 v47, v46, 0x3a800000, v161
	s_waitcnt vmcnt(1)
	v_lshlrev_b32_e32 v42, 16, v40
	v_and_b32_e32 v43, 0xffff0000, v40
	v_rsq_f32_e32 v40, v47
	v_lshlrev_b32_e32 v46, 16, v41
	v_and_b32_e32 v47, 0xffff0000, v41
	s_waitcnt vmcnt(0)
; DI float sigmoidf_(float x) { return 1.f / (1.f + __expf(-x)); }
;     DI void operator()(const f32x4 (&acc)[2][2][4][2], const Unit& u, int wr, int wc, int fr, int fq) const {
;     ...
;             for (int m = 0; m < 4; ++m) { const int row = row0 + ai * HALF + m * 16;
;                 const float* bp = (row < MP) ? base0 + (size_t)row * DM : base1 + (size_t)(row - MP) * DM;
;                 float r = 1.f; if (MODE == 1) r = __builtin_amdgcn_rsqf(ssin[row] * (1.f / DM) + EPS);
;                 float s = 0.f;
; #pragma unroll
;                 for (int bj = 0; bj < 2; ++bj)
; #pragma unroll
;                     for (int n = 0; n < 2; ++n) { const int col = col0 + bj * HALF + n * 16;
;                         f32x4 v = acc[ai][bj][m][n];
;                         if (MODE == 1) { const u32x2 pw = *(const u32x2*)(PP + (size_t)row * DM + col);
;                             v[0] = sigmoidf_(v[0] * r) * bflo(pw.x); v[1] = sigmoidf_(v[1] * r) * bfhi(pw.x); v[2] = sigmoidf_(v[2] * r) * bflo(pw.y); v[3] = sigmoidf_(v[3] * r) * bfhi(pw.y); }
;                         f32x4 h;
;                         if (baseb) { const u32x2 bw = *(const u32x2*)(baseb + (size_t)row * DM + col); h = (f32x4){bflo(bw.x), bfhi(bw.x), bflo(bw.y), bfhi(bw.y)} + v; }
;                         else h = *(const f32x4*)(bp + col) + v;
;                         if (H) *(f32x4*)(H + (size_t)row * DM + col) = h;
	v_lshlrev_b32_e32 v48, 16, v44
	v_mul_f32_e32 v30, v30, v40
	v_mul_f32_e32 v31, v31, v40
	v_mul_f32_e32 v30, 0xbfb8aa3b, v30
	v_mul_f32_e32 v31, 0xbfb8aa3b, v31
	v_mul_f32_e32 v32, v32, v40
	v_mul_f32_e32 v33, v33, v40
	v_exp_f32_e32 v30, v30
	v_exp_f32_e32 v31, v31
	v_mul_f32_e32 v32, 0xbfb8aa3b, v32
	v_mul_f32_e32 v33, 0xbfb8aa3b, v33
	v_exp_f32_e32 v32, v32
	v_exp_f32_e32 v33, v33
	v_pk_add_f32 v[30:31], v[30:31], 1.0 op_sel_hi:[1,0]
	v_and_b32_e32 v49, 0xffff0000, v44
	v_pk_add_f32 v[32:33], v[32:33], 1.0 op_sel_hi:[1,0]
	v_rcp_f32_e32 v31, v31
	v_rcp_f32_e32 v30, v30
	v_rcp_f32_e32 v33, v33
	v_lshlrev_b32_e32 v44, 16, v45
	v_and_b32_e32 v45, 0xffff0000, v45
	v_rcp_f32_e32 v32, v32
	v_pk_fma_f32 v[30:31], v[30:31], v[42:43], v[48:49]
	v_pk_fma_f32 v[32:33], v[32:33], v[46:47], v[44:45]
	global_store_dwordx4 v[34:35], v[30:33], off
	global_load_dwordx2 v[30:31], v[36:37], off offset:32
	s_nop 0
	global_load_dwordx2 v[32:33], v[38:39], off offset:32
	v_mul_f32_e32 v26, v26, v40
	v_mul_f32_e32 v27, v27, v40
	v_mul_f32_e32 v26, 0xbfb8aa3b, v26
	v_mul_f32_e32 v27, 0xbfb8aa3b, v27
	v_mul_f32_e32 v28, v28, v40
	v_mul_f32_e32 v29, v29, v40
	v_exp_f32_e32 v26, v26
	v_exp_f32_e32 v27, v27
	v_mul_f32_e32 v28, 0xbfb8aa3b, v28
	v_mul_f32_e32 v29, 0xbfb8aa3b, v29
	v_exp_f32_e32 v28, v28
	v_exp_f32_e32 v29, v29
	v_pk_add_f32 v[26:27], v[26:27], 1.0 op_sel_hi:[1,0]
	v_mul_f32_e32 v22, v22, v40
	v_pk_add_f32 v[28:29], v[28:29], 1.0 op_sel_hi:[1,0]
	v_rcp_f32_e32 v27, v27
	v_rcp_f32_e32 v26, v26
	v_rcp_f32_e32 v29, v29
	v_rcp_f32_e32 v28, v28
	v_mul_f32_e32 v23, v23, v40
	v_mul_f32_e32 v22, 0xbfb8aa3b, v22
	v_mul_f32_e32 v23, 0xbfb8aa3b, v23
	v_mul_f32_e32 v24, v24, v40
	v_mul_f32_e32 v25, v25, v40
	v_exp_f32_e32 v22, v22
	v_exp_f32_e32 v23, v23
	v_mul_f32_e32 v24, 0xbfb8aa3b, v24
	s_waitcnt vmcnt(1)
	v_lshlrev_b32_e32 v42, 16, v30
	v_and_b32_e32 v43, 0xffff0000, v30
	v_lshlrev_b32_e32 v30, 16, v31
	v_and_b32_e32 v31, 0xffff0000, v31
	s_waitcnt vmcnt(0)
	v_lshlrev_b32_e32 v44, 16, v32
	v_and_b32_e32 v45, 0xffff0000, v32
	v_lshlrev_b32_e32 v32, 16, v33
	v_and_b32_e32 v33, 0xffff0000, v33
	v_pk_fma_f32 v[28:29], v[28:29], v[30:31], v[32:33]
	v_pk_fma_f32 v[26:27], v[26:27], v[42:43], v[44:45]
	global_store_dwordx4 v[34:35], v[26:29], off offset:64
	global_load_dwordx2 v[26:27], v[36:37], off offset:256
	s_nop 0
	global_load_dwordx2 v[28:29], v[38:39], off offset:256
	v_mul_f32_e32 v25, 0xbfb8aa3b, v25
	v_exp_f32_e32 v24, v24
	v_exp_f32_e32 v25, v25
	v_pk_add_f32 v[22:23], v[22:23], 1.0 op_sel_hi:[1,0]
	v_mul_f32_e32 v18, v18, v40
	v_pk_add_f32 v[24:25], v[24:25], 1.0 op_sel_hi:[1,0]
	v_rcp_f32_e32 v23, v23
	v_rcp_f32_e32 v22, v22
	v_rcp_f32_e32 v25, v25
	v_rcp_f32_e32 v24, v24
	v_mul_f32_e32 v19, v19, v40
	v_mul_f32_e32 v18, 0xbfb8aa3b, v18
	v_mul_f32_e32 v19, 0xbfb8aa3b, v19
	v_mul_f32_e32 v20, v20, v40
	v_mul_f32_e32 v21, v21, v40
	v_exp_f32_e32 v18, v18
	v_exp_f32_e32 v19, v19
	v_mul_f32_e32 v20, 0xbfb8aa3b, v20
	v_mul_f32_e32 v21, 0xbfb8aa3b, v21
	v_cmp_gt_i32_e32 vcc, s58, v150
	v_pk_add_f32 v[18:19], v[18:19], 1.0 op_sel_hi:[1,0]
	s_waitcnt vmcnt(1)
	v_lshlrev_b32_e32 v30, 16, v26
	v_and_b32_e32 v31, 0xffff0000, v26
	v_lshlrev_b32_e32 v26, 16, v27
	v_and_b32_e32 v27, 0xffff0000, v27
	s_waitcnt vmcnt(0)
	v_lshlrev_b32_e32 v32, 16, v28
	v_and_b32_e32 v33, 0xffff0000, v28
	v_lshlrev_b32_e32 v28, 16, v29
	v_and_b32_e32 v29, 0xffff0000, v29
	v_pk_fma_f32 v[24:25], v[24:25], v[26:27], v[28:29]
	v_pk_fma_f32 v[22:23], v[22:23], v[30:31], v[32:33]
	global_store_dwordx4 v[34:35], v[22:25], off offset:512
	global_load_dwordx2 v[22:23], v[36:37], off offset:288
	v_exp_f32_e32 v32, v20
	global_load_dwordx2 v[24:25], v[38:39], off offset:288
	v_exp_f32_e32 v33, v21
	s_nop 0
	v_pk_add_f32 v[32:33], v[32:33], 1.0 op_sel_hi:[1,0]
	v_add_u32_e32 v26, 0xb0, v150
	v_ashrrev_i32_e32 v27, 31, v26
	v_cndmask_b32_e32 v27, 0, v27, vcc
	v_rcp_f32_e32 v19, v19
	v_rcp_f32_e32 v18, v18
	v_rcp_f32_e32 v33, v33
	v_rcp_f32_e32 v32, v32
	v_lshlrev_b64 v[28:29], 11, v[26:27]
	v_lshl_add_u64 v[30:31], v[26:27], 2, s[10:11]
	v_lshl_add_u64 v[20:21], s[12:13], 0, v[28:29]
	v_lshl_add_u64 v[20:21], v[20:21], 0, v[146:147]
	s_waitcnt vmcnt(1)
	v_lshlrev_b32_e32 v36, 16, v22
	v_and_b32_e32 v37, 0xffff0000, v22
	v_lshlrev_b32_e32 v22, 16, v23
	v_and_b32_e32 v23, 0xffff0000, v23
	s_waitcnt vmcnt(0)
	v_lshlrev_b32_e32 v38, 16, v24
	v_and_b32_e32 v39, 0xffff0000, v24
	v_lshlrev_b32_e32 v24, 16, v25
	v_and_b32_e32 v25, 0xffff0000, v25
	v_pk_fma_f32 v[24:25], v[32:33], v[22:23], v[24:25]
	v_pk_fma_f32 v[22:23], v[18:19], v[36:37], v[38:39]
	global_store_dwordx4 v[34:35], v[22:25], off offset:576
	global_load_dword v30, v[30:31], off
	s_nop 0
	global_load_dwordx2 v[24:25], v[20:21], off
	v_lshl_add_u64 v[18:19], s[14:15], 0, v[28:29]
	v_lshl_add_u64 v[22:23], v[18:19], 0, v[146:147]
	global_load_dwordx2 v[28:29], v[22:23], off
	v_lshlrev_b64 v[18:19], 12, v[26:27]
	v_lshl_add_u64 v[18:19], s[48:49], 0, v[18:19]
	v_lshl_add_u64 v[18:19], v[18:19], 0, v[148:149]
	s_waitcnt vmcnt(2)
; DI float sigmoidf_(float x) { return 1.f / (1.f + __expf(-x)); }
;     DI void operator()(const f32x4 (&acc)[2][2][4][2], const Unit& u, int wr, int wc, int fr, int fq) const {
;     ...
;             for (int m = 0; m < 4; ++m) { const int row = row0 + ai * HALF + m * 16;
;                 const float* bp = (row < MP) ? base0 + (size_t)row * DM : base1 + (size_t)(row - MP) * DM;
;                 float r = 1.f; if (MODE == 1) r = __builtin_amdgcn_rsqf(ssin[row] * (1.f / DM) + EPS);
;                 float s = 0.f;
; #pragma unroll
;                 for (int bj = 0; bj < 2; ++bj)
; #pragma unroll
;                     for (int n = 0; n < 2; ++n) { const int col = col0 + bj * HALF + n * 16;
;                         f32x4 v = acc[ai][bj][m][n];
;                         if (MODE == 1) { const u32x2 pw = *(const u32x2*)(PP + (size_t)row * DM + col);
;                             v[0] = sigmoidf_(v[0] * r) * bflo(pw.x); v[1] = sigmoidf_(v[1] * r) * bfhi(pw.x); v[2] = sigmoidf_(v[2] * r) * bflo(pw.y); v[3] = sigmoidf_(v[3] * r) * bfhi(pw.y); }
;                         f32x4 h;
;                         if (baseb) { const u32x2 bw = *(const u32x2*)(baseb + (size_t)row * DM + col); h = (f32x4){bflo(bw.x), bfhi(bw.x), bflo(bw.y), bfhi(bw.y)} + v; }
;                         else h = *(const f32x4*)(bp + col) + v;
;                         if (H) *(f32x4*)(H + (size_t)row * DM + col) = h;
	v_fmamk_f32 v31, v30, 0x3a800000, v161
	s_waitcnt vmcnt(1)
	v_lshlrev_b32_e32 v26, 16, v24
	v_and_b32_e32 v27, 0xffff0000, v24
	v_rsq_f32_e32 v24, v31
	v_lshlrev_b32_e32 v30, 16, v25
	v_and_b32_e32 v31, 0xffff0000, v25
	s_waitcnt vmcnt(0)
	v_lshlrev_b32_e32 v32, 16, v28
	v_mul_f32_e32 v14, v14, v24
	v_mul_f32_e32 v15, v15, v24
	v_mul_f32_e32 v14, 0xbfb8aa3b, v14
	v_mul_f32_e32 v15, 0xbfb8aa3b, v15
	v_mul_f32_e32 v16, v16, v24
	v_mul_f32_e32 v17, v17, v24
	v_exp_f32_e32 v14, v14
	v_exp_f32_e32 v15, v15
	v_mul_f32_e32 v16, 0xbfb8aa3b, v16
	v_mul_f32_e32 v17, 0xbfb8aa3b, v17
	v_exp_f32_e32 v16, v16
	v_exp_f32_e32 v17, v17
	v_pk_add_f32 v[14:15], v[14:15], 1.0 op_sel_hi:[1,0]
	v_and_b32_e32 v33, 0xffff0000, v28
	v_pk_add_f32 v[16:17], v[16:17], 1.0 op_sel_hi:[1,0]
	v_rcp_f32_e32 v15, v15
	v_rcp_f32_e32 v14, v14
	v_rcp_f32_e32 v17, v17
	v_lshlrev_b32_e32 v28, 16, v29
	v_and_b32_e32 v29, 0xffff0000, v29
	v_rcp_f32_e32 v16, v16
	v_pk_fma_f32 v[14:15], v[14:15], v[26:27], v[32:33]
	v_pk_fma_f32 v[16:17], v[16:17], v[30:31], v[28:29]
	global_store_dwordx4 v[18:19], v[14:17], off
	global_load_dwordx2 v[14:15], v[20:21], off offset:32
	s_nop 0
	global_load_dwordx2 v[16:17], v[22:23], off offset:32
	v_mul_f32_e32 v10, v10, v24
	v_mul_f32_e32 v11, v11, v24
	v_mul_f32_e32 v10, 0xbfb8aa3b, v10
	v_mul_f32_e32 v11, 0xbfb8aa3b, v11
	v_mul_f32_e32 v12, v12, v24
	v_mul_f32_e32 v13, v13, v24
	v_exp_f32_e32 v10, v10
	v_exp_f32_e32 v11, v11
	v_mul_f32_e32 v12, 0xbfb8aa3b, v12
	v_mul_f32_e32 v13, 0xbfb8aa3b, v13
	v_exp_f32_e32 v12, v12
	v_exp_f32_e32 v13, v13
	v_pk_add_f32 v[10:11], v[10:11], 1.0 op_sel_hi:[1,0]
	v_mul_f32_e32 v6, v6, v24
	v_pk_add_f32 v[12:13], v[12:13], 1.0 op_sel_hi:[1,0]
	v_rcp_f32_e32 v11, v11
	v_rcp_f32_e32 v10, v10
	v_rcp_f32_e32 v13, v13
	v_rcp_f32_e32 v12, v12
	v_mul_f32_e32 v7, v7, v24
	v_mul_f32_e32 v6, 0xbfb8aa3b, v6
	v_mul_f32_e32 v7, 0xbfb8aa3b, v7
	v_mul_f32_e32 v8, v8, v24
	v_mul_f32_e32 v9, v9, v24
	v_exp_f32_e32 v6, v6
	v_exp_f32_e32 v7, v7
	v_mul_f32_e32 v8, 0xbfb8aa3b, v8
	s_waitcnt vmcnt(1)
	v_lshlrev_b32_e32 v26, 16, v14
	v_and_b32_e32 v27, 0xffff0000, v14
	v_lshlrev_b32_e32 v14, 16, v15
	v_and_b32_e32 v15, 0xffff0000, v15
	s_waitcnt vmcnt(0)
	v_lshlrev_b32_e32 v28, 16, v16
	v_and_b32_e32 v29, 0xffff0000, v16
	v_lshlrev_b32_e32 v16, 16, v17
	v_and_b32_e32 v17, 0xffff0000, v17
	v_pk_fma_f32 v[12:13], v[12:13], v[14:15], v[16:17]
	v_pk_fma_f32 v[10:11], v[10:11], v[26:27], v[28:29]
	global_store_dwordx4 v[18:19], v[10:13], off offset:64
	global_load_dwordx2 v[10:11], v[20:21], off offset:256
	s_nop 0
	global_load_dwordx2 v[12:13], v[22:23], off offset:256
	v_mul_f32_e32 v9, 0xbfb8aa3b, v9
	v_exp_f32_e32 v8, v8
	v_exp_f32_e32 v9, v9
	v_pk_add_f32 v[6:7], v[6:7], 1.0 op_sel_hi:[1,0]
	v_mul_f32_e32 v2, v2, v24
	v_pk_add_f32 v[8:9], v[8:9], 1.0 op_sel_hi:[1,0]
	v_rcp_f32_e32 v7, v7
	v_rcp_f32_e32 v6, v6
	v_rcp_f32_e32 v9, v9
	v_rcp_f32_e32 v8, v8
	v_mul_f32_e32 v3, v3, v24
	v_mul_f32_e32 v2, 0xbfb8aa3b, v2
	v_mul_f32_e32 v3, 0xbfb8aa3b, v3
	v_mul_f32_e32 v4, v4, v24
	v_mul_f32_e32 v5, v5, v24
	v_exp_f32_e32 v2, v2
	v_exp_f32_e32 v3, v3
	v_mul_f32_e32 v4, 0xbfb8aa3b, v4
	v_mul_f32_e32 v5, 0xbfb8aa3b, v5
	v_exp_f32_e32 v4, v4
	v_exp_f32_e32 v5, v5
	v_pk_add_f32 v[2:3], v[2:3], 1.0 op_sel_hi:[1,0]
	v_pk_add_f32 v[4:5], v[4:5], 1.0 op_sel_hi:[1,0]
	s_waitcnt vmcnt(1)
	v_lshlrev_b32_e32 v14, 16, v10
	v_and_b32_e32 v15, 0xffff0000, v10
	v_lshlrev_b32_e32 v10, 16, v11
	v_and_b32_e32 v11, 0xffff0000, v11
	s_waitcnt vmcnt(0)
	v_lshlrev_b32_e32 v16, 16, v12
	v_and_b32_e32 v17, 0xffff0000, v12
	v_lshlrev_b32_e32 v12, 16, v13
	v_and_b32_e32 v13, 0xffff0000, v13
	v_pk_fma_f32 v[8:9], v[8:9], v[10:11], v[12:13]
	v_pk_fma_f32 v[6:7], v[6:7], v[14:15], v[16:17]
	global_store_dwordx4 v[18:19], v[6:9], off offset:512
	global_load_dwordx2 v[6:7], v[20:21], off offset:288
	s_nop 0
	global_load_dwordx2 v[8:9], v[22:23], off offset:288
	v_rcp_f32_e32 v3, v3
	v_rcp_f32_e32 v2, v2
	v_rcp_f32_e32 v5, v5
	v_rcp_f32_e32 v4, v4
	s_waitcnt vmcnt(1)
	v_lshlrev_b32_e32 v10, 16, v6
	v_and_b32_e32 v11, 0xffff0000, v6
	v_lshlrev_b32_e32 v6, 16, v7
	v_and_b32_e32 v7, 0xffff0000, v7
	s_waitcnt vmcnt(0)
	v_lshlrev_b32_e32 v12, 16, v8
	v_and_b32_e32 v13, 0xffff0000, v8
	v_lshlrev_b32_e32 v8, 16, v9
	v_and_b32_e32 v9, 0xffff0000, v9
	v_pk_fma_f32 v[4:5], v[4:5], v[6:7], v[8:9]
	v_pk_fma_f32 v[2:3], v[2:3], v[10:11], v[12:13]
	global_store_dwordx4 v[18:19], v[2:5], off offset:576

; __global__ void __launch_bounds__(NTHR, 2) mega_fwd(Args args) {
	.amdhsa_kernel _Z8mega_fwd4Args
		.amdhsa_group_segment_fixed_size 0
		.amdhsa_private_segment_fixed_size 0
		.amdhsa_kernarg_size 584
		.amdhsa_user_sgpr_count 2
		.amdhsa_user_sgpr_dispatch_ptr 0
		.amdhsa_user_sgpr_queue_ptr 0
		.amdhsa_user_sgpr_kernarg_segment_ptr 1
		.amdhsa_user_sgpr_dispatch_id 0
		.amdhsa_user_sgpr_kernarg_preload_length 0
		.amdhsa_user_sgpr_kernarg_preload_offset 0
		.amdhsa_user_sgpr_private_segment_size 0
		.amdhsa_uses_dynamic_stack 0
		.amdhsa_enable_private_segment 0
		.amdhsa_system_sgpr_workgroup_id_x 1
		.amdhsa_system_sgpr_workgroup_id_y 0
		.amdhsa_system_sgpr_workgroup_id_z 0
		.amdhsa_system_sgpr_workgroup_info 0
		.amdhsa_system_vgpr_workitem_id 0
		.amdhsa_next_free_vgpr 256
		.amdhsa_next_free_sgpr 100
		.amdhsa_accum_offset 256
		.amdhsa_reserve_vcc 1
		.amdhsa_float_round_mode_32 0
		.amdhsa_float_round_mode_16_64 0
		.amdhsa_float_denorm_mode_32 3
		.amdhsa_float_denorm_mode_16_64 3
		.amdhsa_dx10_clamp 1
		.amdhsa_ieee_mode 1
		.amdhsa_fp16_overflow 0
		.amdhsa_tg_split 0
		.amdhsa_exception_fp_ieee_invalid_op 0
		.amdhsa_exception_fp_denorm_src 0
		.amdhsa_exception_fp_ieee_div_zero 0
		.amdhsa_exception_fp_ieee_overflow 0
		.amdhsa_exception_fp_ieee_underflow 0
		.amdhsa_exception_fp_ieee_inexact 0
		.amdhsa_exception_int_div_zero 0
	.end_amdhsa_kernel

; __global__ void __launch_bounds__(NTHR, 2) mega_fwd(Args args) {
amdhsa.kernels:
  - .agpr_count:     0
    .args:
      - .offset:         0
        .size:           328
        .value_kind:     by_value
      - .offset:         328
        .size:           4
        .value_kind:     hidden_block_count_x
      - .offset:         332
        .size:           4
        .value_kind:     hidden_block_count_y
      - .offset:         336
        .size:           4
        .value_kind:     hidden_block_count_z
      - .offset:         340
        .size:           2
        .value_kind:     hidden_group_size_x
      - .offset:         342
        .size:           2
        .value_kind:     hidden_group_size_y
      - .offset:         344
        .size:           2
        .value_kind:     hidden_group_size_z
      - .offset:         346
        .size:           2
        .value_kind:     hidden_remainder_x
      - .offset:         348
        .size:           2
        .value_kind:     hidden_remainder_y
      - .offset:         350
        .size:           2
        .value_kind:     hidden_remainder_z
      - .offset:         368
        .size:           8
        .value_kind:     hidden_global_offset_x
      - .offset:         376
        .size:           8
        .value_kind:     hidden_global_offset_y
      - .offset:         384
        .size:           8
        .value_kind:     hidden_global_offset_z
      - .offset:         392
        .size:           2
        .value_kind:     hidden_grid_dims
      - .offset:         448
        .size:           4
        .value_kind:     hidden_dynamic_lds_size
    .group_segment_fixed_size: 0
    .kernarg_segment_align: 8
    .kernarg_segment_size: 584
    .language:       OpenCL C
    .language_version:
      - 2
      - 0
    .max_flat_workgroup_size: 512
    .name:           _Z8mega_fwd4Args
    .private_segment_fixed_size: 0
    .sgpr_count:     106
    .sgpr_spill_count: 85
    .symbol:         _Z8mega_fwd4Args.kd
    .uniform_work_group_size: 1
    .uses_dynamic_stack: false
    .vgpr_count:     256
    .vgpr_spill_count: 0
    .wavefront_size: 64
